# v77 + HGRN pass-C backward-direction readout: the gate / norm-weight / partial-sum loads of iterations 1-3 and 5-7 issued together with iteration 0's and 4's (2 exposed round trips instead of 8), coun
# speedup vs baseline: 1.0079x; 1.0079x over previous
.LBB0_372:
	s_andn2_b64 vcc, exec, s[2:3]
	s_cbranch_vccnz .LBB0_339
	s_mul_i32 s3, s4, 9
	s_ashr_i32 s2, s3, 1
	s_add_i32 s3, s3, 9
	s_ashr_i32 s3, s3, 1
	v_ashrrev_i32_e32 v0, 6, v205
	s_sub_i32 s3, s3, s2
	v_cmp_gt_i32_e32 vcc, s3, v0
	s_and_saveexec_b64 s[38:39], vcc
	s_cbranch_execz .LBB0_338
	v_add_u32_e32 v0, s2, v0
	s_mov_b32 s2, 0x38e38e39
	v_mul_hi_i32 v2, v0, s2
	v_lshrrev_b32_e32 v3, 31, v2
	v_ashrrev_i32_e32 v2, 3, v2
	v_add_u32_e32 v2, v2, v3
	v_mul_lo_u32 v3, v2, 36
	v_sub_u32_e32 v96, v0, v3
	v_cmp_gt_i32_e64 s[40:41], 4, v96
	s_and_b64 s[2:3], s[18:19], s[40:41]
	v_mov_b32_e32 v1, v236
	s_xor_b64 s[2:3], s[2:3], -1
	s_and_b64 exec, exec, s[2:3]
	s_cbranch_execz .LBB0_338
	v_lshrrev_b32_e32 v0, 6, v1
	s_movk_i32 s2, 0x4d00
	v_mul_lo_u32 v0, v0, s2
	v_add_u32_e32 v92, 16, v0
	v_lshlrev_b32_e32 v0, 6, v2
	v_and_b32_e32 v94, 63, v1
	v_and_b32_e32 v0, 0xc0, v0
	v_or_b32_e32 v3, v94, v0
	v_readlane_b32 s0, v255, 20
	v_lshlrev_b32_e32 v160, 2, v3
	v_readlane_b32 s1, v255, 21
	s_nop 4
	global_load_dword v3, v160, s[0:1]
	global_load_dword v6, v160, s[0:1] offset:2048
	v_lshl_add_u64 v[4:5], s[0:1], 0, v[160:161]
	v_add_co_u32_e32 v4, vcc, 0x1000, v4
	s_mov_b32 s0, 0xf149f2ca
	s_nop 0
	v_addc_co_u32_e32 v5, vcc, 0, v5, vcc
	global_load_dword v8, v[4:5], off
	s_nop 0
	global_load_dword v4, v[4:5], off offset:2048
	v_lshlrev_b32_e32 v148, 1, v2
	v_ashrrev_i32_e32 v97, 31, v96
	v_mov_b32_e32 v99, v161
	v_mov_b32_e32 v101, v161
	v_readlane_b32 s44, v254, 28
	v_readlane_b32 s45, v254, 29
	v_mov_b32_e32 v16, v94
	s_waitcnt vmcnt(2)
	v_max3_f32 v7, v3, s0, v6
	v_readlane_b32 s0, v255, 1
	v_readlane_b32 s1, v255, 2
	s_waitcnt vmcnt(0)
	v_max3_f32 v5, v7, v8, v4
	v_sub_f32_e32 v6, v6, v5
	v_mul_f32_e32 v6, 0x3fb8aa3b, v6
	v_sub_f32_e32 v3, v3, v5
	v_exp_f32_e32 v6, v6
	v_sub_f32_e32 v7, v8, v5
	v_mul_f32_e32 v3, 0x3fb8aa3b, v3
	v_mul_f32_e32 v7, 0x3fb8aa3b, v7
	v_exp_f32_e32 v3, v3
	v_exp_f32_e32 v7, v7
	v_sub_f32_e32 v4, v4, v5
	v_mul_f32_e32 v4, 0x3fb8aa3b, v4
	v_exp_f32_e32 v4, v4
	v_add_f32_e32 v5, 0, v6
	v_cndmask_b32_e64 v5, v5, 0, s[0:1]
	v_readlane_b32 s0, v255, 3
	v_add_f32_e32 v8, v7, v5
	v_readlane_b32 s1, v255, 4
	v_add_f32_e32 v3, 0, v3
	v_add_f32_e32 v3, v6, v3
	v_cndmask_b32_e64 v5, v8, v5, s[0:1]
	v_readlane_b32 s0, v255, 5
	v_add_f32_e32 v8, v4, v5
	v_readlane_b32 s1, v255, 6
	v_add_f32_e32 v3, v7, v3
	v_add_f32_e32 v3, v4, v3
	v_cndmask_b32_e64 v5, v8, v5, s[0:1]
	v_div_scale_f32 v4, s[2:3], v3, v3, v5
	v_rcp_f32_e32 v6, v4
	v_readlane_b32 s0, v255, 22
	v_readlane_b32 s1, v255, 23
	v_fma_f32 v7, -v4, v6, 1.0
	v_fmac_f32_e32 v6, v7, v6
	v_div_scale_f32 v7, vcc, v5, v3, v5
	v_mul_f32_e32 v8, v7, v6
	v_fma_f32 v9, -v4, v8, v7
	v_fmac_f32_e32 v8, v9, v6
	v_fma_f32 v4, -v4, v8, v7
	v_div_fmas_f32 v4, v4, v6, v8
	v_div_fixup_f32 v149, v4, v3, v5
	v_ashrrev_i32_e32 v6, 2, v2
	v_mad_i64_i32 v[2:3], s[2:3], v148, 36, v[96:97]
	v_lshlrev_b64 v[2:3], 13, v[2:3]
	v_lshlrev_b32_e32 v4, 7, v1
	v_lshl_add_u64 v[2:3], s[0:1], 0, v[2:3]
	v_and_b32_e32 v98, 0xf80, v4
	v_lshrrev_b32_e32 v1, 2, v1
	v_lshl_add_u64 v[2:3], v[2:3], 0, v[98:99]
	v_and_b32_e32 v100, 8, v1
	v_lshl_add_u64 v[2:3], v[2:3], 0, v[100:101]
	global_load_dwordx2 v[42:43], v[2:3], off
	global_load_dwordx2 v[36:37], v[2:3], off offset:16
	global_load_dwordx2 v[34:35], v[2:3], off offset:32
	global_load_dwordx2 v[4:5], v[2:3], off offset:48
	s_movk_i32 s0, 0x1000
	v_mov_b32_e32 v1, 0xffffff00
	v_lshl_add_u32 v1, v6, 11, v1
	s_mov_b64 s[2:3], s[44:45]
	v_sub_f32_e32 v80, 1.0, v149
	s_waitcnt vmcnt(1)
	v_lshlrev_b32_e32 v40, 16, v35
	s_waitcnt vmcnt(0)
	v_lshlrev_b32_e32 v44, 16, v4
	v_and_b32_e32 v45, 0xffff0000, v4
	v_add_co_u32_e32 v4, vcc, s0, v2
	v_lshlrev_b32_e32 v46, 16, v5
	v_and_b32_e32 v47, 0xffff0000, v5
	v_addc_co_u32_e32 v5, vcc, 0, v3, vcc
	global_load_dwordx2 v[52:53], v[4:5], off
	global_load_dwordx2 v[50:51], v[4:5], off offset:16
	global_load_dwordx2 v[48:49], v[4:5], off offset:32
	global_load_dwordx2 v[38:39], v[4:5], off offset:48
	global_load_dwordx2 v[60:61], v[2:3], off offset:64
	global_load_dwordx2 v[58:59], v[2:3], off offset:80
	global_load_dwordx2 v[56:57], v[2:3], off offset:96
	global_load_dwordx2 v[54:55], v[2:3], off offset:112
	global_load_dwordx2 v[26:27], v[4:5], off offset:64
	global_load_dwordx2 v[28:29], v[4:5], off offset:80
	global_load_dwordx2 v[30:31], v[4:5], off offset:96
	global_load_dwordx2 v[32:33], v[4:5], off offset:112
	v_mov_b32_e32 v2, 0x4000
	v_lshl_add_u32 v2, v6, 8, v2
	v_cndmask_b32_e64 v1, v1, v2, s[40:41]
	v_lshl_add_u32 v93, v96, 6, v1
	v_and_b32_e32 v41, 0xffff0000, v35
	v_ashrrev_i32_e32 v89, 31, v93
	v_and_b32_e32 v35, 31, v16
	v_ashrrev_i32_e32 v81, 5, v16
	v_mov_b64_e32 v[2:3], s[2:3]
	s_movk_i32 s0, 0x1200
	v_mad_i64_i32 v[2:3], s[4:5], v93, s0, v[2:3]
	v_lshlrev_b32_e32 v90, 1, v0
	v_mov_b32_e32 v91, v161
	v_ashrrev_i32_e32 v17, 31, v16
	v_lshl_add_u64 v[0:1], v[2:3], 0, v[90:91]
	v_lshl_add_u64 v[18:19], v[16:17], 1, v[0:1]
	s_mov_b64 s[0:1], 0xb200000
	v_lshl_add_u64 v[0:1], v[18:19], 0, s[0:1]
	global_load_ushort v15, v[0:1], off offset:3072
	global_load_ushort v66, v[0:1], off offset:2048
	s_mov_b32 s7, 0xb202000
	v_add_co_u32_e32 v2, vcc, s7, v18
	s_mov_b32 s11, 0xb205000
	s_nop 0
	v_addc_co_u32_e32 v3, vcc, 0, v19, vcc
	v_add_co_u32_e32 v4, vcc, s11, v18
	s_mov_b32 s12, 0xb207000
	s_nop 0
	v_addc_co_u32_e32 v5, vcc, 0, v19, vcc
	v_add_co_u32_e32 v6, vcc, s12, v18
	s_mov_b32 s13, 0xb209000
	s_nop 0
	v_addc_co_u32_e32 v7, vcc, 0, v19, vcc
	v_add_co_u32_e32 v8, vcc, s13, v18
	s_mov_b32 s14, 0xb20b000
	s_nop 0
	v_addc_co_u32_e32 v9, vcc, 0, v19, vcc
	v_add_co_u32_e32 v10, vcc, s14, v18
	s_mov_b32 s15, 0xb20e000
	s_nop 0
	v_addc_co_u32_e32 v11, vcc, 0, v19, vcc
	v_add_co_u32_e32 v62, vcc, s15, v18
	s_mov_b32 s18, 0xb210000
	s_nop 0
	v_addc_co_u32_e32 v63, vcc, 0, v19, vcc
	v_add_co_u32_e32 v64, vcc, s18, v18
	s_mov_b32 s19, 0xb212000
	s_nop 0
	v_addc_co_u32_e32 v65, vcc, 0, v19, vcc
	v_add_co_u32_e32 v76, vcc, s19, v18
	s_mov_b32 s21, 0xb214000
	s_nop 0
	v_addc_co_u32_e32 v77, vcc, 0, v19, vcc
	v_add_co_u32_e32 v102, vcc, s21, v18
	s_mov_b32 s30, 0xb217000
	s_nop 0
	v_addc_co_u32_e32 v103, vcc, 0, v19, vcc
	global_load_ushort v88, v[4:5], off offset:1024
	global_load_ushort v95, v[4:5], off
	global_load_ushort v104, v[2:3], off offset:3072
	global_load_ushort v14, v[4:5], off offset:512
	global_load_ushort v13, v[2:3], off offset:3584
	global_load_ushort v12, v[0:1], off offset:2560
	v_add_co_u32_e32 v78, vcc, s30, v18
	s_mov_b32 s9, 0xc1f00000
	s_nop 0
	v_addc_co_u32_e32 v79, vcc, 0, v19, vcc
	s_mov_b32 s31, 0xb219000
	v_add_co_u32_e32 v82, vcc, s31, v18
	s_mov_b32 s34, 0xb21b000
	s_nop 0
	v_addc_co_u32_e32 v83, vcc, 0, v19, vcc
	v_add_co_u32_e32 v20, vcc, s34, v18
	s_mov_b32 s35, 0xb21d000
	s_nop 0
	v_addc_co_u32_e32 v21, vcc, 0, v19, vcc
	v_add_co_u32_e32 v68, vcc, s35, v18
	s_mov_b32 s36, 0xb220000
	s_nop 0
	v_addc_co_u32_e32 v69, vcc, 0, v19, vcc
	v_add_co_u32_e32 v22, vcc, s36, v18
	s_mov_b32 s37, 0xb222000
	s_nop 0
	v_addc_co_u32_e32 v23, vcc, 0, v19, vcc
	v_add_co_u32_e32 v24, vcc, s37, v18
	s_mov_b32 s40, 0xb201000
	s_nop 0
	v_addc_co_u32_e32 v25, vcc, 0, v19, vcc
	s_waitcnt vmcnt(7)
	v_lshlrev_b32_e32 v0, 16, v15
	v_max_f32_e32 v0, v0, v0
	v_med3_f32 v0, v0, s9, v244
	v_mul_f32_e32 v0, 0xbfb8aa3b, v0
	v_exp_f32_e32 v86, v0
	v_add_co_u32_e32 v0, vcc, s40, v18
	s_mov_b32 s41, 0xb203000
	v_add_f32_e32 v2, 1.0, v86
	v_rcp_f32_e32 v118, v2
	v_addc_co_u32_e32 v1, vcc, 0, v19, vcc
	s_waitcnt vmcnt(6)
	v_lshlrev_b32_e32 v4, 16, v66
	v_fma_f32 v5, v80, v118, v149
	v_max_f32_e32 v15, 0xda24260, v5
	v_add_co_u32_e32 v2, vcc, s41, v18
	v_mul_f32_e32 v4, v15, v4
	s_nop 0
	v_addc_co_u32_e32 v3, vcc, 0, v19, vcc
	v_bfe_u32 v5, v4, 16, 1
	s_movk_i32 s10, 0x7fff
	s_mov_b32 s46, 0xb204000
	v_add3_u32 v105, v4, v5, s10
	v_add_co_u32_e32 v4, vcc, s46, v18
	s_mov_b32 s28, 0xb206000
	s_nop 0
	v_addc_co_u32_e32 v5, vcc, 0, v19, vcc
	global_load_ushort v106, v[4:5], off offset:-4096
	global_load_ushort v107, v[4:5], off offset:512
	global_load_ushort v87, v[0:1], off offset:3584
	global_load_ushort v110, v[0:1], off offset:2560
	global_load_ushort v111, v[2:3], off offset:3584
	v_add_co_u32_e32 v2, vcc, s28, v18
	s_mov_b32 s29, 0xb208000
	s_nop 0
	v_addc_co_u32_e32 v3, vcc, 0, v19, vcc
	global_load_ushort v156, v[6:7], off offset:1536
	global_load_ushort v157, v[8:9], off offset:2560
	global_load_ushort v158, v[10:11], off offset:3584
	global_load_ushort v116, v[6:7], off offset:2048
	global_load_ushort v117, v[8:9], off offset:3072
	global_load_ushort v121, v[10:11], off offset:3072
	global_load_ushort v120, v[8:9], off offset:2048
	global_load_ushort v126, v[6:7], off offset:1024
	v_add_co_u32_e32 v6, vcc, s29, v18
	s_mov_b32 s42, 0xb20a000
	s_nop 0
	v_addc_co_u32_e32 v7, vcc, 0, v19, vcc
	v_add_co_u32_e32 v8, vcc, s42, v18
	s_mov_b32 s6, 0xb20c000
	s_nop 0
	v_addc_co_u32_e32 v9, vcc, 0, v19, vcc
	v_add_co_u32_e32 v10, vcc, s6, v18
	s_mov_b32 s49, 0xb20d000
	s_nop 0
	v_addc_co_u32_e32 v11, vcc, 0, v19, vcc
	v_add_co_u32_e32 v66, vcc, s49, v18
	s_mov_b32 s4, 0xb20f000
	s_nop 0
	v_addc_co_u32_e32 v67, vcc, 0, v19, vcc
	v_add_co_u32_e32 v74, vcc, s4, v18
	s_mov_b32 s4, 0xb211000
	s_nop 0
	v_addc_co_u32_e32 v75, vcc, 0, v19, vcc
	v_add_co_u32_e32 v84, vcc, s4, v18
	s_mov_b32 s4, 0xb223000
	s_nop 0
	v_addc_co_u32_e32 v85, vcc, 0, v19, vcc
	global_load_ushort v159, v[62:63], off offset:512
	global_load_ushort v162, v[64:65], off offset:1536
	global_load_ushort v163, v[76:77], off offset:2560
	global_load_ushort v164, v[102:103], off offset:3584
	global_load_ushort v127, v[62:63], off offset:1024
	global_load_ushort v137, v[64:65], off offset:2048
	global_load_ushort v141, v[64:65], off offset:1024
	global_load_ushort v131, v[62:63], off
	v_add_co_u32_e32 v62, vcc, s4, v18
	s_mov_b32 s4, 0xb221000
	s_nop 0
	v_addc_co_u32_e32 v63, vcc, 0, v19, vcc
	v_add_co_u32_e32 v64, vcc, s4, v18
	s_mov_b32 s4, 0xb21f000
	s_nop 0
	v_addc_co_u32_e32 v65, vcc, 0, v19, vcc
	v_add_co_u32_e32 v70, vcc, s4, v18
	s_mov_b32 s97, 0xb21c000
	s_nop 0
	v_addc_co_u32_e32 v71, vcc, 0, v19, vcc
	v_add_co_u32_e32 v72, vcc, s97, v18
	s_mov_b32 s4, 0xb21a000
	s_nop 0
	v_addc_co_u32_e32 v73, vcc, 0, v19, vcc
	v_add_co_u32_e32 v108, vcc, s4, v18
	s_mov_b32 s48, 0xb218000
	s_nop 0
	v_addc_co_u32_e32 v109, vcc, 0, v19, vcc
	v_add_co_u32_e32 v112, vcc, s48, v18
	s_mov_b32 s47, 0xb216000
	s_nop 0
	v_addc_co_u32_e32 v113, vcc, 0, v19, vcc
	v_add_co_u32_e32 v114, vcc, s47, v18
	s_mov_b32 s43, 0xb213000
	s_nop 0
	v_addc_co_u32_e32 v115, vcc, 0, v19, vcc
	v_add_co_u32_e32 v124, vcc, s43, v18
	global_load_ushort v165, v[78:79], off offset:512
	global_load_ushort v166, v[82:83], off offset:1536
	global_load_ushort v167, v[20:21], off offset:2560
	global_load_ushort v168, v[68:69], off offset:3584
	global_load_ushort v169, v[22:23], off offset:512
	global_load_ushort v170, v[24:25], off offset:1536
	global_load_ushort v171, v[22:23], off offset:-4096
	global_load_ushort v172, v[78:79], off offset:-4096
	v_addc_co_u32_e32 v125, vcc, 0, v19, vcc
	global_load_ushort v128, v[66:67], off offset:-4096
	global_load_ushort v129, v[66:67], off offset:512
	global_load_ushort v173, v[112:113], off offset:1024
	s_nop 0
	global_load_ushort v66, v[66:67], off
	s_nop 0
	global_load_ushort v67, v[4:5], off
	s_nop 0
	global_load_ushort v4, v[124:125], off offset:3072
	global_load_ushort v5, v[2:3], off offset:1536
	global_load_ushort v130, v[2:3], off offset:512
	global_load_ushort v136, v[6:7], off offset:1536
	global_load_ushort v174, v[2:3], off offset:1024
	global_load_ushort v175, v[0:1], off offset:3072
	s_waitcnt vmcnt(37)
	v_lshlrev_b32_e32 v0, 16, v87
	v_max_f32_e32 v0, v0, v0
	v_med3_f32 v0, v0, s9, v244
	v_mul_f32_e32 v0, 0xbfb8aa3b, v0
	v_exp_f32_e32 v87, v0
	global_load_ushort v0, v[74:75], off offset:1536
	global_load_ushort v1, v[84:85], off offset:2560
	global_load_ushort v2, v[84:85], off offset:1536
	global_load_ushort v3, v[62:63], off offset:2048
	global_load_ushort v176, v[64:65], off offset:1024
	global_load_ushort v177, v[72:73], off offset:3072
	global_load_ushort v178, v[108:109], off offset:2048
	global_load_ushort v179, v[84:85], off offset:2048
	global_load_ushort v138, v[6:7], off offset:2560
	global_load_ushort v139, v[8:9], off offset:3584
	global_load_ushort v140, v[8:9], off offset:2560
	s_nop 0
	global_load_ushort v10, v[10:11], off offset:3584
	s_nop 0
	global_load_ushort v11, v[74:75], off offset:512
	global_load_ushort v180, v[74:75], off offset:1024
	s_nop 0
	global_load_ushort v8, v[8:9], off offset:3072
	s_nop 0
	global_load_ushort v181, v[6:7], off offset:2048
	v_lshlrev_b32_e32 v7, 16, v106
	v_max_f32_e32 v7, v7, v7
	v_add_f32_e32 v84, 1.0, v87
	v_med3_f32 v7, v7, s9, v244
	v_rcp_f32_e32 v119, v84
	v_mul_f32_e32 v7, 0xbfb8aa3b, v7
	v_exp_f32_e32 v84, v7
	s_waitcnt vmcnt(52)
	v_lshlrev_b32_e32 v7, 16, v110
	v_fma_f32 v6, v80, v119, v149
	v_mul_f32_e32 v6, v15, v6
	v_add_f32_e32 v9, 1.0, v84
	v_max_f32_e32 v6, 0xda24260, v6
	v_rcp_f32_e32 v132, v9
	v_mul_f32_e32 v7, v6, v7
	v_bfe_u32 v9, v7, 16, 1
	v_lshl_add_u32 v17, v16, 1, v92
	v_add3_u32 v7, v7, v9, s10
	ds_write_b16_d16_hi v17, v7 offset:144
	v_fma_f32 v7, v80, v132, v149
	v_rcp_f32_e32 v123, v6
	v_mul_f32_e32 v6, v6, v7
	v_lshlrev_b32_e32 v7, 16, v107
	v_max_f32_e32 v7, v7, v7
	v_med3_f32 v7, v7, s9, v244
	v_mul_f32_e32 v7, 0xbfb8aa3b, v7
	v_exp_f32_e32 v85, v7
	v_max_f32_e32 v6, 0xda24260, v6
	v_lshlrev_b32_e32 v7, 16, v104
	v_mul_f32_e32 v7, v6, v7
	v_add_f32_e32 v9, 1.0, v85
	v_rcp_f32_e32 v133, v9
	v_bfe_u32 v9, v7, 16, 1
	v_add3_u32 v7, v7, v9, s10
	ds_write_b16_d16_hi v17, v7 offset:288
	v_fma_f32 v7, v80, v133, v149
	v_rcp_f32_e32 v134, v6
	v_mul_f32_e32 v6, v6, v7
	v_lshlrev_b32_e32 v7, 16, v88
	v_max_f32_e32 v7, v7, v7
	v_med3_f32 v7, v7, s9, v244
	v_mul_f32_e32 v7, 0xbfb8aa3b, v7
	v_exp_f32_e32 v74, v7
	v_max_f32_e32 v6, 0xda24260, v6
	s_waitcnt vmcnt(51)
	v_lshlrev_b32_e32 v7, 16, v111
	v_mul_f32_e32 v7, v6, v7
	v_add_f32_e32 v9, 1.0, v74
	v_rcp_f32_e32 v144, v9
	v_bfe_u32 v9, v7, 16, 1
	v_add3_u32 v7, v7, v9, s10
	ds_write_b16_d16_hi v17, v7 offset:432
	v_fma_f32 v7, v80, v144, v149
	v_rcp_f32_e32 v135, v6
	v_mul_f32_e32 v6, v6, v7
	v_max_f32_e32 v6, 0xda24260, v6
	v_rcp_f32_e32 v146, v6
	ds_write_b16_d16_hi v17, v105
	v_rcp_f32_e32 v122, v15
	v_pk_mul_f32 v[84:85], v[84:85], v[132:133]
	v_pk_mul_f32 v[86:87], v[86:87], v[118:119]
	v_pk_mul_f32 v[84:85], v[80:81], v[84:85] op_sel_hi:[0,1]
	v_pk_mul_f32 v[86:87], v[80:81], v[86:87] op_sel_hi:[0,1]
	s_movk_i32 s4, 0x50
	v_pk_mul_f32 v[84:85], v[84:85], v[134:135]
	v_pk_mul_f32 v[86:87], v[86:87], v[122:123]
	v_and_b32_sdwa v132, v85, v239 dst_sel:DWORD dst_unused:UNUSED_PAD src0_sel:WORD_1 src1_sel:DWORD
	s_waitcnt vmcnt(23)
	v_lshl_or_b32 v9, v66, 16, v158
	s_waitcnt vmcnt(22)
	v_lshl_or_b32 v13, v67, 16, v13
	v_mad_u64_u32 v[66:67], s[4:5], v16, s4, v[92:93]
	s_waitcnt vmcnt(20)
	v_lshlrev_b32_e32 v5, 16, v5
	v_max_f32_e32 v5, v5, v5
	v_med3_f32 v5, v5, s9, v244
	v_mul_f32_e32 v5, 0xbfb8aa3b, v5
	v_exp_f32_e32 v75, v5
	v_lshlrev_b32_e32 v5, 16, v95
	v_mul_f32_e32 v5, v6, v5
	s_waitcnt vmcnt(15)
	v_lshlrev_b32_e32 v0, 16, v0
	v_add_f32_e32 v7, 1.0, v75
	v_rcp_f32_e32 v145, v7
	v_bfe_u32 v7, v5, 16, 1
	v_add3_u32 v5, v5, v7, s10
	ds_write_b16_d16_hi v17, v5 offset:576
	v_fma_f32 v5, v80, v145, v149
	v_mul_f32_e32 v5, v6, v5
	v_lshlrev_b32_e32 v6, 16, v116
	v_max_f32_e32 v6, v6, v6
	v_med3_f32 v6, v6, s9, v244
	v_mul_f32_e32 v6, 0xbfb8aa3b, v6
	v_exp_f32_e32 v150, v6
	v_max_f32_e32 v5, 0xda24260, v5
	v_lshlrev_b32_e32 v6, 16, v130
	v_mul_f32_e32 v6, v5, v6
	v_add_f32_e32 v7, 1.0, v150
	v_rcp_f32_e32 v152, v7
	v_bfe_u32 v7, v6, 16, 1
	v_add3_u32 v6, v6, v7, s10
	ds_write_b16_d16_hi v17, v6 offset:720
	v_fma_f32 v6, v80, v152, v149
	v_rcp_f32_e32 v147, v5
	v_mul_f32_e32 v5, v5, v6
	s_waitcnt vmcnt(7)
	v_lshlrev_b32_e32 v6, 16, v138
	v_max_f32_e32 v6, v6, v6
	v_med3_f32 v6, v6, s9, v244
	v_mul_f32_e32 v6, 0xbfb8aa3b, v6
	v_exp_f32_e32 v151, v6
	v_max_f32_e32 v5, 0xda24260, v5
	v_lshlrev_b32_e32 v6, 16, v126
	v_mul_f32_e32 v6, v5, v6
	v_add_f32_e32 v7, 1.0, v151
	v_rcp_f32_e32 v153, v7
	v_bfe_u32 v7, v6, 16, 1
	v_add3_u32 v6, v6, v7, s10
	ds_write_b16_d16_hi v17, v6 offset:864
	v_fma_f32 v6, v80, v153, v149
	v_rcp_f32_e32 v154, v5
	v_mul_f32_e32 v5, v5, v6
	v_lshlrev_b32_e32 v6, 16, v117
	v_max_f32_e32 v6, v6, v6
	v_med3_f32 v6, v6, s9, v244
	v_mul_f32_e32 v6, 0xbfb8aa3b, v6
	v_exp_f32_e32 v104, v6
	v_max_f32_e32 v5, 0xda24260, v5
	v_lshlrev_b32_e32 v6, 16, v136
	v_mul_f32_e32 v6, v5, v6
	v_add_f32_e32 v7, 1.0, v104
	v_rcp_f32_e32 v106, v7
	v_bfe_u32 v7, v6, 16, 1
	v_add3_u32 v6, v6, v7, s10
	ds_write_b16_d16_hi v17, v6 offset:1008
	v_fma_f32 v6, v80, v106, v149
	v_rcp_f32_e32 v155, v5
	v_mul_f32_e32 v5, v5, v6
	s_waitcnt vmcnt(6)
	v_lshlrev_b32_e32 v6, 16, v139
	v_max_f32_e32 v6, v6, v6
	v_med3_f32 v6, v6, s9, v244
	v_mul_f32_e32 v6, 0xbfb8aa3b, v6
	v_exp_f32_e32 v105, v6
	v_max_f32_e32 v5, 0xda24260, v5
	v_lshlrev_b32_e32 v6, 16, v120
	v_mul_f32_e32 v6, v5, v6
	v_add_f32_e32 v7, 1.0, v105
	v_rcp_f32_e32 v107, v7
	v_bfe_u32 v7, v6, 16, 1
	v_add3_u32 v88, v6, v7, s10
	v_rcp_f32_e32 v110, v5
	v_fma_f32 v6, v80, v107, v149
	v_mul_f32_e32 v5, v5, v6
	v_lshlrev_b32_e32 v6, 16, v128
	v_max_f32_e32 v6, v6, v6
	v_med3_f32 v6, v6, s9, v244
	v_mul_f32_e32 v6, 0xbfb8aa3b, v6
	v_exp_f32_e32 v116, v6
	v_max_f32_e32 v5, 0xda24260, v5
	s_waitcnt vmcnt(5)
	v_lshlrev_b32_e32 v6, 16, v140
	v_mul_f32_e32 v6, v5, v6
	v_add_f32_e32 v7, 1.0, v116
	v_rcp_f32_e32 v120, v7
	v_bfe_u32 v7, v6, 16, 1
	v_add3_u32 v95, v6, v7, s10
	v_rcp_f32_e32 v111, v5
	v_fma_f32 v6, v80, v120, v149
	v_mul_f32_e32 v5, v5, v6
	v_lshlrev_b32_e32 v6, 16, v129
	v_max_f32_e32 v6, v6, v6
	v_med3_f32 v6, v6, s9, v244
	v_mul_f32_e32 v6, 0xbfb8aa3b, v6
	v_exp_f32_e32 v117, v6
	v_lshlrev_b32_e32 v6, 16, v121
	v_max_f32_e32 v5, 0xda24260, v5
	v_mul_f32_e32 v6, v5, v6
	v_add_f32_e32 v7, 1.0, v117
	v_rcp_f32_e32 v121, v7
	v_bfe_u32 v7, v6, 16, 1
	v_add3_u32 v182, v6, v7, s10
	v_rcp_f32_e32 v126, v5
	v_fma_f32 v6, v80, v121, v149
	v_mul_f32_e32 v5, v5, v6
	v_lshlrev_b32_e32 v6, 16, v127
	v_max_f32_e32 v6, v6, v6
	v_med3_f32 v6, v6, s9, v244
	v_mul_f32_e32 v6, 0xbfb8aa3b, v6
	v_exp_f32_e32 v128, v6
	v_max_f32_e32 v0, v0, v0
	v_med3_f32 v0, v0, s9, v244
	v_mul_f32_e32 v0, 0xbfb8aa3b, v0
	v_add_f32_e32 v7, 1.0, v128
	v_rcp_f32_e32 v130, v7
	v_max_f32_e32 v5, 0xda24260, v5
	s_waitcnt vmcnt(4)
	v_lshlrev_b32_e32 v6, 16, v10
	v_exp_f32_e32 v129, v0
	v_mul_f32_e32 v6, v5, v6
	v_bfe_u32 v7, v6, 16, 1
	v_add3_u32 v183, v6, v7, s10
	v_fma_f32 v6, v80, v130, v149
	v_rcp_f32_e32 v127, v5
	v_mul_f32_e32 v5, v5, v6
	v_add_f32_e32 v6, 1.0, v129
	v_max_f32_e32 v0, 0xda24260, v5
	v_lshlrev_b32_e32 v5, 16, v131
	v_rcp_f32_e32 v131, v6
	v_mul_f32_e32 v5, v0, v5
	v_bfe_u32 v6, v5, 16, 1
	v_add3_u32 v184, v5, v6, s10
	v_fma_f32 v5, v80, v131, v149
	v_rcp_f32_e32 v136, v0
	v_mul_f32_e32 v0, v0, v5
	v_lshlrev_b32_e32 v5, 16, v137
	v_max_f32_e32 v5, v5, v5
	v_med3_f32 v5, v5, s9, v244
	v_mul_f32_e32 v5, 0xbfb8aa3b, v5
	v_exp_f32_e32 v138, v5
	v_lshlrev_b32_e32 v1, 16, v1
	v_max_f32_e32 v1, v1, v1
	v_med3_f32 v1, v1, s9, v244
	v_add_f32_e32 v6, 1.0, v138
	v_rcp_f32_e32 v140, v6
	v_mul_f32_e32 v1, 0xbfb8aa3b, v1
	v_max_f32_e32 v0, 0xda24260, v0
	s_waitcnt vmcnt(3)
	v_lshlrev_b32_e32 v5, 16, v11
	v_exp_f32_e32 v139, v1
	v_mul_f32_e32 v5, v0, v5
	v_bfe_u32 v6, v5, 16, 1
	v_add3_u32 v185, v5, v6, s10
	v_fma_f32 v5, v80, v140, v149
	v_rcp_f32_e32 v137, v0
	v_mul_f32_e32 v0, v0, v5
	v_add_f32_e32 v5, 1.0, v139
	v_lshlrev_b32_e32 v1, 16, v141
	v_rcp_f32_e32 v141, v5
	v_max_f32_e32 v0, 0xda24260, v0
	v_mul_f32_e32 v1, v0, v1
	v_bfe_u32 v5, v1, 16, 1
	v_add3_u32 v186, v1, v5, s10
	v_fma_f32 v1, v80, v141, v149
	v_pk_mul_f32 v[150:151], v[150:151], v[152:153]
	v_pk_mul_f32 v[74:75], v[74:75], v[144:145]
	v_rcp_f32_e32 v142, v0
	v_mul_f32_e32 v0, v0, v1
	v_pk_mul_f32 v[150:151], v[80:81], v[150:151] op_sel_hi:[0,1]
	v_pk_mul_f32 v[74:75], v[80:81], v[74:75] op_sel_hi:[0,1]
	v_max_f32_e32 v187, 0xda24260, v0
	v_lshlrev_b32_e32 v0, 16, v2
	v_pk_mul_f32 v[150:151], v[150:151], v[154:155]
	v_pk_mul_f32 v[74:75], v[74:75], v[146:147]
	v_mul_f32_e32 v0, v187, v0
	v_and_b32_sdwa v152, v150, v239 dst_sel:DWORD dst_unused:UNUSED_PAD src0_sel:WORD_1 src1_sel:DWORD
	v_and_b32_sdwa v144, v75, v239 dst_sel:DWORD dst_unused:UNUSED_PAD src0_sel:WORD_1 src1_sel:DWORD
	v_and_b32_sdwa v145, v74, v239 dst_sel:DWORD dst_unused:UNUSED_PAD src0_sel:WORD_1 src1_sel:DWORD
	v_and_b32_sdwa v133, v84, v239 dst_sel:DWORD dst_unused:UNUSED_PAD src0_sel:WORD_1 src1_sel:DWORD
	v_and_b32_sdwa v118, v87, v239 dst_sel:DWORD dst_unused:UNUSED_PAD src0_sel:WORD_1 src1_sel:DWORD
	v_and_b32_sdwa v119, v86, v239 dst_sel:DWORD dst_unused:UNUSED_PAD src0_sel:WORD_1 src1_sel:DWORD
	v_bfe_u32 v1, v0, 16, 1
	v_and_b32_sdwa v67, v151, v239 dst_sel:DWORD dst_unused:UNUSED_PAD src0_sel:WORD_1 src1_sel:DWORD
	v_add3_u32 v150, v150, v152, s10
	v_add3_u32 v75, v75, v144, s10
	v_add3_u32 v74, v74, v145, s10
	v_add3_u32 v85, v85, v132, s10
	v_add3_u32 v84, v84, v133, s10
	v_add3_u32 v87, v87, v118, s10
	v_add3_u32 v86, v86, v119, s10
	v_rcp_f32_e32 v143, v187
	v_add3_u32 v188, v0, v1, s10
	v_lshl_or_b32 v3, v3, 16, v170
	v_lshl_or_b32 v2, v176, 16, v169
	v_lshl_or_b32 v1, v171, 16, v168
	v_lshl_or_b32 v0, v177, 16, v167
	v_lshl_or_b32 v7, v178, 16, v166
	v_lshl_or_b32 v6, v173, 16, v165
	v_lshl_or_b32 v5, v172, 16, v164
	v_lshl_or_b32 v4, v4, 16, v163
	v_lshl_or_b32 v11, v179, 16, v162
	s_waitcnt vmcnt(2)
	v_lshl_or_b32 v10, v180, 16, v159
	s_waitcnt vmcnt(1)
	v_lshl_or_b32 v8, v8, 16, v157
	s_waitcnt vmcnt(0)
	v_lshl_or_b32 v15, v181, 16, v156
	v_lshl_or_b32 v14, v174, 16, v14
	v_lshl_or_b32 v12, v175, 16, v12
	s_movk_i32 s16, 0x50
	v_add3_u32 v67, v151, v67, s10
	ds_write_b16_d16_hi v17, v150 offset:5472
	ds_write_b16_d16_hi v17, v67 offset:5616
	ds_write_b16_d16_hi v17, v74 offset:5184
	ds_write_b16_d16_hi v17, v75 offset:5328
	v_and_b32_e32 v75, 0xffff0000, v75
	v_and_b32_e32 v74, 0xffff0000, v74
	ds_write_b16_d16_hi v17, v84 offset:4896
	ds_write_b16_d16_hi v17, v85 offset:5040
	v_and_b32_e32 v85, 0xffff0000, v85
	v_and_b32_e32 v84, 0xffff0000, v84
	ds_write_b16_d16_hi v17, v86 offset:4608
	ds_write_b16_d16_hi v17, v87 offset:4752
	v_and_b32_e32 v87, 0xffff0000, v87
	v_and_b32_e32 v86, 0xffff0000, v86
	global_load_ushort v118, v[76:77], off offset:3072
	s_nop 0
	global_load_ushort v102, v[102:103], off offset:3072
	s_nop 0
	global_load_ushort v103, v[78:79], off offset:1024
	global_load_ushort v119, v[82:83], off offset:1024
	global_load_ushort v123, v[82:83], off offset:2048
	s_nop 0
	global_load_ushort v78, v[78:79], off
	s_nop 0
	global_load_ushort v79, v[76:77], off offset:2048
	global_load_ushort v82, v[124:125], off offset:3584
	s_mov_b32 s5, 0xb215000
	v_add_co_u32_e32 v76, vcc, s5, v18
	v_pk_mul_f32 v[138:139], v[138:139], v[140:141]
	s_nop 0
	v_addc_co_u32_e32 v77, vcc, 0, v19, vcc
	global_load_ushort v83, v[76:77], off
	s_nop 0
	global_load_ushort v76, v[76:77], off offset:3584
	s_nop 0
	global_load_ushort v77, v[124:125], off offset:2560
	s_nop 0
	global_load_ushort v114, v[114:115], off offset:512
	s_nop 0
	global_load_ushort v115, v[112:113], off offset:1536
	global_load_ushort v144, v[108:109], off offset:1536
	ds_write_b16_d16_hi v17, v88 offset:1152
	ds_write_b16_d16_hi v17, v95 offset:1296
	ds_write_b16_d16_hi v17, v182 offset:1440
	ds_write_b16_d16_hi v17, v183 offset:1584
	ds_write_b16_d16_hi v17, v184 offset:1728
	ds_write_b16_d16_hi v17, v185 offset:1872
	ds_write_b16_d16_hi v17, v186 offset:2016
	ds_write_b16_d16_hi v17, v188 offset:2160
	global_load_ushort v88, v[112:113], off offset:512
	global_load_ushort v95, v[108:109], off offset:2560
	v_pk_mul_f32 v[128:129], v[128:129], v[130:131]
	v_pk_mul_f32 v[116:117], v[116:117], v[120:121]
	v_pk_mul_f32 v[104:105], v[104:105], v[106:107]
	v_pk_mul_f32 v[138:139], v[80:81], v[138:139] op_sel_hi:[0,1]
	v_pk_mul_f32 v[128:129], v[80:81], v[128:129] op_sel_hi:[0,1]
	v_pk_mul_f32 v[116:117], v[80:81], v[116:117] op_sel_hi:[0,1]
	v_pk_mul_f32 v[104:105], v[80:81], v[104:105] op_sel_hi:[0,1]
	v_pk_mul_f32 v[138:139], v[138:139], v[142:143]
	v_pk_mul_f32 v[128:129], v[128:129], v[136:137]
	v_pk_mul_f32 v[116:117], v[116:117], v[126:127]
	v_pk_mul_f32 v[104:105], v[104:105], v[110:111]
	v_and_b32_sdwa v140, v138, v239 dst_sel:DWORD dst_unused:UNUSED_PAD src0_sel:WORD_1 src1_sel:DWORD
	v_and_b32_sdwa v130, v129, v239 dst_sel:DWORD dst_unused:UNUSED_PAD src0_sel:WORD_1 src1_sel:DWORD
	v_and_b32_sdwa v131, v128, v239 dst_sel:DWORD dst_unused:UNUSED_PAD src0_sel:WORD_1 src1_sel:DWORD
	v_and_b32_sdwa v120, v117, v239 dst_sel:DWORD dst_unused:UNUSED_PAD src0_sel:WORD_1 src1_sel:DWORD
	v_and_b32_sdwa v121, v116, v239 dst_sel:DWORD dst_unused:UNUSED_PAD src0_sel:WORD_1 src1_sel:DWORD
	v_and_b32_sdwa v106, v105, v239 dst_sel:DWORD dst_unused:UNUSED_PAD src0_sel:WORD_1 src1_sel:DWORD
	v_and_b32_sdwa v107, v104, v239 dst_sel:DWORD dst_unused:UNUSED_PAD src0_sel:WORD_1 src1_sel:DWORD
	v_add3_u32 v142, v138, v140, s10
	v_add3_u32 v129, v129, v130, s10
	v_add3_u32 v128, v128, v131, s10
	v_add3_u32 v117, v117, v120, s10
	v_add3_u32 v116, v116, v121, s10
	v_add3_u32 v105, v105, v106, s10
	v_add3_u32 v104, v104, v107, s10
	s_waitcnt vmcnt(15)
	v_lshlrev_b32_e32 v108, 16, v118
	s_waitcnt vmcnt(14)
	v_lshlrev_b32_e32 v113, 16, v102
	s_waitcnt vmcnt(10)
	v_lshlrev_b32_e32 v118, 16, v78
	v_max_f32_e32 v78, v108, v108
	s_waitcnt vmcnt(9)
	v_lshlrev_b32_e32 v112, 16, v79
	s_waitcnt vmcnt(8)
	v_lshlrev_b32_e32 v79, 16, v82
	v_med3_f32 v78, v78, s9, v244
	v_lshlrev_b32_e32 v82, 16, v103
	v_max_f32_e32 v79, v79, v79
	v_mul_f32_e32 v78, 0xbfb8aa3b, v78
	s_waitcnt vmcnt(5)
	v_lshlrev_b32_e32 v122, 16, v77
	v_lshlrev_b32_e32 v77, 16, v83
	v_lshlrev_b32_e32 v124, 16, v76
	v_max_f32_e32 v76, v82, v82
	s_waitcnt vmcnt(3)
	v_lshlrev_b32_e32 v82, 16, v115
	v_med3_f32 v79, v79, s9, v244
	v_exp_f32_e32 v102, v78
	v_max_f32_e32 v77, v77, v77
	v_max_f32_e32 v82, v82, v82
	v_mul_f32_e32 v79, 0xbfb8aa3b, v79
	v_lshlrev_b32_e32 v83, 16, v114
	v_med3_f32 v76, v76, s9, v244
	v_med3_f32 v77, v77, s9, v244
	v_med3_f32 v82, v82, s9, v244
	v_exp_f32_e32 v103, v79
	v_max_f32_e32 v83, v83, v83
	v_mul_f32_e32 v76, 0xbfb8aa3b, v76
	v_mul_f32_e32 v77, 0xbfb8aa3b, v77
	v_mul_f32_e32 v82, 0xbfb8aa3b, v82
	v_med3_f32 v83, v83, s9, v244
	v_exp_f32_e32 v76, v76
	v_exp_f32_e32 v78, v77
	v_exp_f32_e32 v77, v82
	v_add_f32_e32 v82, 1.0, v102
	v_mul_f32_e32 v79, 0xbfb8aa3b, v83
	v_rcp_f32_e32 v114, v82
	v_exp_f32_e32 v79, v79
	v_add_f32_e32 v83, 1.0, v103
	v_rcp_f32_e32 v115, v83
	v_add_f32_e32 v108, 1.0, v76
	v_add_f32_e32 v83, 1.0, v78
	v_rcp_f32_e32 v82, v108
	v_rcp_f32_e32 v108, v83
	v_fma_f32 v83, v80, v114, v149
	v_add_f32_e32 v109, 1.0, v79
	v_mul_f32_e32 v83, v187, v83
	v_rcp_f32_e32 v109, v109
	v_fma_f32 v125, v80, v115, v149
	v_max_f32_e32 v83, 0xda24260, v83
	v_rcp_f32_e32 v134, v83
	v_mul_f32_e32 v112, v83, v112
	v_mul_f32_e32 v83, v83, v125
	v_fma_f32 v132, v80, v108, v149
	v_bfe_u32 v125, v112, 16, 1
	v_max_f32_e32 v83, 0xda24260, v83
	v_add3_u32 v146, v112, v125, s10
	v_rcp_f32_e32 v135, v83
	v_mul_f32_e32 v112, v83, v122
	v_mul_f32_e32 v83, v83, v132
	v_fma_f32 v133, v80, v109, v149
	v_bfe_u32 v122, v112, 16, 1
	v_max_f32_e32 v83, 0xda24260, v83
	v_add3_u32 v147, v112, v122, s10
	v_rcp_f32_e32 v132, v83
	v_mul_f32_e32 v112, v83, v113
	v_mul_f32_e32 v83, v83, v133
	v_fma_f32 v145, v80, v82, v149
	v_bfe_u32 v113, v112, 16, 1
	v_max_f32_e32 v83, 0xda24260, v83
	v_add3_u32 v151, v112, v113, s10
	v_rcp_f32_e32 v133, v83
	v_mul_f32_e32 v112, v83, v124
	v_mul_f32_e32 v83, v83, v145
	v_max_f32_e32 v124, 0xda24260, v83
	v_add_f32_e32 v83, 1.0, v77
	v_rcp_f32_e32 v83, v83
	v_bfe_u32 v113, v112, 16, 1
	v_add3_u32 v152, v112, v113, s10
	v_mul_f32_e32 v112, v124, v118
	v_bfe_u32 v113, v112, 16, 1
	v_add3_u32 v153, v112, v113, s10
	v_fma_f32 v112, v80, v83, v149
	v_mul_f32_e32 v113, v124, v112
	v_lshlrev_b32_e32 v112, 16, v123
	v_max_f32_e32 v112, v112, v112
	v_med3_f32 v112, v112, s9, v244
	v_mul_f32_e32 v112, 0xbfb8aa3b, v112
	v_exp_f32_e32 v112, v112
	v_max_f32_e32 v113, 0xda24260, v113
	s_waitcnt vmcnt(1)
	v_lshlrev_b32_e32 v88, 16, v88
	s_waitcnt vmcnt(0)
	v_lshlrev_b32_e32 v95, 16, v95
	v_add_f32_e32 v118, 1.0, v112
	v_rcp_f32_e32 v118, v118
	v_mul_f32_e32 v88, v113, v88
	v_max_f32_e32 v95, v95, v95
	v_rcp_f32_e32 v122, v124
	v_bfe_u32 v124, v88, 16, 1
	v_med3_f32 v95, v95, s9, v244
	v_add3_u32 v88, v88, v124, s10
	v_fma_f32 v124, v80, v118, v149
	v_mul_f32_e32 v95, 0xbfb8aa3b, v95
	v_rcp_f32_e32 v123, v113
	v_mul_f32_e32 v124, v113, v124
	v_exp_f32_e32 v113, v95
	v_lshlrev_b32_e32 v125, 16, v119
	v_max_f32_e32 v95, 0xda24260, v124
	v_mul_f32_e32 v125, v95, v125
	v_add_f32_e32 v119, 1.0, v113
	v_rcp_f32_e32 v119, v119
	v_bfe_u32 v145, v125, 16, 1
	v_add3_u32 v154, v125, v145, s10
	v_rcp_f32_e32 v124, v95
	v_fma_f32 v125, v80, v119, v149
	v_mul_f32_e32 v95, v95, v125
	v_max_f32_e32 v95, 0xda24260, v95
	v_lshlrev_b32_e32 v144, 16, v144
	v_mul_f32_e32 v144, v95, v144
	v_bfe_u32 v145, v144, 16, 1
	v_add3_u32 v155, v144, v145, s10
	v_and_b32_e32 v145, 0xffff0000, v67
	v_and_b32_sdwa v67, v139, v239 dst_sel:DWORD dst_unused:UNUSED_PAD src0_sel:WORD_1 src1_sel:DWORD
	v_rcp_f32_e32 v125, v95
	v_and_b32_e32 v144, 0xffff0000, v150
	v_add3_u32 v67, v139, v67, s10
	ds_write_b16_d16_hi v17, v142 offset:6624
	ds_write_b16_d16_hi v17, v67 offset:6768
	ds_write_b16_d16_hi v17, v128 offset:6336
	ds_write_b16_d16_hi v17, v129 offset:6480
	v_and_b32_e32 v129, 0xffff0000, v129
	v_and_b32_e32 v128, 0xffff0000, v128
	ds_write_b16_d16_hi v17, v116 offset:6048
	ds_write_b16_d16_hi v17, v117 offset:6192
	v_and_b32_e32 v117, 0xffff0000, v117
	v_and_b32_e32 v116, 0xffff0000, v116
	ds_write_b16_d16_hi v17, v104 offset:5760
	ds_write_b16_d16_hi v17, v105 offset:5904
	v_and_b32_e32 v105, 0xffff0000, v105
	v_and_b32_e32 v104, 0xffff0000, v104
	global_load_ushort v106, v[20:21], off offset:3072
	s_nop 0
	global_load_ushort v68, v[68:69], off offset:3072
	s_nop 0
	global_load_ushort v69, v[22:23], off offset:1024
	global_load_ushort v139, v[24:25], off offset:1024
	global_load_ushort v131, v[24:25], off offset:2048
	s_nop 0
	global_load_ushort v22, v[22:23], off
	s_nop 0
	global_load_ushort v20, v[20:21], off offset:2048
	s_nop 0
	global_load_ushort v21, v[72:73], off offset:3584
	s_mov_b32 s4, 0xb21e000
	v_add_co_u32_e32 v18, vcc, s4, v18
	s_waitcnt vmcnt(6)
	v_lshlrev_b32_e32 v68, 16, v68
	v_addc_co_u32_e32 v19, vcc, 0, v19, vcc
	global_load_ushort v23, v[18:19], off
	s_nop 0
	global_load_ushort v18, v[18:19], off offset:3584
	s_nop 0
	global_load_ushort v19, v[72:73], off offset:2560
	global_load_ushort v24, v[70:71], off offset:512
	global_load_ushort v25, v[64:65], off offset:1536
	s_nop 0
	global_load_ushort v70, v[62:63], off offset:1536
	ds_write_b16_d16_hi v17, v146 offset:2304
	ds_write_b16_d16_hi v17, v147 offset:2448
	ds_write_b16_d16_hi v17, v151 offset:2592
	ds_write_b16_d16_hi v17, v152 offset:2736
	ds_write_b16_d16_hi v17, v153 offset:2880
	ds_write_b16_d16_hi v17, v88 offset:3024
	ds_write_b16_d16_hi v17, v154 offset:3168
	ds_write_b16_d16_hi v17, v155 offset:3312
	global_load_ushort v64, v[64:65], off offset:512
	s_nop 0
	global_load_ushort v62, v[62:63], off offset:2560
	v_lshlrev_b32_e32 v63, 16, v106
	s_waitcnt vmcnt(9)
	v_lshlrev_b32_e32 v65, 16, v20
	s_waitcnt vmcnt(8)
	v_lshlrev_b32_e32 v20, 16, v21
	v_lshlrev_b32_e32 v21, 16, v69
	v_lshlrev_b32_e32 v69, 16, v22
	v_max_f32_e32 v22, v63, v63
	v_med3_f32 v22, v22, s9, v244
	v_max_f32_e32 v20, v20, v20
	v_mul_f32_e32 v22, 0xbfb8aa3b, v22
	v_med3_f32 v20, v20, s9, v244
	v_mul_f32_e32 v20, 0xbfb8aa3b, v20
	s_waitcnt vmcnt(6)
	v_lshlrev_b32_e32 v71, 16, v18
	s_waitcnt vmcnt(5)
	v_lshlrev_b32_e32 v63, 16, v19
	v_lshlrev_b32_e32 v19, 16, v23
	s_waitcnt vmcnt(4)
	v_lshlrev_b32_e32 v23, 16, v24
	v_exp_f32_e32 v24, v22
	v_max_f32_e32 v18, v21, v21
	s_waitcnt vmcnt(3)
	v_lshlrev_b32_e32 v21, 16, v25
	v_max_f32_e32 v19, v19, v19
	v_max_f32_e32 v23, v23, v23
	v_max_f32_e32 v21, v21, v21
	v_med3_f32 v19, v19, s9, v244
	v_med3_f32 v23, v23, s9, v244
	v_exp_f32_e32 v25, v20
	v_med3_f32 v21, v21, s9, v244
	v_mul_f32_e32 v19, 0xbfb8aa3b, v19
	v_mul_f32_e32 v22, 0xbfb8aa3b, v23
	v_med3_f32 v18, v18, s9, v244
	v_mul_f32_e32 v23, 0xbfb8aa3b, v21
	v_exp_f32_e32 v20, v19
	v_exp_f32_e32 v21, v22
	v_add_f32_e32 v22, 1.0, v24
	v_mul_f32_e32 v18, 0xbfb8aa3b, v18
	v_rcp_f32_e32 v106, v22
	v_exp_f32_e32 v18, v18
	v_exp_f32_e32 v19, v23
	v_add_f32_e32 v23, 1.0, v25
	v_rcp_f32_e32 v107, v23
	v_add_f32_e32 v23, 1.0, v20
	v_rcp_f32_e32 v110, v23
	v_fma_f32 v23, v80, v106, v149
	v_add_f32_e32 v72, 1.0, v18
	v_add_f32_e32 v73, 1.0, v21
	v_mul_f32_e32 v23, v95, v23
	v_rcp_f32_e32 v22, v72
	v_rcp_f32_e32 v111, v73
	v_fma_f32 v72, v80, v107, v149
	v_max_f32_e32 v23, 0xda24260, v23
	v_rcp_f32_e32 v120, v23
	v_mul_f32_e32 v65, v23, v65
	v_mul_f32_e32 v23, v23, v72
	v_fma_f32 v88, v80, v110, v149
	v_max_f32_e32 v23, 0xda24260, v23
	v_bfe_u32 v72, v65, 16, 1
	v_rcp_f32_e32 v121, v23
	v_mul_f32_e32 v63, v23, v63
	v_mul_f32_e32 v23, v23, v88
	v_fma_f32 v95, v80, v111, v149
	v_add3_u32 v143, v65, v72, s10
	v_bfe_u32 v65, v63, 16, 1
	v_max_f32_e32 v23, 0xda24260, v23
	v_add3_u32 v146, v63, v65, s10
	v_rcp_f32_e32 v126, v23
	v_mul_f32_e32 v63, v23, v68
	v_mul_f32_e32 v23, v23, v95
	v_fma_f32 v73, v80, v22, v149
	v_bfe_u32 v65, v63, 16, 1
	v_max_f32_e32 v23, 0xda24260, v23
	v_add3_u32 v95, v63, v65, s10
	v_rcp_f32_e32 v127, v23
	v_mul_f32_e32 v63, v23, v71
	v_mul_f32_e32 v23, v23, v73
	v_bfe_u32 v65, v63, 16, 1
	v_max_f32_e32 v68, 0xda24260, v23
	v_add3_u32 v147, v63, v65, s10
	v_mul_f32_e32 v63, v68, v69
	v_bfe_u32 v65, v63, 16, 1
	v_add3_u32 v150, v63, v65, s10
	v_lshlrev_b32_e32 v65, 16, v131
	v_max_f32_e32 v65, v65, v65
	v_med3_f32 v65, v65, s9, v244
	v_add_f32_e32 v23, 1.0, v19
	v_mul_f32_e32 v65, 0xbfb8aa3b, v65
	v_rcp_f32_e32 v23, v23
	v_exp_f32_e32 v136, v65
	s_waitcnt vmcnt(0)
	v_lshlrev_b32_e32 v62, 16, v62
	v_max_f32_e32 v62, v62, v62
	v_fma_f32 v63, v80, v23, v149
	v_add_f32_e32 v65, 1.0, v136
	v_med3_f32 v62, v62, s9, v244
	v_mul_f32_e32 v63, v68, v63
	v_rcp_f32_e32 v138, v65
	v_mul_f32_e32 v62, 0xbfb8aa3b, v62
	v_max_f32_e32 v63, 0xda24260, v63
	v_lshlrev_b32_e32 v64, 16, v64
	v_exp_f32_e32 v137, v62
	v_mul_f32_e32 v64, v63, v64
	v_bfe_u32 v65, v64, 16, 1
	v_add3_u32 v151, v64, v65, s10
	v_fma_f32 v64, v80, v138, v149
	v_rcp_f32_e32 v131, v63
	v_mul_f32_e32 v63, v63, v64
	v_add_f32_e32 v64, 1.0, v137
	v_max_f32_e32 v62, 0xda24260, v63
	v_lshlrev_b32_e32 v63, 16, v139
	v_rcp_f32_e32 v139, v64
	v_mul_f32_e32 v63, v62, v63
	v_bfe_u32 v64, v63, 16, 1
	v_add3_u32 v152, v63, v64, s10
	v_fma_f32 v63, v80, v139, v149
	v_rcp_f32_e32 v140, v62
	v_mul_f32_e32 v62, v62, v63
	v_max_f32_e32 v88, 0xda24260, v62
	v_lshlrev_b32_e32 v62, 16, v70
	v_mul_f32_e32 v62, v88, v62
	v_bfe_u32 v63, v62, 16, 1
	v_add3_u32 v153, v62, v63, s10
	v_pk_mul_f32 v[62:63], v[88:89], v[86:87] op_sel_hi:[0,1]
	v_pk_mul_f32 v[64:65], v[88:89], v[84:85] op_sel_hi:[0,1]
	v_rcp_f32_e32 v130, v68
	v_cvt_pk_bf16_f32 v62, v62, v63
	v_cvt_pk_bf16_f32 v63, v64, v65
	v_pk_mul_f32 v[64:65], v[88:89], v[74:75] op_sel_hi:[0,1]
	v_pk_mul_f32 v[68:69], v[88:89], v[144:145] op_sel_hi:[0,1]
	v_cvt_pk_bf16_f32 v64, v64, v65
	v_cvt_pk_bf16_f32 v65, v68, v69
	v_pk_mul_f32 v[68:69], v[88:89], v[104:105] op_sel_hi:[0,1]
	v_pk_mul_f32 v[70:71], v[88:89], v[116:117] op_sel_hi:[0,1]
	v_and_b32_e32 v73, 0xffff0000, v67
	v_and_b32_e32 v72, 0xffff0000, v142
	v_cvt_pk_bf16_f32 v68, v68, v69
	v_cvt_pk_bf16_f32 v69, v70, v71
	v_pk_mul_f32 v[70:71], v[88:89], v[128:129] op_sel_hi:[0,1]
	v_pk_mul_f32 v[72:73], v[88:89], v[72:73] op_sel_hi:[0,1]
	v_cvt_pk_bf16_f32 v70, v70, v71
	v_cvt_pk_bf16_f32 v71, v72, v73
	v_pk_mul_f32 v[72:73], v[102:103], v[114:115]
	v_rcp_f32_e32 v141, v88
	v_pk_mul_f32 v[72:73], v[80:81], v[72:73] op_sel_hi:[0,1]
	v_pk_mul_f32 v[72:73], v[72:73], v[134:135]
	s_nop 0
	v_and_b32_sdwa v67, v73, v239 dst_sel:DWORD dst_unused:UNUSED_PAD src0_sel:WORD_1 src1_sel:DWORD
	v_and_b32_sdwa v74, v72, v239 dst_sel:DWORD dst_unused:UNUSED_PAD src0_sel:WORD_1 src1_sel:DWORD
	v_add3_u32 v67, v73, v67, s10
	v_add3_u32 v72, v72, v74, s10
	v_pk_mul_f32 v[74:75], v[78:79], v[108:109]
	ds_write_b16_d16_hi v17, v72 offset:6912
	ds_write_b16_d16_hi v17, v67 offset:7056
	v_and_b32_e32 v73, 0xffff0000, v67
	v_and_b32_e32 v72, 0xffff0000, v72
	v_pk_mul_f32 v[74:75], v[80:81], v[74:75] op_sel_hi:[0,1]
	v_pk_mul_f32 v[72:73], v[88:89], v[72:73] op_sel_hi:[0,1]
	v_pk_mul_f32 v[74:75], v[74:75], v[132:133]
	v_cvt_pk_bf16_f32 v72, v72, v73
	v_and_b32_sdwa v67, v75, v239 dst_sel:DWORD dst_unused:UNUSED_PAD src0_sel:WORD_1 src1_sel:DWORD
	v_and_b32_sdwa v73, v74, v239 dst_sel:DWORD dst_unused:UNUSED_PAD src0_sel:WORD_1 src1_sel:DWORD
	v_add3_u32 v67, v75, v67, s10
	v_add3_u32 v73, v74, v73, s10
	v_and_b32_e32 v75, 0xffff0000, v67
	v_and_b32_e32 v74, 0xffff0000, v73
	v_pk_mul_f32 v[74:75], v[88:89], v[74:75] op_sel_hi:[0,1]
	ds_write_b16_d16_hi v17, v73 offset:7200
	ds_write_b16_d16_hi v17, v67 offset:7344
	v_cvt_pk_bf16_f32 v73, v74, v75
	v_pk_mul_f32 v[74:75], v[76:77], v[82:83]
	s_nop 0
	v_pk_mul_f32 v[74:75], v[80:81], v[74:75] op_sel_hi:[0,1]
	v_pk_mul_f32 v[74:75], v[74:75], v[122:123]
	s_nop 0
	v_and_b32_sdwa v67, v75, v239 dst_sel:DWORD dst_unused:UNUSED_PAD src0_sel:WORD_1 src1_sel:DWORD
	v_and_b32_sdwa v76, v74, v239 dst_sel:DWORD dst_unused:UNUSED_PAD src0_sel:WORD_1 src1_sel:DWORD
	v_add3_u32 v67, v75, v67, s10
	v_add3_u32 v74, v74, v76, s10
	v_pk_mul_f32 v[76:77], v[112:113], v[118:119]
	ds_write_b16_d16_hi v17, v74 offset:7488
	ds_write_b16_d16_hi v17, v67 offset:7632
	v_and_b32_e32 v75, 0xffff0000, v67
	v_and_b32_e32 v74, 0xffff0000, v74
	v_pk_mul_f32 v[76:77], v[80:81], v[76:77] op_sel_hi:[0,1]
	v_pk_mul_f32 v[74:75], v[88:89], v[74:75] op_sel_hi:[0,1]
	v_pk_mul_f32 v[76:77], v[76:77], v[124:125]
	v_cvt_pk_bf16_f32 v74, v74, v75
	v_and_b32_sdwa v75, v76, v239 dst_sel:DWORD dst_unused:UNUSED_PAD src0_sel:WORD_1 src1_sel:DWORD
	v_and_b32_sdwa v67, v77, v239 dst_sel:DWORD dst_unused:UNUSED_PAD src0_sel:WORD_1 src1_sel:DWORD
	v_add3_u32 v75, v76, v75, s10
	v_add3_u32 v67, v77, v67, s10
	ds_write_b16_d16_hi v17, v75 offset:7776
	ds_write_b16_d16_hi v17, v67 offset:7920
	v_pk_mul_f32 v[24:25], v[24:25], v[106:107]
	v_and_b32_e32 v77, 0xffff0000, v67
	v_and_b32_e32 v76, 0xffff0000, v75
	v_pk_mul_f32 v[24:25], v[80:81], v[24:25] op_sel_hi:[0,1]
	v_pk_mul_f32 v[76:77], v[88:89], v[76:77] op_sel_hi:[0,1]
	v_pk_mul_f32 v[24:25], v[24:25], v[120:121]
	v_cvt_pk_bf16_f32 v75, v76, v77
	v_and_b32_sdwa v67, v25, v239 dst_sel:DWORD dst_unused:UNUSED_PAD src0_sel:WORD_1 src1_sel:DWORD
	v_and_b32_sdwa v76, v24, v239 dst_sel:DWORD dst_unused:UNUSED_PAD src0_sel:WORD_1 src1_sel:DWORD
	v_add3_u32 v25, v25, v67, s10
	v_add3_u32 v24, v24, v76, s10
	v_pk_mul_f32 v[20:21], v[20:21], v[110:111]
	ds_write_b16_d16_hi v17, v143 offset:3456
	ds_write_b16_d16_hi v17, v146 offset:3600
	ds_write_b16_d16_hi v17, v95 offset:3744
	ds_write_b16_d16_hi v17, v147 offset:3888
	ds_write_b16_d16_hi v17, v150 offset:4032
	ds_write_b16_d16_hi v17, v151 offset:4176
	ds_write_b16_d16_hi v17, v152 offset:4320
	ds_write_b16_d16_hi v17, v153 offset:4464
	ds_write_b16_d16_hi v17, v24 offset:8064
	ds_write_b16_d16_hi v17, v25 offset:8208
	v_and_b32_e32 v25, 0xffff0000, v25
	v_and_b32_e32 v24, 0xffff0000, v24
	v_pk_mul_f32 v[20:21], v[80:81], v[20:21] op_sel_hi:[0,1]
	v_pk_mul_f32 v[24:25], v[88:89], v[24:25] op_sel_hi:[0,1]
	v_pk_mul_f32 v[20:21], v[20:21], v[126:127]
	v_cvt_pk_bf16_f32 v76, v24, v25
	v_and_b32_sdwa v24, v21, v239 dst_sel:DWORD dst_unused:UNUSED_PAD src0_sel:WORD_1 src1_sel:DWORD
	v_and_b32_sdwa v25, v20, v239 dst_sel:DWORD dst_unused:UNUSED_PAD src0_sel:WORD_1 src1_sel:DWORD
	v_add3_u32 v21, v21, v24, s10
	v_add3_u32 v20, v20, v25, s10
	v_pk_mul_f32 v[18:19], v[18:19], v[22:23]
	ds_write_b16_d16_hi v17, v20 offset:8352
	ds_write_b16_d16_hi v17, v21 offset:8496
	v_and_b32_e32 v21, 0xffff0000, v21
	v_and_b32_e32 v20, 0xffff0000, v20
	v_pk_mul_f32 v[18:19], v[80:81], v[18:19] op_sel_hi:[0,1]
	v_pk_mul_f32 v[20:21], v[88:89], v[20:21] op_sel_hi:[0,1]
	v_pk_mul_f32 v[18:19], v[18:19], v[130:131]
	v_cvt_pk_bf16_f32 v77, v20, v21
	v_and_b32_sdwa v20, v19, v239 dst_sel:DWORD dst_unused:UNUSED_PAD src0_sel:WORD_1 src1_sel:DWORD
	v_and_b32_sdwa v21, v18, v239 dst_sel:DWORD dst_unused:UNUSED_PAD src0_sel:WORD_1 src1_sel:DWORD
	v_add3_u32 v19, v19, v20, s10
	v_add3_u32 v18, v18, v21, s10
	ds_write_b16_d16_hi v17, v18 offset:8640
	ds_write_b16_d16_hi v17, v19 offset:8784
	v_and_b32_e32 v19, 0xffff0000, v19
	v_and_b32_e32 v18, 0xffff0000, v18
	v_pk_mul_f32 v[18:19], v[88:89], v[18:19] op_sel_hi:[0,1]
	v_cvt_pk_bf16_f32 v78, v18, v19
	v_pk_mul_f32 v[18:19], v[136:137], v[138:139]
	s_nop 0
	v_pk_mul_f32 v[18:19], v[80:81], v[18:19] op_sel_hi:[0,1]
	v_pk_mul_f32 v[18:19], v[18:19], v[140:141]
	s_nop 0
	v_and_b32_sdwa v21, v18, v239 dst_sel:DWORD dst_unused:UNUSED_PAD src0_sel:WORD_1 src1_sel:DWORD
	v_and_b32_sdwa v20, v19, v239 dst_sel:DWORD dst_unused:UNUSED_PAD src0_sel:WORD_1 src1_sel:DWORD
	v_add3_u32 v18, v18, v21, s10
	v_add3_u32 v19, v19, v20, s10
	ds_write_b16_d16_hi v17, v18 offset:8928
	ds_write_b16_d16_hi v17, v19 offset:9072
	v_and_b32_e32 v19, 0xffff0000, v19
	v_and_b32_e32 v18, 0xffff0000, v18
	v_pk_mul_f32 v[18:19], v[88:89], v[18:19] op_sel_hi:[0,1]
	v_cvt_pk_bf16_f32 v79, v18, v19
	v_lshl_add_u32 v16, v16, 2, v92
	ds_write_b128 v66, v[62:65] offset:9216
	ds_write_b128 v66, v[68:71] offset:9232
	ds_write_b128 v66, v[72:75] offset:9248
	ds_write_b128 v66, v[76:79] offset:9264
	ds_write_b32 v16, v88 offset:19456
	ds_write_b128 v66, v[12:15] offset:14336
	ds_write_b128 v66, v[8:11] offset:14352
	ds_write_b128 v66, v[4:7] offset:14368
	ds_write_b128 v66, v[0:3] offset:14384
	s_waitcnt lgkmcnt(0)
	s_movk_i32 s17, 0x90
	v_mad_u32_u24 v72, v35, s17, v92
	v_lshlrev_b32_e32 v73, 4, v81
	v_add_u32_e32 v66, v72, v73
	ds_read_b128 v[0:3], v66 offset:4608
	ds_read_b128 v[4:7], v66
	ds_read_b128 v[18:21], v66 offset:32
	ds_read_b128 v[22:25], v66 offset:4640
	ds_read_b128 v[62:65], v66 offset:4672
	s_waitcnt lgkmcnt(3)
	v_mfma_f32_32x32x16_bf16 v[2:17], v[0:3], v[4:7], 0
	v_lshlrev_b32_e32 v70, 2, v81
	v_cmp_le_i32_e32 vcc, v70, v35
	v_or_b32_e32 v74, 2, v70
	v_or_b32_e32 v75, 3, v70
	v_or_b32_e32 v88, v93, v35
	v_add_u32_e32 v76, 8, v70
	v_lshlrev_b64 v[0:1], 11, v[88:89]
	s_waitcnt lgkmcnt(1)
	v_mfma_f32_32x32x16_bf16 v[2:17], v[22:25], v[18:21], v[2:17]
	ds_read_b128 v[18:21], v66 offset:64
	ds_read_b128 v[22:25], v66 offset:4704
	ds_read_b128 v[66:69], v66 offset:96
	v_lshl_add_u64 v[0:1], s[2:3], 0, v[0:1]
	v_ashrrev_i32_e32 v71, 31, v70
	v_lshl_add_u64 v[0:1], v[0:1], 0, v[90:91]
	v_lshl_add_u64 v[84:85], v[70:71], 1, v[0:1]
	v_add_u32_e32 v0, 16, v70
	s_waitcnt lgkmcnt(2)
	v_mfma_f32_32x32x16_bf16 v[2:17], v[62:65], v[18:21], v[2:17]
	v_add_u32_e32 v18, 9, v70
	v_add_u32_e32 v19, 10, v70
	v_add_u32_e32 v20, 11, v70
	v_lshlrev_b32_e32 v138, 16, v42
	v_and_b32_e32 v139, 0xffff0000, v42
	v_lshlrev_b32_e32 v42, 16, v43
	v_and_b32_e32 v43, 0xffff0000, v43
	s_waitcnt lgkmcnt(0)
	v_mfma_f32_32x32x16_bf16 v[2:17], v[22:25], v[66:69], v[2:17]
	v_lshlrev_b32_e32 v140, 16, v36
	v_and_b32_e32 v141, 0xffff0000, v36
	v_lshlrev_b32_e32 v142, 16, v37
	v_and_b32_e32 v143, 0xffff0000, v37
	v_cvt_pk_bf16_f32 v130, v138, v139
	v_cvt_pk_bf16_f32 v131, v42, v43
	v_cvt_pk_bf16_f32 v132, v140, v141
	s_nop 4
	v_cndmask_b32_e32 v21, 0, v2, vcc
	v_cmp_lt_i32_e32 vcc, v70, v35
	v_cvt_pk_bf16_f32 v133, v142, v143
	v_add_u32_e32 v95, v92, v73
	v_cndmask_b32_e32 v22, 0, v3, vcc
	v_cmp_le_i32_e32 vcc, v74, v35
	v_lshlrev_b32_e32 v74, 3, v81
	v_add_u32_e32 v88, v72, v74
	v_cndmask_b32_e32 v4, 0, v4, vcc
	v_cmp_le_i32_e32 vcc, v75, v35
	v_mad_u32_u24 v144, v35, s16, v95
	v_cvt_pk_bf16_f32 v36, v44, v45
	v_cndmask_b32_e32 v5, 0, v5, vcc
	v_cmp_le_i32_e32 vcc, v76, v35
	v_cvt_pk_bf16_f32 v37, v46, v47
	v_lshlrev_b32_e32 v78, 16, v60
	v_cndmask_b32_e32 v6, 0, v6, vcc
	v_cmp_le_i32_e32 vcc, v18, v35
	v_cvt_pk_bf16_f32 v18, v21, v22
	v_and_b32_e32 v79, 0xffff0000, v60
	v_cndmask_b32_e32 v7, 0, v7, vcc
	v_cmp_le_i32_e32 vcc, v19, v35
	v_cvt_pk_bf16_f32 v19, v4, v5
	v_lshlrev_b32_e32 v82, 16, v61
	v_cndmask_b32_e32 v8, 0, v8, vcc
	v_cmp_le_i32_e32 vcc, v20, v35
	v_cvt_pk_bf16_f32 v20, v6, v7
	v_and_b32_e32 v83, 0xffff0000, v61
	v_cndmask_b32_e32 v9, 0, v9, vcc
	v_cmp_le_i32_e32 vcc, v0, v35
	v_add_u32_e32 v0, 17, v70
	v_cvt_pk_bf16_f32 v21, v8, v9
	v_cndmask_b32_e32 v23, 0, v10, vcc
	v_cmp_le_i32_e32 vcc, v0, v35
	v_add_u32_e32 v0, 18, v70
	v_add_u32_e32 v10, 26, v70
	v_cndmask_b32_e32 v24, 0, v11, vcc
	v_cmp_le_i32_e32 vcc, v0, v35
	v_add_u32_e32 v0, 19, v70
	v_cvt_pk_bf16_f32 v22, v23, v24
	v_cndmask_b32_e32 v25, 0, v12, vcc
	v_cmp_le_i32_e32 vcc, v0, v35
	v_add_u32_e32 v0, 24, v70
	v_lshlrev_b32_e32 v60, 16, v58
	v_cndmask_b32_e32 v68, 0, v13, vcc
	v_cmp_le_i32_e32 vcc, v0, v35
	v_add_u32_e32 v0, 25, v70
	v_add_u32_e32 v70, 27, v70
	v_cndmask_b32_e32 v69, 0, v14, vcc
	v_cmp_le_i32_e32 vcc, v0, v35
	v_mul_u32_u24_e32 v0, 0x50, v35
	v_add3_u32 v81, v92, v74, v0
	v_add_u32_e32 v11, 0x3800, v81
	ds_read2_b64 v[0:3], v11 offset1:2
	ds_read2_b64 v[64:67], v11 offset0:4 offset1:6
	v_cndmask_b32_e32 v71, 0, v15, vcc
	v_cmp_le_i32_e32 vcc, v10, v35
	s_waitcnt lgkmcnt(1)
	v_mfma_f32_32x32x16_bf16 v[0:15], v[0:3], v[18:21], 0
	v_cndmask_b32_e32 v16, 0, v16, vcc
	v_cmp_le_i32_e32 vcc, v70, v35
	v_cvt_pk_bf16_f32 v23, v25, v68
	v_cvt_pk_bf16_f32 v24, v69, v71
	v_cndmask_b32_e32 v17, 0, v17, vcc
	v_cvt_pk_bf16_f32 v25, v16, v17
	ds_read2_b64 v[106:109], v88 offset1:2
	ds_read2_b64 v[110:113], v88 offset0:4 offset1:6
	ds_read2_b64 v[114:117], v88 offset0:8 offset1:10
	ds_read2_b64 v[118:121], v88 offset0:12 offset1:14
	s_waitcnt lgkmcnt(4)
	v_mfma_f32_32x32x16_bf16 v[0:15], v[64:67], v[22:25], v[0:15]
	v_cvt_pk_bf16_f32 v35, v40, v41
	v_and_b32_e32 v61, 0xffff0000, v58
	v_lshlrev_b32_e32 v58, 16, v59
	v_and_b32_e32 v59, 0xffff0000, v59
	v_cvt_pk_bf16_f32 v122, v78, v79
	v_cvt_pk_bf16_f32 v123, v82, v83
	v_cvt_pk_bf16_f32 v124, v60, v61
	s_waitcnt lgkmcnt(3)
	v_mfma_f32_32x32x16_bf16 v[0:15], v[130:133], v[106:109], v[0:15]
	v_lshlrev_b32_e32 v106, 16, v34
	v_and_b32_e32 v107, 0xffff0000, v34
	v_cvt_pk_bf16_f32 v34, v106, v107
	v_cvt_pk_bf16_f32 v125, v58, v59
	v_lshlrev_b32_e32 v86, 16, v56
	v_and_b32_e32 v87, 0xffff0000, v56
	v_lshlrev_b32_e32 v56, 16, v57
	s_waitcnt lgkmcnt(2)
	v_mfma_f32_32x32x16_bf16 v[0:15], v[34:37], v[110:113], v[0:15]
	v_and_b32_e32 v57, 0xffff0000, v57
	v_lshlrev_b32_e32 v102, 16, v54
	v_and_b32_e32 v103, 0xffff0000, v54
	v_lshlrev_b32_e32 v104, 16, v55
	v_and_b32_e32 v105, 0xffff0000, v55
	v_cvt_pk_bf16_f32 v126, v86, v87
	v_cvt_pk_bf16_f32 v127, v56, v57
	s_waitcnt lgkmcnt(1)
	v_mfma_f32_32x32x16_bf16 v[0:15], v[122:125], v[114:117], v[0:15]
	v_cvt_pk_bf16_f32 v128, v102, v103
	v_cvt_pk_bf16_f32 v129, v104, v105
	s_mov_b64 s[2:3], 0x16f00600
	v_lshl_add_u64 v[62:63], v[84:85], 0, s[2:3]
	s_mov_b32 s2, 0x16f00000
	v_lshlrev_b32_e32 v16, 16, v26
	v_and_b32_e32 v17, 0xffff0000, v26
	s_waitcnt lgkmcnt(0)
	v_mfma_f32_32x32x16_bf16 v[0:15], v[126:129], v[118:121], v[0:15]
	v_lshlrev_b32_e32 v64, 16, v27
	v_and_b32_e32 v65, 0xffff0000, v27
	v_lshlrev_b32_e32 v66, 16, v28
	v_and_b32_e32 v67, 0xffff0000, v28
	v_lshlrev_b32_e32 v68, 16, v29
	v_and_b32_e32 v69, 0xffff0000, v29
	v_lshlrev_b32_e32 v70, 16, v30
	s_nop 4
	v_cvt_pk_bf16_f32 v0, v0, v1
	v_cvt_pk_bf16_f32 v1, v2, v3
	v_add_co_u32_e32 v2, vcc, s2, v84
	v_and_b32_e32 v71, 0xffff0000, v30
	s_nop 0
	v_addc_co_u32_e32 v3, vcc, 0, v85, vcc
	global_store_dwordx2 v[2:3], v[0:1], off offset:1536
	v_cvt_pk_bf16_f32 v0, v4, v5
	v_cvt_pk_bf16_f32 v1, v6, v7
	global_store_dwordx2 v[62:63], v[0:1], off offset:16
	v_cvt_pk_bf16_f32 v0, v8, v9
	v_cvt_pk_bf16_f32 v1, v10, v11
	v_lshlrev_b32_e32 v72, 16, v31
	v_and_b32_e32 v73, 0xffff0000, v31
	v_lshlrev_b32_e32 v74, 16, v32
	v_and_b32_e32 v75, 0xffff0000, v32
	v_lshlrev_b32_e32 v76, 16, v33
	v_and_b32_e32 v77, 0xffff0000, v33
	v_lshlrev_b32_e32 v54, 16, v52
	v_and_b32_e32 v55, 0xffff0000, v52
	v_lshlrev_b32_e32 v52, 16, v53
	v_and_b32_e32 v53, 0xffff0000, v53
	v_lshlrev_b32_e32 v130, 16, v50
	v_and_b32_e32 v131, 0xffff0000, v50
	v_lshlrev_b32_e32 v50, 16, v51
	v_and_b32_e32 v51, 0xffff0000, v51
	v_lshlrev_b32_e32 v132, 16, v48
	v_and_b32_e32 v133, 0xffff0000, v48
	v_lshlrev_b32_e32 v48, 16, v49
	v_and_b32_e32 v49, 0xffff0000, v49
	v_lshlrev_b32_e32 v114, 16, v38
	v_and_b32_e32 v115, 0xffff0000, v38
	v_lshlrev_b32_e32 v116, 16, v39
	v_and_b32_e32 v117, 0xffff0000, v39
	global_store_dwordx2 v[62:63], v[0:1], off offset:32
	v_cvt_pk_bf16_f32 v0, v12, v13
	v_cvt_pk_bf16_f32 v1, v14, v15
	v_cvt_pk_bf16_f32 v26, v16, v17
	v_cvt_pk_bf16_f32 v27, v64, v65
	v_cvt_pk_bf16_f32 v28, v66, v67
	v_cvt_pk_bf16_f32 v29, v68, v69
	v_cvt_pk_bf16_f32 v30, v70, v71
	v_cvt_pk_bf16_f32 v31, v72, v73
	v_cvt_pk_bf16_f32 v32, v74, v75
	v_cvt_pk_bf16_f32 v33, v76, v77
	v_cvt_pk_bf16_f32 v134, v54, v55
	v_cvt_pk_bf16_f32 v135, v52, v53
	v_cvt_pk_bf16_f32 v136, v130, v131
	v_cvt_pk_bf16_f32 v137, v50, v51
	v_cvt_pk_bf16_f32 v34, v132, v133
	v_cvt_pk_bf16_f32 v35, v48, v49
	v_cvt_pk_bf16_f32 v36, v114, v115
	v_cvt_pk_bf16_f32 v37, v116, v117
	global_store_dwordx2 v[62:63], v[0:1], off offset:48
	v_add_u32_e32 v38, 0x4000, v81
	ds_read2_b64 v[0:3], v38 offset0:64 offset1:66
	s_waitcnt lgkmcnt(0)
	v_mfma_f32_32x32x16_bf16 v[0:15], v[0:3], v[18:21], 0
	ds_read2_b64 v[18:21], v38 offset0:68 offset1:70
	s_waitcnt lgkmcnt(0)
	v_mfma_f32_32x32x16_bf16 v[0:15], v[18:21], v[22:25], v[0:15]
	ds_read2_b64 v[18:21], v88 offset1:2
	s_waitcnt lgkmcnt(0)
	v_mfma_f32_32x32x16_bf16 v[0:15], v[134:137], v[18:21], v[0:15]
	ds_read2_b64 v[18:21], v88 offset0:4 offset1:6
	s_waitcnt lgkmcnt(0)
	v_mfma_f32_32x32x16_bf16 v[0:15], v[34:37], v[18:21], v[0:15]
	ds_read2_b64 v[18:21], v88 offset0:8 offset1:10
	s_waitcnt lgkmcnt(0)
	v_mfma_f32_32x32x16_bf16 v[0:15], v[26:29], v[18:21], v[0:15]
	ds_read2_b64 v[18:21], v88 offset0:12 offset1:14
	s_waitcnt lgkmcnt(0)
	v_mfma_f32_32x32x16_bf16 v[0:15], v[30:33], v[18:21], v[0:15]
	s_nop 11
	v_cvt_pk_bf16_f32 v0, v0, v1
	v_cvt_pk_bf16_f32 v1, v2, v3
	v_cvt_pk_bf16_f32 v2, v4, v5
	v_cvt_pk_bf16_f32 v3, v6, v7
	v_cvt_pk_bf16_f32 v4, v8, v9
	v_cvt_pk_bf16_f32 v5, v10, v11
	v_cvt_pk_bf16_f32 v6, v12, v13
	v_cvt_pk_bf16_f32 v7, v14, v15
	global_store_dwordx2 v[62:63], v[0:1], off offset:64
	global_store_dwordx2 v[62:63], v[2:3], off offset:80
	global_store_dwordx2 v[62:63], v[4:5], off offset:96
	global_store_dwordx2 v[62:63], v[6:7], off offset:112
	ds_read_b128 v[0:3], v95 offset:19456
	ds_read_b128 v[4:7], v95 offset:19488
	ds_read_b128 v[8:11], v95 offset:19520
	ds_read_b128 v[12:15], v95 offset:19552
	ds_read_b128 v[18:21], v144 offset:9216
	s_waitcnt lgkmcnt(4)
	v_pk_mul_f32 v[34:35], v[2:3], v[42:43]
	ds_read_b128 v[22:25], v144 offset:14336
	s_waitcnt lgkmcnt(3)
	v_pk_mul_f32 v[42:43], v[10:11], v[40:41]
	v_pk_mul_f32 v[40:41], v[8:9], v[106:107]
	ds_read_b128 v[26:29], v144 offset:9248
	ds_read_b128 v[106:109], v144 offset:14368
	ds_read_b128 v[110:113], v144 offset:16896
	v_pk_mul_f32 v[32:33], v[0:1], v[138:139]
	v_pk_mul_f32 v[38:39], v[6:7], v[142:143]
	v_pk_mul_f32 v[36:37], v[4:5], v[140:141]
	s_waitcnt lgkmcnt(5)
	v_pk_mul_f32 v[46:47], v[14:15], v[46:47]
	v_pk_mul_f32 v[44:45], v[12:13], v[44:45]
	v_pk_mul_f32 v[0:1], v[0:1], v[54:55]
	v_pk_mul_f32 v[2:3], v[2:3], v[52:53]
	v_pk_mul_f32 v[4:5], v[4:5], v[130:131]
	v_pk_mul_f32 v[6:7], v[6:7], v[50:51]
	v_pk_mul_f32 v[8:9], v[8:9], v[132:133]
	v_pk_mul_f32 v[10:11], v[10:11], v[48:49]
	v_pk_mul_f32 v[12:13], v[12:13], v[114:115]
	v_pk_mul_f32 v[14:15], v[14:15], v[116:117]
	s_waitcnt lgkmcnt(3)
	v_mfma_f32_32x32x16_bf16 v[32:47], v[18:21], v[22:25], v[32:47]
	ds_read_b128 v[114:117], v144 offset:16928
	s_waitcnt lgkmcnt(1)
	v_mfma_f32_32x32x16_bf16 v[0:15], v[18:21], v[110:113], v[0:15]
	v_mfma_f32_32x32x16_bf16 v[32:47], v[26:29], v[106:109], v[32:47]
	s_waitcnt lgkmcnt(0)
	v_mfma_f32_32x32x16_bf16 v[0:15], v[26:29], v[114:117], v[0:15]
	ds_read_b128 v[18:21], v95 offset:19584
	ds_read_b128 v[26:29], v95 offset:19616
	ds_read_b128 v[118:121], v95 offset:19648
	ds_read_b128 v[122:125], v95 offset:19680
	ds_read_b128 v[126:129], v144 offset:11776
	s_waitcnt lgkmcnt(4)
	v_pk_mul_f32 v[50:51], v[20:21], v[82:83]
	v_pk_mul_f32 v[48:49], v[18:19], v[78:79]
	s_waitcnt lgkmcnt(3)
	v_pk_mul_f32 v[54:55], v[28:29], v[58:59]
	v_pk_mul_f32 v[52:53], v[26:27], v[60:61]
	s_waitcnt lgkmcnt(2)
	v_pk_mul_f32 v[58:59], v[120:121], v[56:57]
	v_pk_mul_f32 v[56:57], v[118:119], v[86:87]
	s_waitcnt lgkmcnt(1)
	v_pk_mul_f32 v[62:63], v[124:125], v[104:105]
	v_pk_mul_f32 v[60:61], v[122:123], v[102:103]
	ds_read_b128 v[82:85], v144 offset:11808
	v_pk_mul_f32 v[16:17], v[18:19], v[16:17]
	s_waitcnt lgkmcnt(1)
	v_mfma_f32_32x32x16_bf16 v[48:63], v[126:129], v[22:25], v[48:63]
	v_mul_f32_e64 v18, v20, v64
	v_mul_f32_e64 v19, v21, v65
	v_mul_f32_e64 v20, v26, v66
	v_mul_f32_e64 v21, v27, v67
	v_mul_f32_e64 v22, v28, v68
	v_mul_f32_e64 v23, v29, v69
	v_pk_mul_f32 v[24:25], v[118:119], v[70:71]
	v_pk_mul_f32 v[26:27], v[120:121], v[72:73]
	v_pk_mul_f32 v[28:29], v[122:123], v[74:75]
	v_pk_mul_f32 v[30:31], v[124:125], v[76:77]
	s_waitcnt lgkmcnt(0)
	s_waitcnt lgkmcnt(0)
	v_mfma_f32_32x32x16_bf16 v[48:63], v[82:85], v[106:109], v[48:63]
	v_mfma_f32_32x32x16_bf16 v[16:31], v[126:129], v[110:113], v[16:31]
	v_mfma_f32_32x32x16_bf16 v[16:31], v[82:85], v[114:117], v[16:31]
	v_mov_b32_e32 v82, v94
	s_mov_b64 s[16:17], s[44:45]
	v_or_b32_e32 v95, 32, v93
	v_and_b32_e32 v124, 31, v82
	v_ashrrev_i32_e32 v125, 5, v82
	v_mov_b64_e32 v[64:65], s[16:17]
	s_movk_i32 s2, 0x1200
	v_mad_i64_i32 v[64:65], s[2:3], v95, s2, v[64:65]
	v_ashrrev_i32_e32 v83, 31, v82
	v_lshl_add_u64 v[64:65], v[64:65], 0, v[90:91]
	v_lshl_add_u64 v[64:65], v[82:83], 1, v[64:65]
	v_lshl_add_u64 v[114:115], v[64:65], 0, s[0:1]
	global_load_ushort v88, v[114:115], off offset:2560
	global_load_ushort v81, v[114:115], off offset:3072
	v_add_co_u32_e32 v112, vcc, s7, v64
	s_mov_b32 s0, 0xb20f000
	s_nop 0
	v_addc_co_u32_e32 v113, vcc, 0, v65, vcc
	global_load_ushort v126, v[112:113], off offset:3584
	v_add_co_u32_e32 v110, vcc, s11, v64
	v_lshl_add_u32 v83, v82, 1, v92
	s_nop 0
	v_addc_co_u32_e32 v111, vcc, 0, v65, vcc
	v_add_co_u32_e32 v108, vcc, s12, v64
	s_waitcnt vmcnt(1)
	v_lshlrev_b32_e32 v81, 16, v81
	v_max_f32_e32 v81, v81, v81
	v_med3_f32 v81, v81, s9, v244
	v_mul_f32_e32 v81, 0xbfb8aa3b, v81
	v_exp_f32_e32 v81, v81
	v_addc_co_u32_e32 v109, vcc, 0, v65, vcc
	v_add_co_u32_e32 v106, vcc, s13, v64
	v_add_f32_e32 v116, 1.0, v81
	v_rcp_f32_e32 v116, v116
	v_addc_co_u32_e32 v107, vcc, 0, v65, vcc
	v_add_co_u32_e32 v104, vcc, s14, v64
	v_fma_f32 v117, v80, v116, v149
	v_max_f32_e32 v183, 0xda24260, v117
	v_mul_f32_e32 v81, v81, v116
	v_rcp_f32_e32 v116, v183
	v_mul_f32_e32 v81, v80, v81
	v_addc_co_u32_e32 v105, vcc, 0, v65, vcc
	v_mul_f32_e32 v81, v81, v116
	v_bfe_u32 v116, v81, 16, 1
	v_add3_u32 v133, v81, v116, s10
	global_load_ushort v81, v[114:115], off offset:2048
	global_load_ushort v127, v[110:111], off offset:512
	global_load_ushort v128, v[108:109], off offset:1536
	global_load_ushort v129, v[106:107], off offset:2560
	global_load_ushort v130, v[104:105], off offset:3584
	v_add_co_u32_e32 v102, vcc, s15, v64
	s_waitcnt vmcnt(4)
	v_lshlrev_b32_e32 v81, 16, v81
	v_addc_co_u32_e32 v103, vcc, 0, v65, vcc
	v_add_co_u32_e32 v86, vcc, s18, v64
	global_load_ushort v131, v[102:103], off offset:512
	s_nop 0
	v_addc_co_u32_e32 v87, vcc, 0, v65, vcc
	v_add_co_u32_e32 v74, vcc, s19, v64
	global_load_ushort v132, v[86:87], off offset:1536
	s_nop 0
	v_addc_co_u32_e32 v75, vcc, 0, v65, vcc
	v_add_co_u32_e32 v78, vcc, s21, v64
	global_load_ushort v134, v[74:75], off offset:2560
	s_nop 0
	v_addc_co_u32_e32 v79, vcc, 0, v65, vcc
	v_add_co_u32_e32 v76, vcc, s30, v64
	global_load_ushort v135, v[78:79], off offset:3584
	s_nop 0
	v_addc_co_u32_e32 v77, vcc, 0, v65, vcc
	v_add_co_u32_e32 v84, vcc, s31, v64
	v_mul_f32_e32 v81, v183, v81
	s_nop 0
	v_addc_co_u32_e32 v85, vcc, 0, v65, vcc
	v_add_co_u32_e32 v66, vcc, s34, v64
	global_load_ushort v137, v[84:85], off offset:1536
	global_load_ushort v136, v[76:77], off offset:512
	v_addc_co_u32_e32 v67, vcc, 0, v65, vcc
	v_add_co_u32_e32 v72, vcc, s35, v64
	global_load_ushort v138, v[66:67], off offset:2560
	s_nop 0
	v_addc_co_u32_e32 v73, vcc, 0, v65, vcc
	v_add_co_u32_e32 v68, vcc, s36, v64
	global_load_ushort v139, v[72:73], off offset:3584
	s_nop 0
	v_addc_co_u32_e32 v69, vcc, 0, v65, vcc
	v_add_co_u32_e32 v70, vcc, s37, v64
	global_load_ushort v140, v[68:69], off offset:512
	s_nop 0
	v_addc_co_u32_e32 v71, vcc, 0, v65, vcc
	v_add_co_u32_e32 v116, vcc, s40, v64
	global_load_ushort v141, v[70:71], off offset:1536
	s_nop 0
	v_addc_co_u32_e32 v117, vcc, 0, v65, vcc
	global_load_ushort v187, v[116:117], off offset:3584
	global_load_ushort v182, v[116:117], off offset:2560
	v_bfe_u32 v114, v81, 16, 1
	v_add3_u32 v188, v81, v114, s10
	v_add_co_u32_e32 v114, vcc, s41, v64
	s_nop 1
	v_addc_co_u32_e32 v115, vcc, 0, v65, vcc
	v_add_co_u32_e32 v118, vcc, s46, v64
	s_nop 1
	v_addc_co_u32_e32 v119, vcc, 0, v65, vcc
	global_load_ushort v180, v[118:119], off offset:-4096
	global_load_ushort v176, v[112:113], off offset:3072
	global_load_ushort v175, v[118:119], off offset:512
	global_load_ushort v170, v[114:115], off offset:3584
	global_load_ushort v181, v[110:111], off offset:1024
	global_load_ushort v178, v[110:111], off
	v_add_co_u32_e32 v120, vcc, s28, v64
	s_nop 1
	v_addc_co_u32_e32 v121, vcc, 0, v65, vcc
	v_add_co_u32_e32 v122, vcc, s29, v64
	global_load_ushort v186, v[120:121], off offset:1536
	global_load_ushort v185, v[120:121], off offset:512
	global_load_ushort v184, v[108:109], off offset:2048
	global_load_ushort v179, v[108:109], off offset:1024
	v_addc_co_u32_e32 v123, vcc, 0, v65, vcc
	v_add_co_u32_e32 v190, vcc, s42, v64
	global_load_ushort v177, v[122:123], off offset:2560
	global_load_ushort v173, v[122:123], off offset:1536
	global_load_ushort v174, v[106:107], off offset:3072
	global_load_ushort v172, v[106:107], off offset:2048
	v_addc_co_u32_e32 v191, vcc, 0, v65, vcc
	v_add_co_u32_e32 v106, vcc, s6, v64
	global_load_ushort v171, v[190:191], off offset:3584
	global_load_ushort v169, v[190:191], off offset:2560
	v_addc_co_u32_e32 v107, vcc, 0, v65, vcc
	v_add_co_u32_e32 v154, vcc, s49, v64
	s_waitcnt vmcnt(4)
	v_lshlrev_b32_e32 v173, 16, v173
	v_addc_co_u32_e32 v155, vcc, 0, v65, vcc
	v_add_co_u32_e32 v192, vcc, s0, v64
	s_mov_b32 s0, 0xb211000
	s_nop 0
	v_addc_co_u32_e32 v193, vcc, 0, v65, vcc
	v_add_co_u32_e32 v194, vcc, s0, v64
	s_mov_b32 s0, 0xb21a000
	s_nop 0
	v_addc_co_u32_e32 v195, vcc, 0, v65, vcc
	v_add_co_u32_e32 v108, vcc, s43, v64
	global_load_ushort v166, v[154:155], off offset:-4096
	global_load_ushort v164, v[104:105], off offset:3072
	global_load_ushort v167, v[154:155], off offset:512
	global_load_ushort v158, v[106:107], off offset:3584
	global_load_ushort v168, v[102:103], off offset:1024
	global_load_ushort v163, v[102:103], off
	v_addc_co_u32_e32 v109, vcc, 0, v65, vcc
	v_add_co_u32_e32 v110, vcc, s47, v64
	global_load_ushort v165, v[192:193], off offset:1536
	global_load_ushort v157, v[192:193], off offset:512
	global_load_ushort v162, v[86:87], off offset:2048
	global_load_ushort v156, v[86:87], off offset:1024
	v_addc_co_u32_e32 v111, vcc, 0, v65, vcc
	v_add_co_u32_e32 v112, vcc, s48, v64
	global_load_ushort v159, v[194:195], off offset:2560
	global_load_ushort v81, v[194:195], off offset:1536
	v_addc_co_u32_e32 v113, vcc, 0, v65, vcc
	v_add_co_u32_e32 v114, vcc, s0, v64
	s_mov_b32 s0, 0xb223000
	s_nop 0
	v_addc_co_u32_e32 v115, vcc, 0, v65, vcc
	v_add_co_u32_e32 v86, vcc, s0, v64
	s_mov_b32 s0, 0xb221000
	s_nop 0
	v_addc_co_u32_e32 v87, vcc, 0, v65, vcc
	v_add_co_u32_e32 v102, vcc, s0, v64
	s_mov_b32 s0, 0xb21f000
	s_nop 0
	v_addc_co_u32_e32 v103, vcc, 0, v65, vcc
	v_add_co_u32_e32 v104, vcc, s0, v64
	global_load_ushort v142, v[86:87], off offset:2048
	global_load_ushort v143, v[102:103], off offset:1024
	global_load_ushort v145, v[68:69], off offset:-4096
	v_addc_co_u32_e32 v105, vcc, 0, v65, vcc
	v_add_co_u32_e32 v106, vcc, s97, v64
	s_nop 1
	v_addc_co_u32_e32 v107, vcc, 0, v65, vcc
	global_load_ushort v146, v[106:107], off offset:3072
	global_load_ushort v147, v[114:115], off offset:2048
	global_load_ushort v150, v[112:113], off offset:1024
	global_load_ushort v151, v[76:77], off offset:-4096
	global_load_ushort v152, v[108:109], off offset:3072
	global_load_ushort v153, v[194:195], off offset:2048
	global_load_ushort v144, v[192:193], off offset:1024
	s_nop 0
	global_load_ushort v154, v[154:155], off
	s_nop 0
	global_load_ushort v155, v[190:191], off offset:3072
	s_nop 0
	global_load_ushort v122, v[122:123], off offset:2048
	s_nop 0
	global_load_ushort v120, v[120:121], off offset:1024
	s_nop 0
	global_load_ushort v118, v[118:119], off
	s_nop 0
	global_load_ushort v121, v[116:117], off offset:3072
	v_lshlrev_b32_e32 v116, 16, v187
	v_max_f32_e32 v116, v116, v116
	v_med3_f32 v116, v116, s9, v244
	v_mul_f32_e32 v116, 0xbfb8aa3b, v116
	v_exp_f32_e32 v116, v116
	ds_write_b16_d16_hi v83, v188
	ds_write_b16_d16_hi v83, v133 offset:4608
	v_add_f32_e32 v117, 1.0, v116
	v_rcp_f32_e32 v117, v117
	s_nop 0
	v_fma_f32 v119, v80, v117, v149
	v_mul_f32_e32 v116, v116, v117
	v_mul_f32_e32 v117, v183, v119
	v_max_f32_e32 v117, 0xda24260, v117
	v_rcp_f32_e32 v119, v117
	v_mul_f32_e32 v116, v80, v116
	v_mul_f32_e32 v116, v116, v119
	v_bfe_u32 v119, v116, 16, 1
	v_add3_u32 v119, v116, v119, s10
	v_lshlrev_b32_e32 v116, 16, v182
	v_mul_f32_e32 v116, v117, v116
	v_bfe_u32 v123, v116, 16, 1
	v_add3_u32 v116, v116, v123, s10
	ds_write_b16_d16_hi v83, v116 offset:144
	ds_write_b16_d16_hi v83, v119 offset:4752
	v_lshlrev_b32_e32 v116, 16, v180
	v_max_f32_e32 v116, v116, v116
	v_med3_f32 v116, v116, s9, v244
	v_mul_f32_e32 v116, 0xbfb8aa3b, v116
	v_exp_f32_e32 v116, v116
	s_nop 0
	v_add_f32_e32 v123, 1.0, v116
	v_rcp_f32_e32 v123, v123
	s_nop 0
	v_fma_f32 v180, v80, v123, v149
	v_mul_f32_e32 v117, v117, v180
	v_max_f32_e32 v117, 0xda24260, v117
	v_mul_f32_e32 v116, v116, v123
	v_rcp_f32_e32 v123, v117
	v_mul_f32_e32 v116, v80, v116
	v_mul_f32_e32 v116, v116, v123
	v_bfe_u32 v123, v116, 16, 1
	v_add3_u32 v116, v116, v123, s10
	v_lshlrev_b32_e32 v123, 16, v176
	v_mul_f32_e32 v123, v117, v123
	v_bfe_u32 v176, v123, 16, 1
	v_add3_u32 v123, v123, v176, s10
	ds_write_b16_d16_hi v83, v123 offset:288
	ds_write_b16_d16_hi v83, v116 offset:4896
	v_lshlrev_b32_e32 v123, 16, v175
	v_max_f32_e32 v123, v123, v123
	v_med3_f32 v123, v123, s9, v244
	v_mul_f32_e32 v123, 0xbfb8aa3b, v123
	v_exp_f32_e32 v123, v123
	s_nop 0
	v_add_f32_e32 v175, 1.0, v123
	v_rcp_f32_e32 v175, v175
	s_nop 0
	v_fma_f32 v176, v80, v175, v149
	v_mul_f32_e32 v117, v117, v176
	v_mul_f32_e32 v123, v123, v175
	v_max_f32_e32 v175, 0xda24260, v117
	v_rcp_f32_e32 v117, v175
	v_mul_f32_e32 v123, v80, v123
	v_mul_f32_e32 v117, v123, v117
	v_bfe_u32 v123, v117, 16, 1
	v_add3_u32 v117, v117, v123, s10
	v_lshlrev_b32_e32 v123, 16, v170
	v_mul_f32_e32 v123, v175, v123
	v_bfe_u32 v170, v123, 16, 1
	v_add3_u32 v123, v123, v170, s10
	ds_write_b16_d16_hi v83, v123 offset:432
	ds_write_b16_d16_hi v83, v117 offset:5040
	v_lshlrev_b32_e32 v123, 16, v181
	v_max_f32_e32 v123, v123, v123
	v_med3_f32 v123, v123, s9, v244
	v_mul_f32_e32 v123, 0xbfb8aa3b, v123
	v_exp_f32_e32 v123, v123
	s_nop 0
	v_add_f32_e32 v170, 1.0, v123
	v_rcp_f32_e32 v170, v170
	s_nop 0
	v_fma_f32 v176, v80, v170, v149
	v_mul_f32_e32 v123, v123, v170
	v_mul_f32_e32 v170, v175, v176
	v_max_f32_e32 v170, 0xda24260, v170
	v_rcp_f32_e32 v175, v170
	v_mul_f32_e32 v123, v80, v123
	v_mul_f32_e32 v123, v123, v175
	v_bfe_u32 v175, v123, 16, 1
	v_add3_u32 v123, v123, v175, s10
	v_lshlrev_b32_e32 v175, 16, v178
	v_mul_f32_e32 v175, v170, v175
	v_bfe_u32 v176, v175, 16, 1
	v_add3_u32 v175, v175, v176, s10
	ds_write_b16_d16_hi v83, v175 offset:576
	ds_write_b16_d16_hi v83, v123 offset:5184
	v_lshlrev_b32_e32 v175, 16, v186
	v_max_f32_e32 v175, v175, v175
	v_med3_f32 v175, v175, s9, v244
	v_mul_f32_e32 v175, 0xbfb8aa3b, v175
	v_exp_f32_e32 v175, v175
	s_nop 0
	v_add_f32_e32 v176, 1.0, v175
	v_rcp_f32_e32 v176, v176
	s_nop 0
	v_fma_f32 v178, v80, v176, v149
	v_mul_f32_e32 v170, v170, v178
	v_max_f32_e32 v170, 0xda24260, v170
	v_mul_f32_e32 v175, v175, v176
	v_rcp_f32_e32 v176, v170
	v_mul_f32_e32 v175, v80, v175
	v_mul_f32_e32 v175, v175, v176
	v_bfe_u32 v176, v175, 16, 1
	v_add3_u32 v175, v175, v176, s10
	v_lshlrev_b32_e32 v176, 16, v185
	v_mul_f32_e32 v176, v170, v176
	v_bfe_u32 v178, v176, 16, 1
	v_add3_u32 v176, v176, v178, s10
	ds_write_b16_d16_hi v83, v176 offset:720
	ds_write_b16_d16_hi v83, v175 offset:5328
	v_lshlrev_b32_e32 v176, 16, v184
	v_max_f32_e32 v176, v176, v176
	v_med3_f32 v176, v176, s9, v244
	v_mul_f32_e32 v176, 0xbfb8aa3b, v176
	v_exp_f32_e32 v176, v176
	s_nop 0
	v_add_f32_e32 v178, 1.0, v176
	v_rcp_f32_e32 v178, v178
	s_nop 0
	v_fma_f32 v180, v80, v178, v149
	v_mul_f32_e32 v170, v170, v180
	v_mul_f32_e32 v176, v176, v178
	v_max_f32_e32 v178, 0xda24260, v170
	v_rcp_f32_e32 v170, v178
	v_mul_f32_e32 v176, v80, v176
	v_mul_f32_e32 v170, v176, v170
	v_bfe_u32 v176, v170, 16, 1
	v_add3_u32 v170, v170, v176, s10
	v_lshlrev_b32_e32 v176, 16, v179
	v_mul_f32_e32 v176, v178, v176
	v_bfe_u32 v179, v176, 16, 1
	v_add3_u32 v176, v176, v179, s10
	ds_write_b16_d16_hi v83, v176 offset:864
	ds_write_b16_d16_hi v83, v170 offset:5472
	v_lshlrev_b32_e32 v176, 16, v177
	v_max_f32_e32 v176, v176, v176
	v_med3_f32 v176, v176, s9, v244
	v_mul_f32_e32 v176, 0xbfb8aa3b, v176
	v_exp_f32_e32 v176, v176
	s_nop 0
	v_add_f32_e32 v177, 1.0, v176
	v_rcp_f32_e32 v177, v177
	s_nop 0
	v_fma_f32 v179, v80, v177, v149
	v_mul_f32_e32 v176, v176, v177
	v_mul_f32_e32 v177, v178, v179
	v_max_f32_e32 v177, 0xda24260, v177
	v_rcp_f32_e32 v178, v177
	v_mul_f32_e32 v176, v80, v176
	v_mul_f32_e32 v173, v177, v173
	v_mul_f32_e32 v176, v176, v178
	v_bfe_u32 v178, v176, 16, 1
	v_add3_u32 v176, v176, v178, s10
	v_bfe_u32 v178, v173, 16, 1
	v_add3_u32 v173, v173, v178, s10
	ds_write_b16_d16_hi v83, v173 offset:1008
	ds_write_b16_d16_hi v83, v176 offset:5616
	s_waitcnt vmcnt(31)
	v_lshlrev_b32_e32 v173, 16, v174
	v_max_f32_e32 v173, v173, v173
	v_med3_f32 v173, v173, s9, v244
	v_mul_f32_e32 v173, 0xbfb8aa3b, v173
	v_exp_f32_e32 v173, v173
	s_waitcnt vmcnt(29)
	v_lshlrev_b32_e32 v171, 16, v171
	v_max_f32_e32 v171, v171, v171
	v_med3_f32 v171, v171, s9, v244
	v_add_f32_e32 v174, 1.0, v173
	v_rcp_f32_e32 v174, v174
	v_mul_f32_e32 v171, 0xbfb8aa3b, v171
	v_exp_f32_e32 v178, v171
	v_lshlrev_b32_e32 v172, 16, v172
	v_fma_f32 v171, v80, v174, v149
	v_mul_f32_e32 v171, v177, v171
	v_max_f32_e32 v177, 0xda24260, v171
	v_rcp_f32_e32 v171, v177
	v_mul_f32_e32 v173, v173, v174
	v_mul_f32_e32 v173, v80, v173
	v_mul_f32_e32 v172, v177, v172
	v_mul_f32_e32 v171, v173, v171
	v_bfe_u32 v173, v171, 16, 1
	v_add3_u32 v171, v171, v173, s10
	v_add_f32_e32 v173, 1.0, v178
	v_rcp_f32_e32 v173, v173
	v_bfe_u32 v174, v172, 16, 1
	v_add3_u32 v172, v172, v174, s10
	ds_write_b16_d16_hi v83, v172 offset:1152
	v_fma_f32 v172, v80, v173, v149
	v_mul_f32_e32 v172, v177, v172
	v_max_f32_e32 v174, 0xda24260, v172
	v_rcp_f32_e32 v172, v174
	v_mul_f32_e32 v173, v178, v173
	v_mul_f32_e32 v173, v80, v173
	s_waitcnt vmcnt(28)
	v_lshlrev_b32_e32 v169, 16, v169
	v_mul_f32_e32 v172, v173, v172
	v_bfe_u32 v173, v172, 16, 1
	v_mul_f32_e32 v169, v174, v169
	ds_write_b16_d16_hi v83, v171 offset:5760
	v_add3_u32 v172, v172, v173, s10
	v_bfe_u32 v173, v169, 16, 1
	v_add3_u32 v169, v169, v173, s10
	global_load_ushort v173, v[74:75], off offset:3072
	global_load_ushort v177, v[108:109], off offset:2560
	s_nop 0
	global_load_ushort v78, v[78:79], off offset:3072
	s_nop 0
	global_load_ushort v79, v[76:77], off offset:1024
	global_load_ushort v178, v[84:85], off offset:2048
	s_nop 0
	global_load_ushort v85, v[84:85], off offset:1024
	s_nop 0
	global_load_ushort v76, v[76:77], off
	s_nop 0
	global_load_ushort v77, v[74:75], off offset:2048
	s_waitcnt vmcnt(35)
	v_lshlrev_b32_e32 v74, 16, v166
	v_max_f32_e32 v74, v74, v74
	v_med3_f32 v74, v74, s9, v244
	v_mul_f32_e32 v74, 0xbfb8aa3b, v74
	v_exp_f32_e32 v84, v74
	v_add_co_u32_e32 v74, vcc, s5, v64
	s_waitcnt vmcnt(32)
	v_lshlrev_b32_e32 v158, 16, v158
	v_addc_co_u32_e32 v75, vcc, 0, v65, vcc
	v_add_f32_e32 v166, 1.0, v84
	global_load_ushort v108, v[108:109], off offset:3584
	s_nop 0
	global_load_ushort v109, v[74:75], off
	s_nop 0
	global_load_ushort v110, v[110:111], off offset:512
	s_nop 0
	global_load_ushort v74, v[74:75], off offset:3584
	s_nop 0
	global_load_ushort v75, v[112:113], off offset:1536
	global_load_ushort v111, v[114:115], off offset:2560
	s_nop 0
	global_load_ushort v114, v[114:115], off offset:1536
	s_nop 0
	global_load_ushort v112, v[112:113], off offset:512
	v_rcp_f32_e32 v166, v166
	s_waitcnt vmcnt(37)
	v_lshlrev_b32_e32 v165, 16, v165
	v_max_f32_e32 v165, v165, v165
	v_med3_f32 v165, v165, s9, v244
	v_fma_f32 v113, v80, v166, v149
	v_mul_f32_e32 v113, v174, v113
	v_mul_f32_e32 v84, v84, v166
	v_lshlrev_b32_e32 v166, 16, v167
	v_max_f32_e32 v113, 0xda24260, v113
	v_max_f32_e32 v166, v166, v166
	v_rcp_f32_e32 v115, v113
	v_med3_f32 v166, v166, s9, v244
	v_mul_f32_e32 v166, 0xbfb8aa3b, v166
	v_exp_f32_e32 v166, v166
	v_mul_f32_e32 v84, v80, v84
	v_mul_f32_e32 v84, v84, v115
	v_bfe_u32 v115, v84, 16, 1
	v_add3_u32 v84, v84, v115, s10
	v_lshlrev_b32_e32 v115, 16, v164
	v_add_f32_e32 v164, 1.0, v166
	v_rcp_f32_e32 v164, v164
	v_mul_f32_e32 v115, v113, v115
	v_bfe_u32 v167, v115, 16, 1
	v_add3_u32 v115, v115, v167, s10
	ds_write_b16_d16_hi v83, v115 offset:1440
	v_fma_f32 v115, v80, v164, v149
	v_mul_f32_e32 v113, v113, v115
	v_mul_f32_e32 v164, v166, v164
	v_lshlrev_b32_e32 v166, 16, v168
	v_max_f32_e32 v113, 0xda24260, v113
	v_max_f32_e32 v166, v166, v166
	v_rcp_f32_e32 v115, v113
	v_med3_f32 v166, v166, s9, v244
	v_mul_f32_e32 v166, 0xbfb8aa3b, v166
	v_exp_f32_e32 v166, v166
	v_mul_f32_e32 v164, v80, v164
	v_mul_f32_e32 v115, v164, v115
	v_bfe_u32 v164, v115, 16, 1
	v_add3_u32 v115, v115, v164, s10
	v_add_f32_e32 v164, 1.0, v166
	v_rcp_f32_e32 v164, v164
	v_mul_f32_e32 v158, v113, v158
	v_bfe_u32 v167, v158, 16, 1
	v_add3_u32 v158, v158, v167, s10
	ds_write_b16_d16_hi v83, v158 offset:1584
	v_fma_f32 v158, v80, v164, v149
	v_mul_f32_e32 v113, v113, v158
	v_max_f32_e32 v113, 0xda24260, v113
	v_rcp_f32_e32 v158, v113
	v_mul_f32_e32 v165, 0xbfb8aa3b, v165
	v_mul_f32_e32 v164, v166, v164
	v_exp_f32_e32 v165, v165
	v_mul_f32_e32 v164, v80, v164
	v_mul_f32_e32 v158, v164, v158
	v_bfe_u32 v164, v158, 16, 1
	v_add3_u32 v158, v158, v164, s10
	v_add_f32_e32 v164, 1.0, v165
	v_lshlrev_b32_e32 v163, 16, v163
	v_rcp_f32_e32 v164, v164
	v_mul_f32_e32 v163, v113, v163
	v_bfe_u32 v166, v163, 16, 1
	v_add3_u32 v163, v163, v166, s10
	ds_write_b16_d16_hi v83, v163 offset:1728
	v_fma_f32 v163, v80, v164, v149
	v_mul_f32_e32 v113, v113, v163
	s_waitcnt vmcnt(35)
	v_lshlrev_b32_e32 v162, 16, v162
	v_max_f32_e32 v113, 0xda24260, v113
	v_max_f32_e32 v162, v162, v162
	v_rcp_f32_e32 v163, v113
	v_med3_f32 v162, v162, s9, v244
	v_mul_f32_e32 v162, 0xbfb8aa3b, v162
	v_mul_f32_e32 v164, v165, v164
	v_exp_f32_e32 v162, v162
	v_mul_f32_e32 v164, v80, v164
	v_mul_f32_e32 v163, v164, v163
	v_bfe_u32 v164, v163, 16, 1
	v_add3_u32 v163, v163, v164, s10
	v_add_f32_e32 v164, 1.0, v162
	v_lshlrev_b32_e32 v157, 16, v157
	v_rcp_f32_e32 v164, v164
	v_mul_f32_e32 v157, v113, v157
	v_bfe_u32 v165, v157, 16, 1
	v_add3_u32 v157, v157, v165, s10
	ds_write_b16_d16_hi v83, v157 offset:1872
	v_fma_f32 v157, v80, v164, v149
	v_mul_f32_e32 v113, v113, v157
	s_waitcnt vmcnt(33)
	v_lshlrev_b32_e32 v159, 16, v159
	v_max_f32_e32 v113, 0xda24260, v113
	v_max_f32_e32 v159, v159, v159
	v_rcp_f32_e32 v157, v113
	v_med3_f32 v159, v159, s9, v244
	v_mul_f32_e32 v159, 0xbfb8aa3b, v159
	v_mul_f32_e32 v162, v162, v164
	v_exp_f32_e32 v159, v159
	v_mul_f32_e32 v162, v80, v162
	v_mul_f32_e32 v157, v162, v157
	v_bfe_u32 v162, v157, 16, 1
	v_add3_u32 v157, v157, v162, s10
	v_add_f32_e32 v162, 1.0, v159
	v_lshlrev_b32_e32 v156, 16, v156
	v_rcp_f32_e32 v162, v162
	v_mul_f32_e32 v156, v113, v156
	v_bfe_u32 v164, v156, 16, 1
	v_add3_u32 v156, v156, v164, s10
	ds_write_b16_d16_hi v83, v156 offset:2016
	v_fma_f32 v156, v80, v162, v149
	v_mul_f32_e32 v113, v113, v156
	v_max_f32_e32 v113, 0xda24260, v113
	v_rcp_f32_e32 v156, v113
	v_mul_f32_e32 v159, v159, v162
	v_mul_f32_e32 v159, v80, v159
	s_waitcnt vmcnt(32)
	v_lshlrev_b32_e32 v81, 16, v81
	v_mul_f32_e32 v156, v159, v156
	v_bfe_u32 v159, v156, 16, 1
	v_mul_f32_e32 v81, v113, v81
	v_add3_u32 v159, v156, v159, s10
	v_bfe_u32 v156, v81, 16, 1
	v_add3_u32 v81, v81, v156, s10
	ds_write_b16_d16_hi v83, v169 offset:1296
	ds_write_b16_d16_hi v83, v172 offset:5904
	ds_write_b16_d16_hi v83, v84 offset:6048
	ds_write_b16_d16_hi v83, v115 offset:6192
	ds_write_b16_d16_hi v83, v158 offset:6336
	ds_write_b16_d16_hi v83, v163 offset:6480
	ds_write_b16_d16_hi v83, v157 offset:6624
	ds_write_b16_d16_hi v83, v81 offset:2160
	ds_write_b16_d16_hi v83, v159 offset:6768
	s_waitcnt vmcnt(15)
	v_lshlrev_b32_e32 v81, 16, v173
	v_max_f32_e32 v81, v81, v81
	v_med3_f32 v81, v81, s9, v244
	v_mul_f32_e32 v81, 0xbfb8aa3b, v81
	v_exp_f32_e32 v81, v81
	s_waitcnt vmcnt(7)
	v_lshlrev_b32_e32 v108, 16, v108
	v_max_f32_e32 v108, v108, v108
	v_med3_f32 v108, v108, s9, v244
	v_add_f32_e32 v156, 1.0, v81
	v_rcp_f32_e32 v156, v156
	v_mul_f32_e32 v108, 0xbfb8aa3b, v108
	v_exp_f32_e32 v108, v108
	v_lshlrev_b32_e32 v77, 16, v77
	v_fma_f32 v162, v80, v156, v149
	v_mul_f32_e32 v113, v113, v162
	v_max_f32_e32 v113, 0xda24260, v113
	v_rcp_f32_e32 v162, v113
	v_mul_f32_e32 v81, v81, v156
	v_mul_f32_e32 v81, v80, v81
	v_mul_f32_e32 v77, v113, v77
	v_mul_f32_e32 v81, v81, v162
	v_bfe_u32 v156, v81, 16, 1
	v_add3_u32 v156, v81, v156, s10
	v_add_f32_e32 v81, 1.0, v108
	v_rcp_f32_e32 v81, v81
	v_bfe_u32 v162, v77, 16, 1
	v_add3_u32 v77, v77, v162, s10
	ds_write_b16_d16_hi v83, v77 offset:2304
	v_fma_f32 v77, v80, v81, v149
	ds_write_b16_d16_hi v83, v156 offset:6912
	v_mul_f32_e32 v77, v113, v77
	global_load_ushort v162, v[66:67], off offset:3072
	global_load_ushort v164, v[72:73], off offset:3072
	global_load_ushort v165, v[68:69], off offset:1024
	global_load_ushort v166, v[70:71], off offset:2048
	global_load_ushort v167, v[86:87], off offset:1536
	global_load_ushort v168, v[70:71], off offset:1024
	global_load_ushort v169, v[68:69], off
	global_load_ushort v173, v[66:67], off offset:2048
	s_waitcnt vmcnt(14)
	v_lshlrev_b32_e32 v66, 16, v109
	v_max_f32_e32 v77, 0xda24260, v77
	v_max_f32_e32 v66, v66, v66
	v_rcp_f32_e32 v113, v77
	v_med3_f32 v66, v66, s9, v244
	v_mul_f32_e32 v66, 0xbfb8aa3b, v66
	v_mul_f32_e32 v81, v108, v81
	v_exp_f32_e32 v66, v66
	v_mul_f32_e32 v81, v80, v81
	v_mul_f32_e32 v81, v81, v113
	v_bfe_u32 v108, v81, 16, 1
	v_add_co_u32_e32 v64, vcc, s4, v64
	v_add3_u32 v108, v81, v108, s10
	v_lshlrev_b32_e32 v81, 16, v177
	v_addc_co_u32_e32 v65, vcc, 0, v65, vcc
	v_add_f32_e32 v67, 1.0, v66
	global_load_ushort v174, v[106:107], off offset:3584
	global_load_ushort v177, v[64:65], off
	global_load_ushort v179, v[64:65], off offset:3584
	s_nop 0
	global_load_ushort v106, v[106:107], off offset:2560
	s_nop 0
	global_load_ushort v104, v[104:105], off offset:512
	s_nop 0
	global_load_ushort v180, v[102:103], off offset:1536
	s_nop 0
	global_load_ushort v102, v[102:103], off offset:512
	s_nop 0
	global_load_ushort v86, v[86:87], off offset:2560
	v_rcp_f32_e32 v67, v67
	v_mul_f32_e32 v81, v77, v81
	v_bfe_u32 v113, v81, 16, 1
	v_add3_u32 v81, v81, v113, s10
	v_fma_f32 v64, v80, v67, v149
	v_mul_f32_e32 v64, v77, v64
	v_mul_f32_e32 v66, v66, v67
	s_waitcnt vmcnt(21)
	v_lshlrev_b32_e32 v67, 16, v110
	v_max_f32_e32 v64, 0xda24260, v64
	v_max_f32_e32 v67, v67, v67
	v_rcp_f32_e32 v65, v64
	v_med3_f32 v67, v67, s9, v244
	v_mul_f32_e32 v67, 0xbfb8aa3b, v67
	v_exp_f32_e32 v67, v67
	v_mul_f32_e32 v66, v80, v66
	v_mul_f32_e32 v65, v66, v65
	v_bfe_u32 v66, v65, 16, 1
	v_add3_u32 v181, v65, v66, s10
	v_add_f32_e32 v66, 1.0, v67
	v_lshlrev_b32_e32 v65, 16, v78
	v_rcp_f32_e32 v66, v66
	v_mul_f32_e32 v65, v64, v65
	v_bfe_u32 v68, v65, 16, 1
	v_add3_u32 v65, v65, v68, s10
	ds_write_b16_d16_hi v83, v65 offset:2592
	v_fma_f32 v65, v80, v66, v149
	v_mul_f32_e32 v66, v67, v66
	v_lshlrev_b32_e32 v67, 16, v79
	v_mul_f32_e32 v64, v64, v65
	v_max_f32_e32 v67, v67, v67
	v_max_f32_e32 v64, 0xda24260, v64
	v_med3_f32 v67, v67, s9, v244
	v_rcp_f32_e32 v65, v64
	v_mul_f32_e32 v67, 0xbfb8aa3b, v67
	v_exp_f32_e32 v67, v67
	v_mul_f32_e32 v66, v80, v66
	v_mul_f32_e32 v65, v66, v65
	v_bfe_u32 v66, v65, 16, 1
	v_add_f32_e32 v68, 1.0, v67
	v_add3_u32 v65, v65, v66, s10
	s_waitcnt vmcnt(20)
	v_lshlrev_b32_e32 v66, 16, v74
	v_rcp_f32_e32 v68, v68
	v_mul_f32_e32 v66, v64, v66
	v_bfe_u32 v69, v66, 16, 1
	v_add3_u32 v66, v66, v69, s10
	ds_write_b16_d16_hi v83, v66 offset:2736
	v_fma_f32 v66, v80, v68, v149
	v_mul_f32_e32 v64, v64, v66
	v_mul_f32_e32 v67, v67, v68
	s_waitcnt vmcnt(19)
	v_lshlrev_b32_e32 v68, 16, v75
	v_max_f32_e32 v64, 0xda24260, v64
	v_max_f32_e32 v68, v68, v68
	v_rcp_f32_e32 v66, v64
	v_med3_f32 v68, v68, s9, v244
	v_mul_f32_e32 v68, 0xbfb8aa3b, v68
	v_exp_f32_e32 v68, v68
	v_mul_f32_e32 v67, v80, v67
	v_mul_f32_e32 v66, v67, v66
	v_bfe_u32 v67, v66, 16, 1
	v_add3_u32 v182, v66, v67, s10
	v_add_f32_e32 v67, 1.0, v68
	v_lshlrev_b32_e32 v66, 16, v76
	v_rcp_f32_e32 v67, v67
	v_mul_f32_e32 v66, v64, v66
	v_bfe_u32 v69, v66, 16, 1
	v_add3_u32 v66, v66, v69, s10
	ds_write_b16_d16_hi v83, v66 offset:2880
	v_fma_f32 v66, v80, v67, v149
	v_mul_f32_e32 v67, v68, v67
	v_lshlrev_b32_e32 v68, 16, v178
	v_mul_f32_e32 v64, v64, v66
	v_max_f32_e32 v68, v68, v68
	v_max_f32_e32 v64, 0xda24260, v64
	v_med3_f32 v68, v68, s9, v244
	v_rcp_f32_e32 v66, v64
	v_mul_f32_e32 v68, 0xbfb8aa3b, v68
	v_exp_f32_e32 v68, v68
	v_mul_f32_e32 v67, v80, v67
	v_mul_f32_e32 v66, v67, v66
	v_bfe_u32 v67, v66, 16, 1
	v_add_f32_e32 v69, 1.0, v68
	v_add3_u32 v66, v66, v67, s10
	s_waitcnt vmcnt(16)
	v_lshlrev_b32_e32 v67, 16, v112
	v_rcp_f32_e32 v69, v69
	v_mul_f32_e32 v67, v64, v67
	v_bfe_u32 v70, v67, 16, 1
	v_add3_u32 v67, v67, v70, s10
	ds_write_b16_d16_hi v83, v67 offset:3024
	v_fma_f32 v67, v80, v69, v149
	v_mul_f32_e32 v64, v64, v67
	v_mul_f32_e32 v68, v68, v69
	v_lshlrev_b32_e32 v69, 16, v111
	v_max_f32_e32 v64, 0xda24260, v64
	v_max_f32_e32 v69, v69, v69
	v_rcp_f32_e32 v67, v64
	v_med3_f32 v69, v69, s9, v244
	v_mul_f32_e32 v69, 0xbfb8aa3b, v69
	v_exp_f32_e32 v69, v69
	v_mul_f32_e32 v68, v80, v68
	v_mul_f32_e32 v67, v68, v67
	v_bfe_u32 v68, v67, 16, 1
	v_add3_u32 v178, v67, v68, s10
	v_add_f32_e32 v68, 1.0, v69
	v_lshlrev_b32_e32 v67, 16, v85
	v_rcp_f32_e32 v68, v68
	v_mul_f32_e32 v67, v64, v67
	v_bfe_u32 v70, v67, 16, 1
	v_add3_u32 v67, v67, v70, s10
	ds_write_b16_d16_hi v83, v67 offset:3168
	v_fma_f32 v67, v80, v68, v149
	v_mul_f32_e32 v64, v64, v67
	v_max_f32_e32 v76, 0xda24260, v64
	v_rcp_f32_e32 v64, v76
	v_mul_f32_e32 v67, v69, v68
	v_mul_f32_e32 v67, v80, v67
	ds_write_b16_d16_hi v83, v81 offset:2448
	v_mul_f32_e32 v64, v67, v64
	v_bfe_u32 v67, v64, 16, 1
	v_add3_u32 v64, v64, v67, s10
	v_lshlrev_b32_e32 v67, 16, v114
	v_mul_f32_e32 v67, v76, v67
	v_bfe_u32 v68, v67, 16, 1
	v_add3_u32 v67, v67, v68, s10
	ds_write_b16_d16_hi v83, v108 offset:7056
	ds_write_b16_d16_hi v83, v181 offset:7200
	ds_write_b16_d16_hi v83, v65 offset:7344
	ds_write_b16_d16_hi v83, v182 offset:7488
	ds_write_b16_d16_hi v83, v66 offset:7632
	ds_write_b16_d16_hi v83, v178 offset:7776
	ds_write_b16_d16_hi v83, v67 offset:3312
	ds_write_b16_d16_hi v83, v64 offset:7920
	s_waitcnt vmcnt(15)
	v_lshlrev_b32_e32 v72, 16, v162
	v_max_f32_e32 v72, v72, v72
	v_med3_f32 v72, v72, s9, v244
	v_mul_f32_e32 v72, 0xbfb8aa3b, v72
	v_and_b32_e32 v103, 0xffff0000, v108
	v_exp_f32_e32 v108, v72
	v_lshl_or_b32 v78, v120, 16, v127
	s_waitcnt vmcnt(4)
	v_lshlrev_b32_e32 v106, 16, v106
	s_waitcnt vmcnt(3)
	v_lshlrev_b32_e32 v104, 16, v104
	v_add_f32_e32 v77, 1.0, v108
	v_rcp_f32_e32 v110, v77
	v_max_f32_e32 v104, v104, v104
	v_med3_f32 v104, v104, s9, v244
	v_mul_f32_e32 v104, 0xbfb8aa3b, v104
	v_fma_f32 v112, v80, v110, v149
	v_mul_f32_e32 v76, v76, v112
	v_max_f32_e32 v112, 0xda24260, v76
	v_lshl_or_b32 v76, v121, 16, v88
	v_mul_f32_e32 v88, v108, v110
	v_lshlrev_b32_e32 v110, 16, v174
	v_max_f32_e32 v110, v110, v110
	v_rcp_f32_e32 v114, v112
	v_med3_f32 v110, v110, s9, v244
	v_mul_f32_e32 v110, 0xbfb8aa3b, v110
	v_exp_f32_e32 v110, v110
	v_mul_f32_e32 v88, v80, v88
	v_mul_f32_e32 v88, v88, v114
	v_bfe_u32 v108, v88, 16, 1
	v_add3_u32 v120, v88, v108, s10
	v_add_f32_e32 v108, 1.0, v110
	v_lshlrev_b32_e32 v88, 16, v173
	v_rcp_f32_e32 v108, v108
	v_mul_f32_e32 v88, v112, v88
	v_bfe_u32 v114, v88, 16, 1
	v_add3_u32 v88, v88, v114, s10
	ds_write_b16_d16_hi v83, v88 offset:3456
	v_fma_f32 v88, v80, v108, v149
	v_mul_f32_e32 v88, v112, v88
	v_max_f32_e32 v88, 0xda24260, v88
	v_rcp_f32_e32 v112, v88
	v_mul_f32_e32 v108, v110, v108
	v_mul_f32_e32 v108, v80, v108
	v_mul_f32_e32 v106, v88, v106
	v_mul_f32_e32 v108, v108, v112
	v_bfe_u32 v110, v108, 16, 1
	v_add3_u32 v108, v108, v110, s10
	v_lshlrev_b32_e32 v110, 16, v177
	v_max_f32_e32 v110, v110, v110
	v_med3_f32 v110, v110, s9, v244
	v_mul_f32_e32 v110, 0xbfb8aa3b, v110
	v_exp_f32_e32 v110, v110
	v_bfe_u32 v114, v106, 16, 1
	v_add3_u32 v106, v106, v114, s10
	ds_write_b16_d16_hi v83, v106 offset:3600
	v_add_f32_e32 v112, 1.0, v110
	v_rcp_f32_e32 v112, v112
	v_and_b32_e32 v121, 0xffff0000, v108
	ds_write_b16_d16_hi v83, v108 offset:8208
	v_exp_f32_e32 v104, v104
	v_fma_f32 v106, v80, v112, v149
	v_mul_f32_e32 v88, v88, v106
	v_max_f32_e32 v88, 0xda24260, v88
	v_rcp_f32_e32 v106, v88
	v_mul_f32_e32 v108, v110, v112
	v_mul_f32_e32 v108, v80, v108
	v_lshl_or_b32 v79, v122, 16, v128
	v_mul_f32_e32 v106, v108, v106
	v_bfe_u32 v108, v106, 16, 1
	v_add3_u32 v122, v106, v108, s10
	v_add_f32_e32 v108, 1.0, v104
	v_lshlrev_b32_e32 v106, 16, v164
	v_rcp_f32_e32 v108, v108
	v_mul_f32_e32 v106, v88, v106
	v_bfe_u32 v110, v106, 16, 1
	v_add3_u32 v106, v106, v110, s10
	ds_write_b16_d16_hi v83, v106 offset:3744
	v_fma_f32 v106, v80, v108, v149
	v_mul_f32_e32 v88, v88, v106
	v_max_f32_e32 v88, 0xda24260, v88
	v_rcp_f32_e32 v106, v88
	v_mul_f32_e32 v104, v104, v108
	v_mul_f32_e32 v104, v80, v104
	v_lshlrev_b32_e32 v108, 16, v179
	v_mul_f32_e32 v104, v104, v106
	v_bfe_u32 v106, v104, 16, 1
	v_add3_u32 v104, v104, v106, s10
	v_lshlrev_b32_e32 v106, 16, v165
	v_max_f32_e32 v106, v106, v106
	v_med3_f32 v106, v106, s9, v244
	v_mul_f32_e32 v106, 0xbfb8aa3b, v106
	v_exp_f32_e32 v106, v106
	v_mul_f32_e32 v108, v88, v108
	v_bfe_u32 v112, v108, 16, 1
	v_add3_u32 v108, v108, v112, s10
	v_add_f32_e32 v110, 1.0, v106
	v_rcp_f32_e32 v110, v110
	ds_write_b16_d16_hi v83, v108 offset:3888
	v_lshl_or_b32 v74, v144, 16, v131
	v_and_b32_e32 v131, 0xffff0000, v104
	v_fma_f32 v108, v80, v110, v149
	v_mul_f32_e32 v88, v88, v108
	v_max_f32_e32 v88, 0xda24260, v88
	v_rcp_f32_e32 v108, v88
	ds_write_b16_d16_hi v83, v104 offset:8496
	v_mul_f32_e32 v104, v106, v110
	v_mul_f32_e32 v104, v80, v104
	v_mul_f32_e32 v104, v104, v108
	s_waitcnt vmcnt(2)
	v_lshlrev_b32_e32 v108, 16, v180
	v_max_f32_e32 v108, v108, v108
	v_med3_f32 v108, v108, s9, v244
	v_mul_f32_e32 v108, 0xbfb8aa3b, v108
	v_exp_f32_e32 v108, v108
	v_bfe_u32 v106, v104, 16, 1
	v_lshl_or_b32 v75, v153, 16, v132
	v_add3_u32 v132, v104, v106, s10
	v_add_f32_e32 v106, 1.0, v108
	v_lshlrev_b32_e32 v104, 16, v169
	v_rcp_f32_e32 v106, v106
	v_mul_f32_e32 v104, v88, v104
	v_bfe_u32 v110, v104, 16, 1
	v_add3_u32 v104, v104, v110, s10
	ds_write_b16_d16_hi v83, v104 offset:4032
	v_fma_f32 v104, v80, v106, v149
	v_mul_f32_e32 v88, v88, v104
	v_max_f32_e32 v88, 0xda24260, v88
	v_rcp_f32_e32 v104, v88
	v_mul_f32_e32 v106, v108, v106
	v_mul_f32_e32 v106, v80, v106
	s_waitcnt vmcnt(1)
	v_lshlrev_b32_e32 v102, 16, v102
	v_mul_f32_e32 v104, v106, v104
	v_bfe_u32 v106, v104, 16, 1
	v_add3_u32 v104, v104, v106, s10
	v_lshlrev_b32_e32 v106, 16, v166
	v_max_f32_e32 v106, v106, v106
	v_med3_f32 v106, v106, s9, v244
	v_mul_f32_e32 v106, 0xbfb8aa3b, v106
	v_exp_f32_e32 v106, v106
	v_mul_f32_e32 v102, v88, v102
	v_bfe_u32 v110, v102, 16, 1
	v_add3_u32 v102, v102, v110, s10
	v_add_f32_e32 v108, 1.0, v106
	v_rcp_f32_e32 v108, v108
	ds_write_b16_d16_hi v83, v102 offset:4176
	s_waitcnt vmcnt(0)
	v_lshlrev_b32_e32 v86, 16, v86
	v_max_f32_e32 v86, v86, v86
	v_fma_f32 v102, v80, v108, v149
	v_mul_f32_e32 v88, v88, v102
	v_max_f32_e32 v88, 0xda24260, v88
	v_rcp_f32_e32 v102, v88
	v_med3_f32 v86, v86, s9, v244
	v_mul_f32_e32 v86, 0xbfb8aa3b, v86
	v_lshl_or_b32 v69, v151, 16, v135
	v_and_b32_e32 v135, 0xffff0000, v104
	ds_write_b16_d16_hi v83, v104 offset:8784
	v_mul_f32_e32 v104, v106, v108
	v_exp_f32_e32 v86, v86
	v_mul_f32_e32 v104, v80, v104
	v_mul_f32_e32 v102, v104, v102
	v_bfe_u32 v104, v102, 16, 1
	v_lshl_or_b32 v70, v150, 16, v136
	v_add3_u32 v136, v102, v104, s10
	v_add_f32_e32 v104, 1.0, v86
	v_rcp_f32_e32 v104, v104
	v_lshlrev_b32_e32 v102, 16, v168
	v_mul_f32_e32 v102, v88, v102
	v_bfe_u32 v106, v102, 16, 1
	v_fmac_f32_e32 v149, v80, v104
	v_mul_f32_e32 v88, v88, v149
	v_add3_u32 v102, v102, v106, s10
	v_max_f32_e32 v88, 0xda24260, v88
	ds_write_b16_d16_hi v83, v102 offset:4320
	v_rcp_f32_e32 v102, v88
	v_mul_f32_e32 v86, v86, v104
	v_mul_f32_e32 v80, v80, v86
	v_and_b32_e32 v81, 0xffff0000, v64
	v_mul_f32_e32 v80, v80, v102
	v_bfe_u32 v86, v80, 16, 1
	v_add3_u32 v80, v80, v86, s10
	v_lshlrev_b32_e32 v86, 16, v167
	v_mul_f32_e32 v86, v88, v86
	v_bfe_u32 v102, v86, 16, 1
	v_add3_u32 v86, v86, v102, s10
	v_and_b32_e32 v85, 0xffff0000, v66
	v_and_b32_e32 v87, 0xffff0000, v65
	v_and_b32_e32 v105, 0xffff0000, v159
	v_and_b32_e32 v107, 0xffff0000, v163
	v_and_b32_e32 v109, 0xffff0000, v115
	v_and_b32_e32 v111, 0xffff0000, v172
	v_and_b32_e32 v113, 0xffff0000, v176
	v_and_b32_e32 v115, 0xffff0000, v175
	v_and_b32_e32 v117, 0xffff0000, v117
	v_and_b32_e32 v119, 0xffff0000, v119
	v_lshl_or_b32 v67, v142, 16, v141
	v_lshl_or_b32 v66, v143, 16, v140
	v_lshl_or_b32 v65, v145, 16, v139
	v_lshl_or_b32 v64, v146, 16, v138
	v_lshl_or_b32 v71, v147, 16, v137
	v_lshl_or_b32 v68, v152, 16, v134
	v_lshl_or_b32 v73, v154, 16, v130
	v_lshl_or_b32 v72, v155, 16, v129
	v_lshl_or_b32 v77, v118, 16, v126
	ds_write_b16_d16_hi v83, v120 offset:8064
	ds_write_b16_d16_hi v83, v122 offset:8352
	ds_write_b16_d16_hi v83, v132 offset:8640
	ds_write_b16_d16_hi v83, v136 offset:8928
	v_and_b32_e32 v137, 0xffff0000, v80
	ds_write_b16_d16_hi v83, v86 offset:4464
	ds_write_b16_d16_hi v83, v80 offset:9072
	v_and_b32_e32 v112, 0xffff0000, v170
	v_and_b32_e32 v104, 0xffff0000, v157
	v_and_b32_e32 v80, 0xffff0000, v178
	v_pk_mul_f32 v[112:113], v[88:89], v[112:113] op_sel_hi:[0,1]
	v_and_b32_e32 v108, 0xffff0000, v84
	v_pk_mul_f32 v[104:105], v[88:89], v[104:105] op_sel_hi:[0,1]
	v_and_b32_e32 v84, 0xffff0000, v182
	v_pk_mul_f32 v[80:81], v[88:89], v[80:81] op_sel_hi:[0,1]
	v_and_b32_e32 v120, 0xffff0000, v120
	v_cvt_pk_bf16_f32 v129, v112, v113
	v_cvt_pk_bf16_f32 v113, v104, v105
	v_pk_mul_f32 v[84:85], v[88:89], v[84:85] op_sel_hi:[0,1]
	v_cvt_pk_bf16_f32 v105, v80, v81
	v_pk_mul_f32 v[80:81], v[88:89], v[120:121] op_sel_hi:[0,1]
	v_and_b32_e32 v130, 0xffff0000, v122
	v_and_b32_e32 v102, 0xffff0000, v156
	v_and_b32_e32 v86, 0xffff0000, v181
	v_cvt_pk_bf16_f32 v104, v84, v85
	v_cvt_pk_bf16_f32 v84, v80, v81
	v_pk_mul_f32 v[80:81], v[88:89], v[130:131] op_sel_hi:[0,1]
	v_and_b32_e32 v134, 0xffff0000, v132
	v_and_b32_e32 v118, 0xffff0000, v133
	v_and_b32_e32 v116, 0xffff0000, v116
	v_and_b32_e32 v114, 0xffff0000, v123
	v_and_b32_e32 v110, 0xffff0000, v171
	v_and_b32_e32 v106, 0xffff0000, v158
	v_pk_mul_f32 v[102:103], v[88:89], v[102:103] op_sel_hi:[0,1]
	v_pk_mul_f32 v[86:87], v[88:89], v[86:87] op_sel_hi:[0,1]
	v_cvt_pk_bf16_f32 v85, v80, v81
	v_pk_mul_f32 v[80:81], v[88:89], v[134:135] op_sel_hi:[0,1]
	v_and_b32_e32 v136, 0xffff0000, v136
	s_movk_i32 s0, 0x50
	v_pk_mul_f32 v[118:119], v[88:89], v[118:119] op_sel_hi:[0,1]
	v_pk_mul_f32 v[116:117], v[88:89], v[116:117] op_sel_hi:[0,1]
	v_pk_mul_f32 v[114:115], v[88:89], v[114:115] op_sel_hi:[0,1]
	v_pk_mul_f32 v[110:111], v[88:89], v[110:111] op_sel_hi:[0,1]
	v_pk_mul_f32 v[108:109], v[88:89], v[108:109] op_sel_hi:[0,1]
	v_pk_mul_f32 v[106:107], v[88:89], v[106:107] op_sel_hi:[0,1]
	v_cvt_pk_bf16_f32 v102, v102, v103
	v_cvt_pk_bf16_f32 v103, v86, v87
	v_cvt_pk_bf16_f32 v86, v80, v81
	v_pk_mul_f32 v[80:81], v[88:89], v[136:137] op_sel_hi:[0,1]
	v_mad_u64_u32 v[138:139], s[2:3], v82, s0, v[92:93]
	v_cvt_pk_bf16_f32 v126, v118, v119
	v_cvt_pk_bf16_f32 v127, v116, v117
	v_cvt_pk_bf16_f32 v128, v114, v115
	v_cvt_pk_bf16_f32 v110, v110, v111
	v_cvt_pk_bf16_f32 v111, v108, v109
	v_cvt_pk_bf16_f32 v112, v106, v107
	v_cvt_pk_bf16_f32 v87, v80, v81
	v_lshl_add_u32 v80, v82, 2, v92
	ds_write_b128 v138, v[126:129] offset:9216
	ds_write_b128 v138, v[110:113] offset:9232
	ds_write_b128 v138, v[102:105] offset:9248
	ds_write_b128 v138, v[84:87] offset:9264
	ds_write_b32 v80, v88 offset:19456
	ds_write_b128 v138, v[76:79] offset:14336
	ds_write_b128 v138, v[72:75] offset:14352
	ds_write_b128 v138, v[68:71] offset:14368
	ds_write_b128 v138, v[64:67] offset:14384
	s_waitcnt lgkmcnt(0)
	v_or_b32_e32 v88, v95, v124
	v_lshlrev_b64 v[64:65], 11, v[88:89]
	v_lshl_add_u64 v[64:65], s[16:17], 0, v[64:65]
	v_lshlrev_b32_e32 v80, 2, v125
	s_movk_i32 s48, 0x90
	v_lshl_add_u64 v[64:65], v[64:65], 0, v[90:91]
	v_ashrrev_i32_e32 v81, 31, v80
	v_mad_u32_u24 v88, v124, s48, v92
	v_lshl_add_u64 v[104:105], v[80:81], 1, v[64:65]
	v_lshl_add_u32 v81, v125, 4, v88
	ds_read_b128 v[64:67], v81 offset:4608
	ds_read_b128 v[68:71], v81
	ds_read_b128 v[82:85], v81 offset:32
	ds_read_b128 v[106:109], v81 offset:4640
	s_waitcnt lgkmcnt(2)
	v_mfma_f32_32x32x16_bf16 v[64:79], v[64:67], v[68:71], 0
	v_cmp_le_i32_e32 vcc, v80, v124
	v_cvt_pk_bf16_f32 v32, v32, v33
	v_cvt_pk_bf16_f32 v33, v34, v35
	v_cvt_pk_bf16_f32 v34, v36, v37
	v_cvt_pk_bf16_f32 v35, v38, v39
	v_cvt_pk_bf16_f32 v36, v48, v49
	v_cvt_pk_bf16_f32 v37, v50, v51
	s_waitcnt lgkmcnt(0)
	v_mfma_f32_32x32x16_bf16 v[64:79], v[106:109], v[82:85], v[64:79]
	ds_read_b128 v[82:85], v81 offset:4672
	ds_read_b128 v[106:109], v81 offset:64
	v_cvt_pk_bf16_f32 v38, v52, v53
	v_cvt_pk_bf16_f32 v39, v54, v55
	s_mov_b32 s6, 0x16f00000
	s_mov_b64 s[4:5], 0x16f00600
	v_lshl_add_u64 v[102:103], v[104:105], 0, s[4:5]
	s_waitcnt lgkmcnt(0)
	v_mfma_f32_32x32x16_bf16 v[64:79], v[82:85], v[106:109], v[64:79]
	ds_read_b128 v[82:85], v81 offset:4704
	ds_read_b128 v[106:109], v81 offset:96
	v_or_b32_e32 v81, 2, v80
	s_waitcnt lgkmcnt(0)
	v_mfma_f32_32x32x16_bf16 v[64:79], v[82:85], v[106:109], v[64:79]
	s_nop 11
	v_cndmask_b32_e32 v64, 0, v64, vcc
	v_cmp_lt_i32_e32 vcc, v80, v124
	s_nop 1
	v_cndmask_b32_e32 v65, 0, v65, vcc
	v_cmp_le_i32_e32 vcc, v81, v124
	v_or_b32_e32 v81, 3, v80
	v_cvt_pk_bf16_f32 v84, v64, v65
	v_cndmask_b32_e32 v66, 0, v66, vcc
	v_cmp_le_i32_e32 vcc, v81, v124
	v_add_u32_e32 v81, 8, v80
	v_lshlrev_b32_e32 v64, 3, v125
	v_cndmask_b32_e32 v67, 0, v67, vcc
	v_cmp_le_i32_e32 vcc, v81, v124
	v_add_u32_e32 v81, 9, v80
	v_mul_u32_u24_e32 v65, 0x50, v124
	v_cndmask_b32_e32 v68, 0, v68, vcc
	v_cmp_le_i32_e32 vcc, v81, v124
	v_add_u32_e32 v81, 10, v80
	v_add3_u32 v114, v92, v64, v65
	v_cndmask_b32_e32 v69, 0, v69, vcc
	v_cmp_le_i32_e32 vcc, v81, v124
	v_add_u32_e32 v81, 11, v80
	v_cvt_pk_bf16_f32 v86, v68, v69
	v_cndmask_b32_e32 v70, 0, v70, vcc
	v_cmp_le_i32_e32 vcc, v81, v124
	v_add_u32_e32 v81, 16, v80
	v_add_u32_e32 v68, 0x3800, v114
	v_cndmask_b32_e32 v71, 0, v71, vcc
	v_cmp_le_i32_e32 vcc, v81, v124
	v_add_u32_e32 v81, 17, v80
	v_cvt_pk_bf16_f32 v85, v66, v67
	v_cndmask_b32_e32 v72, 0, v72, vcc
	v_cmp_le_i32_e32 vcc, v81, v124
	v_add_u32_e32 v81, 18, v80
	v_add_u32_e32 v88, v88, v64
	v_cndmask_b32_e32 v73, 0, v73, vcc
	v_cmp_le_i32_e32 vcc, v81, v124
	v_add_u32_e32 v81, 19, v80
	ds_read2_b64 v[64:67], v68 offset1:2
	ds_read2_b64 v[106:109], v68 offset0:4 offset1:6
	v_cndmask_b32_e32 v74, 0, v74, vcc
	v_cmp_le_i32_e32 vcc, v81, v124
	v_add_u32_e32 v81, 24, v80
	v_cvt_pk_bf16_f32 v87, v70, v71
	v_cndmask_b32_e32 v75, 0, v75, vcc
	v_cmp_le_i32_e32 vcc, v81, v124
	v_add_u32_e32 v81, 25, v80
	s_nop 0
	v_cndmask_b32_e32 v76, 0, v76, vcc
	v_cmp_le_i32_e32 vcc, v81, v124
	v_add_u32_e32 v81, 26, v80
	v_add_u32_e32 v80, 27, v80
	v_cndmask_b32_e32 v77, 0, v77, vcc
	v_cmp_le_i32_e32 vcc, v81, v124
	v_cvt_pk_bf16_f32 v81, v74, v75
	v_cvt_pk_bf16_f32 v82, v76, v77
	v_cndmask_b32_e32 v78, 0, v78, vcc
	v_cmp_le_i32_e32 vcc, v80, v124
	v_cvt_pk_bf16_f32 v80, v72, v73
	s_nop 0
	v_cndmask_b32_e32 v79, 0, v79, vcc
	v_cvt_pk_bf16_f32 v83, v78, v79
	s_waitcnt lgkmcnt(1)
	v_mfma_f32_32x32x16_bf16 v[64:79], v[64:67], v[84:87], 0
	s_waitcnt lgkmcnt(0)
	v_mfma_f32_32x32x16_bf16 v[64:79], v[106:109], v[80:83], v[64:79]
	ds_read2_b64 v[106:109], v88 offset1:2
	ds_read2_b64 v[110:113], v88 offset0:4 offset1:6
	s_waitcnt lgkmcnt(1)
	v_mfma_f32_32x32x16_bf16 v[64:79], v[32:35], v[106:109], v[64:79]
	v_cvt_pk_bf16_f32 v32, v40, v41
	v_cvt_pk_bf16_f32 v33, v42, v43
	v_cvt_pk_bf16_f32 v34, v44, v45
	v_cvt_pk_bf16_f32 v35, v46, v47
	s_waitcnt lgkmcnt(0)
	s_nop 0
	v_mfma_f32_32x32x16_bf16 v[64:79], v[32:35], v[110:113], v[64:79]
	ds_read2_b64 v[32:35], v88 offset0:8 offset1:10
	s_waitcnt lgkmcnt(0)
	v_mfma_f32_32x32x16_bf16 v[64:79], v[36:39], v[32:35], v[64:79]
	ds_read2_b64 v[32:35], v88 offset0:12 offset1:14
	v_cvt_pk_bf16_f32 v36, v56, v57
	v_cvt_pk_bf16_f32 v37, v58, v59
	v_cvt_pk_bf16_f32 v38, v60, v61
	v_cvt_pk_bf16_f32 v39, v62, v63
	s_waitcnt lgkmcnt(0)
	s_nop 0
	v_mfma_f32_32x32x16_bf16 v[64:79], v[36:39], v[32:35], v[64:79]
	v_add_co_u32_e32 v34, vcc, s6, v104
	s_nop 1
	v_addc_co_u32_e32 v35, vcc, 0, v105, vcc
	s_nop 7
	v_cvt_pk_bf16_f32 v32, v64, v65
	v_cvt_pk_bf16_f32 v33, v66, v67
	global_store_dwordx2 v[34:35], v[32:33], off offset:1536
	v_cvt_pk_bf16_f32 v32, v68, v69
	v_cvt_pk_bf16_f32 v33, v70, v71
	global_store_dwordx2 v[102:103], v[32:33], off offset:16
	v_cvt_pk_bf16_f32 v32, v72, v73
	v_cvt_pk_bf16_f32 v33, v74, v75
	global_store_dwordx2 v[102:103], v[32:33], off offset:32
	v_cvt_pk_bf16_f32 v32, v76, v77
	v_cvt_pk_bf16_f32 v33, v78, v79
	global_store_dwordx2 v[102:103], v[32:33], off offset:48
	v_add_u32_e32 v48, 0x4000, v114
	ds_read2_b64 v[32:35], v48 offset0:64 offset1:66
	ds_read2_b64 v[48:51], v48 offset0:68 offset1:70
	ds_read2_b64 v[52:55], v88 offset1:2
	v_cvt_pk_bf16_f32 v0, v0, v1
	v_cvt_pk_bf16_f32 v1, v2, v3
	v_cvt_pk_bf16_f32 v2, v4, v5
	v_cvt_pk_bf16_f32 v3, v6, v7
	ds_read2_b64 v[4:7], v88 offset0:4 offset1:6
	v_cvt_pk_bf16_f32 v8, v8, v9
	v_cvt_pk_bf16_f32 v9, v10, v11
	s_waitcnt lgkmcnt(3)
	v_mfma_f32_32x32x16_bf16 v[32:47], v[32:35], v[84:87], 0
	v_cvt_pk_bf16_f32 v10, v12, v13
	v_cvt_pk_bf16_f32 v11, v14, v15
	v_cvt_pk_bf16_f32 v12, v16, v17
	v_cvt_pk_bf16_f32 v13, v18, v19
	v_cvt_pk_bf16_f32 v14, v20, v21
	v_cvt_pk_bf16_f32 v15, v22, v23
	s_waitcnt lgkmcnt(2)
	v_mfma_f32_32x32x16_bf16 v[32:47], v[48:51], v[80:83], v[32:47]
	s_waitcnt lgkmcnt(1)
	v_mfma_f32_32x32x16_bf16 v[32:47], v[0:3], v[52:55], v[32:47]
	ds_read2_b64 v[0:3], v88 offset0:8 offset1:10
	s_waitcnt lgkmcnt(1)
	v_mfma_f32_32x32x16_bf16 v[32:47], v[8:11], v[4:7], v[32:47]
	ds_read2_b64 v[4:7], v88 offset0:12 offset1:14
	v_cvt_pk_bf16_f32 v8, v24, v25
	v_cvt_pk_bf16_f32 v9, v26, v27
	v_cvt_pk_bf16_f32 v10, v28, v29
	v_cvt_pk_bf16_f32 v11, v30, v31
	s_waitcnt lgkmcnt(1)
	v_mfma_f32_32x32x16_bf16 v[32:47], v[12:15], v[0:3], v[32:47]
	s_waitcnt lgkmcnt(0)
	v_mfma_f32_32x32x16_bf16 v[32:47], v[8:11], v[4:7], v[32:47]
	s_nop 11
	v_cvt_pk_bf16_f32 v0, v32, v33
	v_cvt_pk_bf16_f32 v1, v34, v35
	v_cvt_pk_bf16_f32 v2, v36, v37
	v_cvt_pk_bf16_f32 v3, v38, v39
	v_cvt_pk_bf16_f32 v4, v40, v41
	v_cvt_pk_bf16_f32 v5, v42, v43
	v_cvt_pk_bf16_f32 v6, v44, v45
	v_cvt_pk_bf16_f32 v7, v46, v47
	global_store_dwordx2 v[102:103], v[0:1], off offset:64
	global_store_dwordx2 v[102:103], v[2:3], off offset:80
	global_store_dwordx2 v[102:103], v[4:5], off offset:96
	global_store_dwordx2 v[102:103], v[6:7], off offset:112
	s_waitcnt lgkmcnt(0)
	v_lshl_add_u64 v[0:1], s[44:45], 0, v[160:161]
	v_add_co_u32_e32 v2, vcc, s20, v0
	s_movk_i32 s11, 0x3000
	s_nop 0
	v_addc_co_u32_e32 v3, vcc, 0, v1, vcc
	v_add_co_u32_e32 v4, vcc, s11, v0
	s_movk_i32 s7, 0x4000
	s_nop 0
	v_addc_co_u32_e32 v5, vcc, 0, v1, vcc
	v_add_co_u32_e32 v0, vcc, s7, v0
	v_readlane_b32 s0, v255, 22
	s_nop 0
	v_addc_co_u32_e32 v1, vcc, 0, v1, vcc
	global_load_dword v24, v[2:3], off offset:3072
	global_load_dword v25, v[4:5], off offset:1024
	global_load_dword v26, v[4:5], off offset:3072
	global_load_dword v27, v[0:1], off offset:1024
	v_or_b32_e32 v0, 1, v148
	v_mad_i64_i32 v[0:1], s[2:3], v0, 36, v[96:97]
	v_lshlrev_b64 v[0:1], 13, v[0:1]
	v_readlane_b32 s1, v255, 23
	v_readlane_b32 s2, v255, 1
	v_readlane_b32 s3, v255, 2
	v_lshl_add_u64 v[0:1], s[0:1], 0, v[0:1]
	v_lshl_add_u64 v[0:1], v[0:1], 0, v[98:99]
	v_lshl_add_u64 v[0:1], v[0:1], 0, v[100:101]
	global_load_dwordx2 v[2:3], v[0:1], off
	global_load_dwordx2 v[4:5], v[0:1], off offset:16
	global_load_dwordx2 v[6:7], v[0:1], off offset:32
	global_load_dwordx2 v[8:9], v[0:1], off offset:48
	s_movk_i32 s0, 0x1000
	v_add_co_u32_e32 v10, vcc, s0, v0
	s_mov_b32 s1, 0xf149f2ca
	s_nop 0
	v_addc_co_u32_e32 v11, vcc, 0, v1, vcc
	global_load_dwordx2 v[12:13], v[10:11], off
	global_load_dwordx2 v[14:15], v[10:11], off offset:16
	global_load_dwordx2 v[16:17], v[10:11], off offset:32
	global_load_dwordx2 v[18:19], v[10:11], off offset:48
	global_load_dwordx2 v[20:21], v[0:1], off offset:64
	global_load_dwordx2 v[22:23], v[0:1], off offset:80
	global_load_dwordx2 v[58:59], v[0:1], off offset:96
	s_nop 0
	global_load_dwordx2 v[0:1], v[0:1], off offset:112
	s_nop 0
	global_load_dwordx2 v[64:65], v[10:11], off offset:64
	global_load_dwordx2 v[72:73], v[10:11], off offset:80
	global_load_dwordx2 v[76:77], v[10:11], off offset:96
	s_nop 0
	global_load_dwordx2 v[10:11], v[10:11], off offset:112
	s_mov_b64 s[40:41], s[44:45]
	s_mov_b64 s[12:13], s[44:45]
	s_waitcnt vmcnt(18)
	v_max3_f32 v28, v24, s1, v25
	s_waitcnt vmcnt(16)
	v_max3_f32 v28, v28, v26, v27
	v_sub_f32_e32 v25, v25, v28
	v_mul_f32_e32 v25, 0x3fb8aa3b, v25
	v_sub_f32_e32 v24, v24, v28
	v_sub_f32_e32 v26, v26, v28
	v_exp_f32_e32 v25, v25
	v_mul_f32_e32 v24, 0x3fb8aa3b, v24
	v_mul_f32_e32 v26, 0x3fb8aa3b, v26
	v_sub_f32_e32 v27, v27, v28
	v_exp_f32_e32 v50, v24
	v_exp_f32_e32 v51, v26
	v_mul_f32_e32 v27, 0x3fb8aa3b, v27
	v_exp_f32_e32 v52, v27
	s_waitcnt vmcnt(15)
	v_lshlrev_b32_e32 v32, 16, v2
	v_and_b32_e32 v33, 0xffff0000, v2
	v_add_f32_e32 v2, 0, v25
	v_cndmask_b32_e64 v2, v2, 0, s[2:3]
	v_readlane_b32 s2, v255, 3
	v_lshlrev_b32_e32 v34, 16, v3
	v_and_b32_e32 v35, 0xffff0000, v3
	s_waitcnt vmcnt(14)
	v_lshlrev_b32_e32 v36, 16, v4
	v_and_b32_e32 v37, 0xffff0000, v4
	v_add_f32_e32 v3, 0, v50
	v_add_f32_e32 v4, v51, v2
	v_readlane_b32 s3, v255, 4
	v_add_f32_e32 v3, v25, v3
	v_add_f32_e32 v3, v51, v3
	v_cndmask_b32_e64 v2, v4, v2, s[2:3]
	v_readlane_b32 s2, v255, 5
	v_add_f32_e32 v4, v52, v2
	v_readlane_b32 s3, v255, 6
	v_add_f32_e32 v3, v52, v3
	v_lshlrev_b32_e32 v38, 16, v5
	v_cndmask_b32_e64 v2, v4, v2, s[2:3]
	v_div_scale_f32 v4, s[2:3], v3, v3, v2
	v_and_b32_e32 v39, 0xffff0000, v5
	v_rcp_f32_e32 v5, v4
	s_waitcnt vmcnt(13)
	v_lshlrev_b32_e32 v42, 16, v7
	v_and_b32_e32 v43, 0xffff0000, v7
	v_lshlrev_b32_e32 v40, 16, v6
	v_fma_f32 v7, -v4, v5, 1.0
	v_and_b32_e32 v41, 0xffff0000, v6
	v_div_scale_f32 v6, vcc, v2, v3, v2
	v_fmac_f32_e32 v5, v7, v5
	v_mul_f32_e32 v7, v6, v5
	s_waitcnt vmcnt(12)
	v_lshlrev_b32_e32 v44, 16, v8
	v_and_b32_e32 v45, 0xffff0000, v8
	v_fma_f32 v8, -v4, v7, v6
	v_fmac_f32_e32 v7, v8, v5
	v_fma_f32 v4, -v4, v7, v6
	s_waitcnt vmcnt(9)
	v_lshlrev_b32_e32 v24, 16, v16
	v_and_b32_e32 v25, 0xffff0000, v16
	v_div_fmas_f32 v4, v4, v5, v7
	v_mov_b32_e32 v16, v94
	v_div_fixup_f32 v116, v4, v3, v2
	s_add_u32 s2, s40, 0xb200000
	v_lshlrev_b32_e32 v46, 16, v9
	v_and_b32_e32 v47, 0xffff0000, v9
	v_lshlrev_b32_e32 v26, 16, v12
	v_and_b32_e32 v27, 0xffff0000, v12
	v_lshlrev_b32_e32 v28, 16, v13
	v_and_b32_e32 v29, 0xffff0000, v13
	v_lshlrev_b32_e32 v30, 16, v14
	v_and_b32_e32 v31, 0xffff0000, v14
	v_lshlrev_b32_e32 v48, 16, v15
	v_and_b32_e32 v49, 0xffff0000, v15
	v_lshlrev_b32_e32 v84, 16, v17
	v_and_b32_e32 v85, 0xffff0000, v17
	s_waitcnt vmcnt(8)
	v_lshlrev_b32_e32 v86, 16, v18
	v_and_b32_e32 v87, 0xffff0000, v18
	v_lshlrev_b32_e32 v96, 16, v19
	v_and_b32_e32 v97, 0xffff0000, v19
	s_waitcnt vmcnt(7)
	v_lshlrev_b32_e32 v54, 16, v20
	v_and_b32_e32 v55, 0xffff0000, v20
	v_lshlrev_b32_e32 v50, 16, v21
	v_and_b32_e32 v51, 0xffff0000, v21
	s_waitcnt vmcnt(6)
	v_lshlrev_b32_e32 v52, 16, v22
	v_and_b32_e32 v53, 0xffff0000, v22
	v_lshlrev_b32_e32 v82, 16, v23
	v_and_b32_e32 v83, 0xffff0000, v23
	s_waitcnt vmcnt(5)
	v_lshlrev_b32_e32 v56, 16, v58
	v_and_b32_e32 v57, 0xffff0000, v58
	v_lshlrev_b32_e32 v58, 16, v59
	v_and_b32_e32 v59, 0xffff0000, v59
	s_waitcnt vmcnt(4)
	v_lshlrev_b32_e32 v60, 16, v0
	v_and_b32_e32 v61, 0xffff0000, v0
	v_lshlrev_b32_e32 v62, 16, v1
	v_and_b32_e32 v63, 0xffff0000, v1
	s_waitcnt vmcnt(3)
	v_lshlrev_b32_e32 v66, 16, v64
	v_and_b32_e32 v67, 0xffff0000, v64
	v_lshlrev_b32_e32 v68, 16, v65
	v_and_b32_e32 v69, 0xffff0000, v65
	s_waitcnt vmcnt(2)
	v_lshlrev_b32_e32 v70, 16, v72
	v_and_b32_e32 v71, 0xffff0000, v72
	v_lshlrev_b32_e32 v72, 16, v73
	v_and_b32_e32 v73, 0xffff0000, v73
	s_waitcnt vmcnt(1)
	v_lshlrev_b32_e32 v74, 16, v76
	v_and_b32_e32 v75, 0xffff0000, v76
	v_lshlrev_b32_e32 v76, 16, v77
	v_and_b32_e32 v77, 0xffff0000, v77
	s_waitcnt vmcnt(0)
	v_lshlrev_b32_e32 v78, 16, v10
	v_and_b32_e32 v79, 0xffff0000, v10
	v_lshlrev_b32_e32 v80, 16, v11
	v_and_b32_e32 v81, 0xffff0000, v11
	v_sub_f32_e32 v117, 1.0, v116
	v_and_b32_e32 v118, 31, v16
	v_ashrrev_i32_e32 v119, 5, v16
	s_addc_u32 s3, s41, 0
	v_mov_b64_e32 v[64:65], s[2:3]
	s_movk_i32 s1, 0x1200
	v_mad_i64_i32 v[0:1], s[2:3], v95, s1, v[64:65]
	v_ashrrev_i32_e32 v17, 31, v16
	v_lshl_add_u64 v[0:1], v[0:1], 0, v[90:91]
	v_lshl_add_u64 v[0:1], v[16:17], 1, v[0:1]
	s_mov_b32 s37, 0x23000
	v_add_co_u32_e32 v12, vcc, s37, v0
	s_movk_i32 s2, 0x5000
	s_nop 0
	v_addc_co_u32_e32 v13, vcc, 0, v1, vcc
	global_load_ushort v88, v[12:13], off offset:3072
	global_load_ushort v109, v[12:13], off offset:1536
	v_add_co_u32_e32 v2, vcc, s20, v0
	s_mov_b32 s28, 0x9000
	s_nop 0
	v_addc_co_u32_e32 v3, vcc, 0, v1, vcc
	v_add_co_u32_e32 v4, vcc, s2, v0
	s_movk_i32 s2, 0x7000
	s_nop 0
	v_addc_co_u32_e32 v5, vcc, 0, v1, vcc
	v_add_co_u32_e32 v6, vcc, s2, v0
	s_mov_b32 s29, 0xb000
	s_nop 0
	v_addc_co_u32_e32 v7, vcc, 0, v1, vcc
	v_add_co_u32_e32 v18, vcc, s28, v0
	s_mov_b32 s18, 0xe000
	s_nop 0
	v_addc_co_u32_e32 v19, vcc, 0, v1, vcc
	v_add_co_u32_e32 v20, vcc, s29, v0
	s_mov_b32 s2, 0x10000
	s_nop 0
	v_addc_co_u32_e32 v21, vcc, 0, v1, vcc
	v_add_co_u32_e32 v22, vcc, s18, v0
	s_mov_b32 s30, 0x17000
	s_nop 0
	v_addc_co_u32_e32 v23, vcc, 0, v1, vcc
	v_add_co_u32_e32 v98, vcc, s2, v0
	s_mov_b32 s2, 0x14000
	s_nop 0
	v_addc_co_u32_e32 v99, vcc, 0, v1, vcc
	v_add_co_u32_e32 v8, vcc, s51, v0
	s_mov_b32 s31, 0x19000
	s_nop 0
	v_addc_co_u32_e32 v9, vcc, 0, v1, vcc
	v_add_co_u32_e32 v10, vcc, s2, v0
	s_mov_b32 s34, 0x1b000
	s_nop 0
	v_addc_co_u32_e32 v11, vcc, 0, v1, vcc
	v_add_co_u32_e32 v14, vcc, s30, v0
	s_mov_b32 s35, 0x1d000
	s_nop 0
	v_addc_co_u32_e32 v15, vcc, 0, v1, vcc
	v_add_co_u32_e32 v100, vcc, s31, v0
	s_mov_b32 s19, 0x20000
	s_nop 0
	v_addc_co_u32_e32 v101, vcc, 0, v1, vcc
	v_add_co_u32_e32 v102, vcc, s34, v0
	s_mov_b32 s36, 0x22000
	s_nop 0
	v_addc_co_u32_e32 v103, vcc, 0, v1, vcc
	v_add_co_u32_e32 v104, vcc, s35, v0
	s_mov_b32 s21, 0x21000
	s_nop 0
	v_addc_co_u32_e32 v105, vcc, 0, v1, vcc
	v_add_co_u32_e32 v106, vcc, s19, v0
	s_mov_b32 s42, 0x1f000
	s_nop 0
	v_addc_co_u32_e32 v107, vcc, 0, v1, vcc
	v_add_co_u32_e32 v120, vcc, s36, v0
	s_mov_b32 s17, 0x1e000
	s_nop 0
	v_addc_co_u32_e32 v121, vcc, 0, v1, vcc
	v_add_co_u32_e32 v110, vcc, s21, v0
	s_mov_b32 s16, 0x1c000
	s_nop 0
	v_addc_co_u32_e32 v111, vcc, 0, v1, vcc
	global_load_ushort v113, v[110:111], off offset:512
	global_load_ushort v108, v[110:111], off offset:1024
	global_load_ushort v122, v[110:111], off offset:2048
	s_nop 0
	global_load_ushort v110, v[12:13], off offset:2048
	global_load_ushort v112, v[120:121], off offset:1536
	global_load_ushort v145, v[120:121], off offset:2560
	global_load_ushort v123, v[104:105], off offset:3584
	global_load_ushort v124, v[106:107], off offset:512
	global_load_ushort v154, v[120:121], off offset:1024
	global_load_ushort v155, v[106:107], off offset:1536
	global_load_ushort v156, v[106:107], off
	global_load_ushort v159, v[104:105], off offset:3072
	global_load_ushort v162, v[104:105], off
	global_load_ushort v166, v[102:103], off offset:3584
	s_waitcnt vmcnt(15)
	v_lshlrev_b32_e32 v12, 16, v88
	v_max_f32_e32 v12, v12, v12
	v_med3_f32 v12, v12, s9, v244
	v_mul_f32_e32 v12, 0xbfb8aa3b, v12
	v_exp_f32_e32 v88, v12
	v_add_co_u32_e32 v12, vcc, s42, v0
	s_mov_b32 s2, 0x1a000
	v_add_f32_e32 v111, 1.0, v88
	v_addc_co_u32_e32 v13, vcc, 0, v1, vcc
	v_rcp_f32_e32 v111, v111
	v_add_co_u32_e32 v136, vcc, s17, v0
	s_waitcnt vmcnt(14)
	v_lshlrev_b32_e32 v109, 16, v109
	v_addc_co_u32_e32 v137, vcc, 0, v1, vcc
	v_add_co_u32_e32 v134, vcc, s16, v0
	v_fma_f32 v114, v117, v111, v116
	s_nop 0
	v_addc_co_u32_e32 v135, vcc, 0, v1, vcc
	v_max_f32_e32 v152, 0xda24260, v114
	v_add_co_u32_e32 v120, vcc, s2, v0
	v_mul_f32_e32 v88, v88, v111
	v_rcp_f32_e32 v111, v152
	v_addc_co_u32_e32 v121, vcc, 0, v1, vcc
	s_mov_b32 s2, 0x18000
	v_add_co_u32_e32 v138, vcc, s2, v0
	s_mov_b32 s2, 0x16000
	s_nop 0
	v_addc_co_u32_e32 v139, vcc, 0, v1, vcc
	v_mul_f32_e32 v88, v117, v88
	v_mul_f32_e32 v109, v152, v109
	global_load_ushort v125, v[14:15], off offset:512
	global_load_ushort v127, v[100:101], off offset:1536
	global_load_ushort v128, v[102:103], off offset:2560
	global_load_ushort v167, v[102:103], off offset:2048
	global_load_ushort v169, v[100:101], off offset:2560
	global_load_ushort v172, v[100:101], off offset:1024
	global_load_ushort v168, v[14:15], off offset:1536
	global_load_ushort v164, v[14:15], off
	v_add_co_u32_e32 v14, vcc, s2, v0
	v_bfe_u32 v114, v109, 16, 1
	v_mul_f32_e32 v88, v88, v111
	v_addc_co_u32_e32 v15, vcc, 0, v1, vcc
	s_mov_b32 s43, 0x15000
	v_add3_u32 v153, v109, v114, s10
	v_bfe_u32 v109, v88, 16, 1
	v_add_co_u32_e32 v140, vcc, s43, v0
	v_add3_u32 v114, v88, v109, s10
	s_nop 0
	v_addc_co_u32_e32 v141, vcc, 0, v1, vcc
	global_load_ushort v126, v[22:23], off offset:512
	global_load_ushort v129, v[98:99], off offset:1536
	global_load_ushort v130, v[8:9], off offset:2560
	global_load_ushort v131, v[10:11], off offset:3584
	global_load_ushort v158, v[10:11], off offset:3072
	global_load_ushort v115, v[10:11], off
	global_load_ushort v111, v[8:9], off offset:3584
	global_load_ushort v109, v[8:9], off offset:2048
	global_load_ushort v173, v[12:13], off offset:1024
	global_load_ushort v174, v[136:137], off offset:3584
	global_load_ushort v175, v[134:135], off offset:2560
	global_load_ushort v176, v[120:121], off offset:1536
	global_load_ushort v133, v[120:121], off offset:2048
	s_nop 0
	global_load_ushort v134, v[134:135], off offset:3072
	s_nop 0
	global_load_ushort v177, v[136:137], off offset:512
	global_load_ushort v135, v[12:13], off
	global_load_ushort v178, v[120:121], off offset:3072
	global_load_ushort v171, v[138:139], off offset:2048
	global_load_ushort v170, v[138:139], off offset:512
	global_load_ushort v165, v[14:15], off offset:1024
	global_load_ushort v163, v[140:141], off offset:3584
	global_load_ushort v160, v[140:141], off offset:512
	global_load_ushort v137, v[14:15], off
	s_nop 0
	global_load_ushort v139, v[138:139], off offset:1024
	s_mov_b32 s44, 0x13000
	v_add_co_u32_e32 v146, vcc, s44, v0
	s_mov_b32 s45, 0x11000
	s_nop 0
	v_addc_co_u32_e32 v147, vcc, 0, v1, vcc
	v_add_co_u32_e32 v106, vcc, s45, v0
	s_mov_b32 s46, 0xf000
	s_nop 0
	v_addc_co_u32_e32 v107, vcc, 0, v1, vcc
	v_add_co_u32_e32 v102, vcc, s46, v0
	s_mov_b32 s47, 0xd000
	s_nop 0
	v_addc_co_u32_e32 v103, vcc, 0, v1, vcc
	v_add_co_u32_e32 v104, vcc, s47, v0
	s_mov_b32 s15, 0xa000
	s_nop 0
	v_addc_co_u32_e32 v105, vcc, 0, v1, vcc
	v_add_co_u32_e32 v100, vcc, s15, v0
	s_mov_b32 s14, 0x8000
	s_waitcnt vmcnt(40)
	v_lshlrev_b32_e32 v8, 16, v145
	v_max_f32_e32 v8, v8, v8
	v_med3_f32 v8, v8, s9, v244
	v_mul_f32_e32 v8, 0xbfb8aa3b, v8
	v_exp_f32_e32 v88, v8
	v_addc_co_u32_e32 v101, vcc, 0, v1, vcc
	v_lshlrev_b32_e32 v122, 16, v122
	v_add_f32_e32 v120, 1.0, v88
	v_rcp_f32_e32 v120, v120
	v_add_co_u32_e32 v10, vcc, s14, v0
	v_max_f32_e32 v122, v122, v122
	v_fma_f32 v121, v117, v120, v116
	v_mul_f32_e32 v121, v152, v121
	v_addc_co_u32_e32 v11, vcc, 0, v1, vcc
	v_max_f32_e32 v121, 0xda24260, v121
	v_med3_f32 v122, v122, s9, v244
	v_add_co_u32_e32 v12, vcc, s27, v0
	v_rcp_f32_e32 v152, v121
	v_mul_f32_e32 v122, 0xbfb8aa3b, v122
	v_addc_co_u32_e32 v13, vcc, 0, v1, vcc
	v_exp_f32_e32 v122, v122
	v_add_co_u32_e32 v14, vcc, s7, v0
	v_mul_f32_e32 v88, v88, v120
	s_nop 0
	v_addc_co_u32_e32 v15, vcc, 0, v1, vcc
	v_mul_f32_e32 v88, v117, v88
	v_add_co_u32_e32 v8, vcc, s0, v0
	v_mul_f32_e32 v88, v88, v152
	global_load_ushort v132, v[0:1], off offset:2560
	global_load_ushort v136, v[2:3], off offset:3584
	global_load_ushort v138, v[4:5], off offset:512
	global_load_ushort v140, v[6:7], off offset:1536
	global_load_ushort v141, v[18:19], off offset:2560
	global_load_ushort v143, v[20:21], off offset:3584
	global_load_ushort v144, v[22:23], off offset:-4096
	global_load_ushort v142, v[4:5], off offset:-4096
	v_addc_co_u32_e32 v9, vcc, 0, v1, vcc
	global_load_ushort v157, v[146:147], off offset:2560
	global_load_ushort v150, v[146:147], off offset:3072
	global_load_ushort v151, v[106:107], off offset:2048
	global_load_ushort v149, v[102:103], off offset:1024
	global_load_ushort v148, v[100:101], off offset:3072
	s_nop 0
	global_load_ushort v146, v[10:11], off offset:2048
	global_load_ushort v147, v[12:13], off offset:1024
	global_load_ushort v145, v[8:9], off offset:3072
	v_bfe_u32 v120, v88, 16, 1
	v_add_f32_e32 v152, 1.0, v122
	v_add3_u32 v88, v88, v120, s10
	s_waitcnt vmcnt(53)
	v_lshlrev_b32_e32 v120, 16, v154
	v_rcp_f32_e32 v152, v152
	v_lshl_add_u32 v17, v16, 1, v92
	v_mul_f32_e32 v120, v121, v120
	ds_write_b16_d16_hi v17, v153 offset:4464
	v_bfe_u32 v153, v120, 16, 1
	v_add3_u32 v120, v120, v153, s10
	ds_write_b16_d16_hi v17, v120 offset:4320
	v_fma_f32 v120, v117, v152, v116
	v_mul_f32_e32 v120, v121, v120
	v_mul_f32_e32 v122, v122, v152
	s_waitcnt vmcnt(52)
	v_lshlrev_b32_e32 v152, 16, v155
	v_max_f32_e32 v120, 0xda24260, v120
	v_max_f32_e32 v152, v152, v152
	v_rcp_f32_e32 v121, v120
	v_med3_f32 v152, v152, s9, v244
	v_mul_f32_e32 v152, 0xbfb8aa3b, v152
	v_exp_f32_e32 v152, v152
	v_mul_f32_e32 v122, v117, v122
	v_mul_f32_e32 v121, v122, v121
	v_bfe_u32 v122, v121, 16, 1
	v_add3_u32 v153, v121, v122, s10
	v_add_f32_e32 v121, 1.0, v152
	v_lshlrev_b32_e32 v113, 16, v113
	v_rcp_f32_e32 v121, v121
	v_mul_f32_e32 v113, v120, v113
	v_bfe_u32 v122, v113, 16, 1
	v_add3_u32 v113, v113, v122, s10
	ds_write_b16_d16_hi v17, v113 offset:4176
	v_fma_f32 v113, v117, v121, v116
	s_waitcnt vmcnt(31)
	v_lshlrev_b32_e32 v122, 16, v173
	v_mul_f32_e32 v113, v120, v113
	v_max_f32_e32 v122, v122, v122
	v_max_f32_e32 v113, 0xda24260, v113
	v_med3_f32 v122, v122, s9, v244
	v_rcp_f32_e32 v120, v113
	v_mul_f32_e32 v122, 0xbfb8aa3b, v122
	v_exp_f32_e32 v122, v122
	v_mul_f32_e32 v121, v152, v121
	v_mul_f32_e32 v121, v117, v121
	v_mul_f32_e32 v120, v121, v120
	v_bfe_u32 v121, v120, 16, 1
	v_add_f32_e32 v152, 1.0, v122
	v_add3_u32 v120, v120, v121, s10
	v_lshlrev_b32_e32 v121, 16, v156
	v_rcp_f32_e32 v152, v152
	v_mul_f32_e32 v121, v113, v121
	v_bfe_u32 v154, v121, 16, 1
	v_add3_u32 v121, v121, v154, s10
	ds_write_b16_d16_hi v17, v121 offset:4032
	v_fma_f32 v121, v117, v152, v116
	v_mul_f32_e32 v113, v113, v121
	v_mul_f32_e32 v122, v122, v152
	s_waitcnt vmcnt(25)
	v_lshlrev_b32_e32 v152, 16, v177
	v_max_f32_e32 v113, 0xda24260, v113
	v_max_f32_e32 v152, v152, v152
	v_rcp_f32_e32 v121, v113
	v_med3_f32 v152, v152, s9, v244
	v_mul_f32_e32 v152, 0xbfb8aa3b, v152
	v_exp_f32_e32 v152, v152
	v_mul_f32_e32 v122, v117, v122
	v_mul_f32_e32 v121, v122, v121
	v_bfe_u32 v122, v121, 16, 1
	v_add3_u32 v154, v121, v122, s10
	v_add_f32_e32 v122, 1.0, v152
	v_lshlrev_b32_e32 v121, 16, v174
	v_rcp_f32_e32 v122, v122
	v_mul_f32_e32 v121, v113, v121
	v_bfe_u32 v155, v121, 16, 1
	v_add3_u32 v121, v121, v155, s10
	ds_write_b16_d16_hi v17, v121 offset:3888
	v_fma_f32 v121, v117, v122, v116
	v_mul_f32_e32 v122, v152, v122
	v_lshlrev_b32_e32 v152, 16, v162
	v_mul_f32_e32 v113, v113, v121
	v_max_f32_e32 v152, v152, v152
	v_max_f32_e32 v113, 0xda24260, v113
	v_med3_f32 v152, v152, s9, v244
	v_rcp_f32_e32 v121, v113
	v_mul_f32_e32 v152, 0xbfb8aa3b, v152
	v_exp_f32_e32 v152, v152
	v_mul_f32_e32 v122, v117, v122
	v_mul_f32_e32 v121, v122, v121
	v_bfe_u32 v122, v121, 16, 1
	v_add_f32_e32 v155, 1.0, v152
	v_add3_u32 v121, v121, v122, s10
	v_lshlrev_b32_e32 v122, 16, v159
	v_rcp_f32_e32 v155, v155
	v_mul_f32_e32 v122, v113, v122
	v_bfe_u32 v156, v122, 16, 1
	v_add3_u32 v122, v122, v156, s10
	ds_write_b16_d16_hi v17, v122 offset:3744
	v_fma_f32 v122, v117, v155, v116
	v_mul_f32_e32 v113, v113, v122
	v_mul_f32_e32 v152, v152, v155
	v_lshlrev_b32_e32 v155, 16, v166
	v_max_f32_e32 v113, 0xda24260, v113
	v_max_f32_e32 v155, v155, v155
	v_rcp_f32_e32 v122, v113
	v_med3_f32 v155, v155, s9, v244
	v_mul_f32_e32 v155, 0xbfb8aa3b, v155
	v_exp_f32_e32 v156, v155
	v_mul_f32_e32 v152, v117, v152
	v_mul_f32_e32 v122, v152, v122
	v_bfe_u32 v152, v122, 16, 1
	v_add3_u32 v155, v122, v152, s10
	v_add_f32_e32 v152, 1.0, v156
	v_lshlrev_b32_e32 v122, 16, v175
	v_rcp_f32_e32 v152, v152
	v_mul_f32_e32 v122, v113, v122
	v_bfe_u32 v159, v122, 16, 1
	v_add3_u32 v122, v122, v159, s10
	ds_write_b16_d16_hi v17, v122 offset:3600
	v_fma_f32 v122, v117, v152, v116
	v_mul_f32_e32 v113, v113, v122
	v_max_f32_e32 v113, 0xda24260, v113
	v_rcp_f32_e32 v122, v113
	v_mul_f32_e32 v152, v156, v152
	v_mul_f32_e32 v152, v117, v152
	ds_write_b16_d16_hi v17, v114 offset:9072
	v_mul_f32_e32 v122, v152, v122
	v_bfe_u32 v152, v122, 16, 1
	v_add3_u32 v122, v122, v152, s10
	v_lshlrev_b32_e32 v152, 16, v167
	v_mul_f32_e32 v152, v113, v152
	v_bfe_u32 v156, v152, 16, 1
	v_add3_u32 v152, v152, v156, s10
	ds_write_b16_d16_hi v17, v88 offset:8928
	ds_write_b16_d16_hi v17, v153 offset:8784
	ds_write_b16_d16_hi v17, v120 offset:8640
	ds_write_b16_d16_hi v17, v154 offset:8496
	ds_write_b16_d16_hi v17, v121 offset:8352
	ds_write_b16_d16_hi v17, v155 offset:8208
	ds_write_b16_d16_hi v17, v152 offset:3456
	ds_write_b16_d16_hi v17, v122 offset:8064
	s_waitcnt vmcnt(23)
	v_lshlrev_b32_e32 v152, 16, v178
	v_max_f32_e32 v152, v152, v152
	v_med3_f32 v152, v152, s9, v244
	v_mul_f32_e32 v152, 0xbfb8aa3b, v152
	v_exp_f32_e32 v152, v152
	v_lshlrev_b32_e32 v109, 16, v109
	v_add_f32_e32 v156, 1.0, v152
	v_rcp_f32_e32 v156, v156
	s_nop 0
	v_fma_f32 v159, v117, v156, v116
	v_mul_f32_e32 v113, v113, v159
	v_max_f32_e32 v113, 0xda24260, v113
	v_mul_f32_e32 v152, v152, v156
	v_rcp_f32_e32 v156, v113
	v_mul_f32_e32 v152, v117, v152
	v_mul_f32_e32 v152, v152, v156
	v_bfe_u32 v156, v152, 16, 1
	v_add3_u32 v156, v152, v156, s10
	v_lshlrev_b32_e32 v152, 16, v176
	v_mul_f32_e32 v152, v113, v152
	v_bfe_u32 v159, v152, 16, 1
	v_add3_u32 v152, v152, v159, s10
	ds_write_b16_d16_hi v17, v152 offset:3312
	ds_write_b16_d16_hi v17, v156 offset:7920
	v_lshlrev_b32_e32 v152, 16, v169
	v_max_f32_e32 v152, v152, v152
	v_med3_f32 v152, v152, s9, v244
	v_mul_f32_e32 v152, 0xbfb8aa3b, v152
	v_exp_f32_e32 v152, v152
	s_nop 0
	v_add_f32_e32 v159, 1.0, v152
	v_rcp_f32_e32 v159, v159
	s_nop 0
	v_fma_f32 v162, v117, v159, v116
	v_mul_f32_e32 v113, v113, v162
	v_max_f32_e32 v173, 0xda24260, v113
	v_rcp_f32_e32 v113, v173
	v_mul_f32_e32 v152, v152, v159
	v_mul_f32_e32 v152, v117, v152
	v_mul_f32_e32 v113, v152, v113
	v_bfe_u32 v152, v113, 16, 1
	v_add3_u32 v152, v113, v152, s10
	v_lshlrev_b32_e32 v113, 16, v172
	v_mul_f32_e32 v113, v173, v113
	v_bfe_u32 v159, v113, 16, 1
	v_add3_u32 v172, v113, v159, s10
	global_load_ushort v169, v[106:107], off offset:3072
	global_load_ushort v167, v[106:107], off offset:1536
	global_load_ushort v166, v[98:99], off offset:2560
	global_load_ushort v162, v[98:99], off offset:1024
	global_load_ushort v159, v[102:103], off offset:2048
	global_load_ushort v113, v[102:103], off offset:512
	s_nop 0
	global_load_ushort v107, v[22:23], off offset:1536
	global_load_ushort v106, v[22:23], off
	s_nop 0
	global_load_ushort v104, v[104:105], off offset:1024
	v_add_co_u32_e32 v22, vcc, s50, v0
	s_nop 1
	v_addc_co_u32_e32 v23, vcc, 0, v1, vcc
	global_load_ushort v103, v[22:23], off offset:3584
	global_load_ushort v102, v[22:23], off offset:512
	global_load_ushort v99, v[20:21], off offset:3072
	global_load_ushort v98, v[20:21], off
	s_nop 0
	global_load_ushort v21, v[100:101], off offset:2560
	global_load_ushort v20, v[18:19], off offset:3584
	s_nop 0
	global_load_ushort v19, v[18:19], off offset:2048
	s_waitcnt vmcnt(38)
	v_lshlrev_b32_e32 v18, 16, v171
	v_max_f32_e32 v18, v18, v18
	v_med3_f32 v18, v18, s9, v244
	v_mul_f32_e32 v18, 0xbfb8aa3b, v18
	v_exp_f32_e32 v18, v18
	ds_write_b16_d16_hi v17, v172 offset:3168
	ds_write_b16_d16_hi v17, v152 offset:7776
	v_add_f32_e32 v22, 1.0, v18
	v_rcp_f32_e32 v22, v22
	s_nop 0
	v_fma_f32 v23, v117, v22, v116
	v_mul_f32_e32 v18, v18, v22
	v_mul_f32_e32 v22, v173, v23
	v_max_f32_e32 v22, 0xda24260, v22
	v_rcp_f32_e32 v23, v22
	v_mul_f32_e32 v18, v117, v18
	v_mul_f32_e32 v18, v18, v23
	v_bfe_u32 v23, v18, 16, 1
	v_add3_u32 v23, v18, v23, s10
	s_waitcnt vmcnt(37)
	v_lshlrev_b32_e32 v18, 16, v170
	v_mul_f32_e32 v18, v22, v18
	v_bfe_u32 v100, v18, 16, 1
	v_add3_u32 v18, v18, v100, s10
	ds_write_b16_d16_hi v17, v18 offset:3024
	ds_write_b16_d16_hi v17, v23 offset:7632
	v_lshlrev_b32_e32 v18, 16, v168
	v_max_f32_e32 v18, v18, v18
	v_med3_f32 v18, v18, s9, v244
	v_mul_f32_e32 v18, 0xbfb8aa3b, v18
	v_exp_f32_e32 v18, v18
	s_nop 0
	v_add_f32_e32 v100, 1.0, v18
	v_rcp_f32_e32 v100, v100
	s_nop 0
	v_fma_f32 v101, v117, v100, v116
	v_mul_f32_e32 v22, v22, v101
	v_max_f32_e32 v22, 0xda24260, v22
	v_mul_f32_e32 v18, v18, v100
	v_rcp_f32_e32 v100, v22
	v_mul_f32_e32 v18, v117, v18
	v_mul_f32_e32 v18, v18, v100
	v_bfe_u32 v100, v18, 16, 1
	v_add3_u32 v18, v18, v100, s10
	v_lshlrev_b32_e32 v100, 16, v164
	v_mul_f32_e32 v100, v22, v100
	v_bfe_u32 v101, v100, 16, 1
	v_add3_u32 v100, v100, v101, s10
	ds_write_b16_d16_hi v17, v100 offset:2880
	ds_write_b16_d16_hi v17, v18 offset:7488
	s_waitcnt vmcnt(36)
	v_lshlrev_b32_e32 v100, 16, v165
	v_max_f32_e32 v100, v100, v100
	v_med3_f32 v100, v100, s9, v244
	v_mul_f32_e32 v100, 0xbfb8aa3b, v100
	v_exp_f32_e32 v100, v100
	s_nop 0
	v_add_f32_e32 v101, 1.0, v100
	v_rcp_f32_e32 v101, v101
	s_nop 0
	v_fma_f32 v105, v117, v101, v116
	v_mul_f32_e32 v22, v22, v105
	v_max_f32_e32 v22, 0xda24260, v22
	v_mul_f32_e32 v100, v100, v101
	v_rcp_f32_e32 v101, v22
	v_mul_f32_e32 v100, v117, v100
	v_mul_f32_e32 v100, v100, v101
	v_bfe_u32 v101, v100, 16, 1
	v_add3_u32 v101, v100, v101, s10
	s_waitcnt vmcnt(35)
	v_lshlrev_b32_e32 v100, 16, v163
	v_mul_f32_e32 v100, v22, v100
	v_bfe_u32 v105, v100, 16, 1
	v_add3_u32 v100, v100, v105, s10
	ds_write_b16_d16_hi v17, v100 offset:2736
	ds_write_b16_d16_hi v17, v101 offset:7344
	s_waitcnt vmcnt(34)
	v_lshlrev_b32_e32 v100, 16, v160
	v_max_f32_e32 v100, v100, v100
	v_med3_f32 v100, v100, s9, v244
	v_mul_f32_e32 v100, 0xbfb8aa3b, v100
	v_exp_f32_e32 v100, v100
	s_nop 0
	v_add_f32_e32 v105, 1.0, v100
	v_rcp_f32_e32 v105, v105
	s_nop 0
	v_fma_f32 v160, v117, v105, v116
	v_mul_f32_e32 v22, v22, v160
	v_mul_f32_e32 v100, v100, v105
	v_max_f32_e32 v105, 0xda24260, v22
	v_rcp_f32_e32 v22, v105
	v_mul_f32_e32 v100, v117, v100
	v_mul_f32_e32 v22, v100, v22
	v_bfe_u32 v100, v22, 16, 1
	v_add3_u32 v22, v22, v100, s10
	v_lshlrev_b32_e32 v100, 16, v158
	v_mul_f32_e32 v100, v105, v100
	v_bfe_u32 v158, v100, 16, 1
	v_add3_u32 v100, v100, v158, s10
	ds_write_b16_d16_hi v17, v100 offset:2592
	ds_write_b16_d16_hi v17, v22 offset:7200
	v_lshlrev_b32_e32 v100, 16, v115
	v_max_f32_e32 v100, v100, v100
	v_med3_f32 v100, v100, s9, v244
	v_mul_f32_e32 v100, 0xbfb8aa3b, v100
	v_exp_f32_e32 v100, v100
	s_nop 0
	v_add_f32_e32 v115, 1.0, v100
	v_rcp_f32_e32 v115, v115
	s_nop 0
	v_fma_f32 v158, v117, v115, v116
	v_mul_f32_e32 v105, v105, v158
	v_mul_f32_e32 v100, v100, v115
	v_max_f32_e32 v115, 0xda24260, v105
	v_rcp_f32_e32 v105, v115
	v_mul_f32_e32 v100, v117, v100
	v_mul_f32_e32 v100, v100, v105
	v_bfe_u32 v105, v100, 16, 1
	v_add3_u32 v105, v100, v105, s10
	s_waitcnt vmcnt(23)
	v_lshlrev_b32_e32 v100, 16, v157
	v_mul_f32_e32 v100, v115, v100
	v_bfe_u32 v157, v100, 16, 1
	v_add3_u32 v100, v100, v157, s10
	ds_write_b16_d16_hi v17, v100 offset:2448
	ds_write_b16_d16_hi v17, v105 offset:7056
	v_lshlrev_b32_e32 v100, 16, v111
	v_max_f32_e32 v100, v100, v100
	v_med3_f32 v100, v100, s9, v244
	v_mul_f32_e32 v100, 0xbfb8aa3b, v100
	v_exp_f32_e32 v100, v100
	s_nop 0
	v_add_f32_e32 v111, 1.0, v100
	v_rcp_f32_e32 v111, v111
	s_nop 0
	v_fma_f32 v157, v117, v111, v116
	v_mul_f32_e32 v100, v100, v111
	v_mul_f32_e32 v111, v115, v157
	v_max_f32_e32 v111, 0xda24260, v111
	v_rcp_f32_e32 v115, v111
	v_mul_f32_e32 v100, v117, v100
	v_mul_f32_e32 v109, v111, v109
	v_mul_f32_e32 v100, v100, v115
	v_bfe_u32 v115, v100, 16, 1
	v_add3_u32 v100, v100, v115, s10
	v_bfe_u32 v115, v109, 16, 1
	v_add3_u32 v109, v109, v115, s10
	ds_write_b16_d16_hi v17, v109 offset:2304
	ds_write_b16_d16_hi v17, v100 offset:6912
	s_waitcnt vmcnt(15)
	v_lshlrev_b32_e32 v109, 16, v169
	v_max_f32_e32 v109, v109, v109
	v_med3_f32 v109, v109, s9, v244
	v_mul_f32_e32 v109, 0xbfb8aa3b, v109
	v_exp_f32_e32 v109, v109
	s_nop 0
	v_add_f32_e32 v115, 1.0, v109
	v_rcp_f32_e32 v115, v115
	s_nop 0
	v_fma_f32 v157, v117, v115, v116
	v_mul_f32_e32 v111, v111, v157
	v_max_f32_e32 v111, 0xda24260, v111
	v_mul_f32_e32 v109, v109, v115
	v_rcp_f32_e32 v115, v111
	v_mul_f32_e32 v109, v117, v109
	v_mul_f32_e32 v109, v109, v115
	v_bfe_u32 v115, v109, 16, 1
	v_add3_u32 v109, v109, v115, s10
	s_waitcnt vmcnt(14)
	v_lshlrev_b32_e32 v115, 16, v167
	v_mul_f32_e32 v115, v111, v115
	v_bfe_u32 v157, v115, 16, 1
	v_add3_u32 v115, v115, v157, s10
	ds_write_b16_d16_hi v17, v115 offset:2160
	ds_write_b16_d16_hi v17, v109 offset:6768
	s_waitcnt vmcnt(13)
	v_lshlrev_b32_e32 v115, 16, v166
	v_max_f32_e32 v115, v115, v115
	v_med3_f32 v115, v115, s9, v244
	v_mul_f32_e32 v115, 0xbfb8aa3b, v115
	v_exp_f32_e32 v115, v115
	global_load_ushort v175, v[10:11], off offset:3072
	global_load_ushort v173, v[10:11], off offset:1536
	global_load_ushort v174, v[6:7], off offset:2560
	global_load_ushort v171, v[6:7], off offset:1024
	global_load_ushort v172, v[12:13], off offset:2048
	global_load_ushort v169, v[12:13], off offset:512
	global_load_ushort v170, v[4:5], off offset:1536
	global_load_ushort v166, v[4:5], off
	global_load_ushort v168, v[14:15], off offset:1024
	v_add_co_u32_e32 v4, vcc, s11, v0
	v_add_f32_e32 v157, 1.0, v115
	v_rcp_f32_e32 v157, v157
	v_addc_co_u32_e32 v5, vcc, 0, v1, vcc
	v_fma_f32 v158, v117, v157, v116
	v_mul_f32_e32 v111, v111, v158
	v_max_f32_e32 v111, 0xda24260, v111
	v_mul_f32_e32 v115, v115, v157
	v_rcp_f32_e32 v157, v111
	v_mul_f32_e32 v115, v117, v115
	v_mul_f32_e32 v115, v115, v157
	v_bfe_u32 v157, v115, 16, 1
	v_add3_u32 v157, v115, v157, s10
	s_waitcnt vmcnt(21)
	v_lshlrev_b32_e32 v115, 16, v162
	v_mul_f32_e32 v115, v111, v115
	v_bfe_u32 v158, v115, 16, 1
	v_add3_u32 v115, v115, v158, s10
	global_load_ushort v165, v[4:5], off offset:3584
	global_load_ushort v167, v[4:5], off offset:512
	global_load_ushort v163, v[2:3], off offset:3072
	global_load_ushort v164, v[2:3], off
	global_load_ushort v160, v[8:9], off offset:2560
	global_load_ushort v162, v[0:1], off offset:3584
	global_load_ushort v158, v[0:1], off offset:2048
	s_waitcnt vmcnt(27)
	v_lshlrev_b32_e32 v0, 16, v159
	v_max_f32_e32 v0, v0, v0
	v_med3_f32 v0, v0, s9, v244
	v_mul_f32_e32 v0, 0xbfb8aa3b, v0
	v_exp_f32_e32 v0, v0
	ds_write_b16_d16_hi v17, v115 offset:2016
	ds_write_b16_d16_hi v17, v157 offset:6624
	v_add_f32_e32 v1, 1.0, v0
	v_rcp_f32_e32 v1, v1
	s_nop 0
	v_fma_f32 v2, v117, v1, v116
	v_mul_f32_e32 v0, v0, v1
	v_mul_f32_e32 v1, v111, v2
	v_max_f32_e32 v1, 0xda24260, v1
	v_rcp_f32_e32 v2, v1
	v_mul_f32_e32 v0, v117, v0
	v_mul_f32_e32 v0, v0, v2
	v_bfe_u32 v2, v0, 16, 1
	v_add3_u32 v0, v0, v2, s10
	s_waitcnt vmcnt(26)
	v_lshlrev_b32_e32 v2, 16, v113
	v_mul_f32_e32 v2, v1, v2
	v_bfe_u32 v3, v2, 16, 1
	v_add3_u32 v2, v2, v3, s10
	ds_write_b16_d16_hi v17, v2 offset:1872
	ds_write_b16_d16_hi v17, v0 offset:6480
	s_waitcnt vmcnt(25)
	v_lshlrev_b32_e32 v2, 16, v107
	v_max_f32_e32 v2, v2, v2
	v_med3_f32 v2, v2, s9, v244
	v_mul_f32_e32 v2, 0xbfb8aa3b, v2
	v_exp_f32_e32 v2, v2
	s_nop 0
	v_add_f32_e32 v3, 1.0, v2
	v_rcp_f32_e32 v3, v3
	s_nop 0
	v_fma_f32 v4, v117, v3, v116
	v_mul_f32_e32 v1, v1, v4
	v_max_f32_e32 v1, 0xda24260, v1
	v_mul_f32_e32 v2, v2, v3
	v_rcp_f32_e32 v3, v1
	v_mul_f32_e32 v2, v117, v2
	v_mul_f32_e32 v2, v2, v3
	v_bfe_u32 v3, v2, 16, 1
	v_add3_u32 v159, v2, v3, s10
	s_waitcnt vmcnt(24)
	v_lshlrev_b32_e32 v2, 16, v106
	v_mul_f32_e32 v2, v1, v2
	v_bfe_u32 v3, v2, 16, 1
	v_add3_u32 v2, v2, v3, s10
	ds_write_b16_d16_hi v17, v2 offset:1728
	ds_write_b16_d16_hi v17, v159 offset:6336
	s_waitcnt vmcnt(23)
	v_lshlrev_b32_e32 v2, 16, v104
	v_max_f32_e32 v2, v2, v2
	v_med3_f32 v2, v2, s9, v244
	v_mul_f32_e32 v2, 0xbfb8aa3b, v2
	v_exp_f32_e32 v2, v2
	s_nop 0
	v_add_f32_e32 v3, 1.0, v2
	v_rcp_f32_e32 v3, v3
	s_nop 0
	v_fma_f32 v4, v117, v3, v116
	v_mul_f32_e32 v1, v1, v4
	v_max_f32_e32 v1, 0xda24260, v1
	v_mul_f32_e32 v2, v2, v3
	v_rcp_f32_e32 v3, v1
	v_mul_f32_e32 v2, v117, v2
	v_mul_f32_e32 v2, v2, v3
	v_bfe_u32 v3, v2, 16, 1
	v_add3_u32 v2, v2, v3, s10
	s_waitcnt vmcnt(22)
	v_lshlrev_b32_e32 v3, 16, v103
	v_mul_f32_e32 v3, v1, v3
	v_bfe_u32 v4, v3, 16, 1
	v_add3_u32 v3, v3, v4, s10
	ds_write_b16_d16_hi v17, v3 offset:1584
	ds_write_b16_d16_hi v17, v2 offset:6192
	s_waitcnt vmcnt(21)
	v_lshlrev_b32_e32 v3, 16, v102
	v_max_f32_e32 v3, v3, v3
	v_med3_f32 v3, v3, s9, v244
	v_mul_f32_e32 v3, 0xbfb8aa3b, v3
	v_exp_f32_e32 v3, v3
	s_nop 0
	v_add_f32_e32 v4, 1.0, v3
	v_rcp_f32_e32 v4, v4
	s_nop 0
	v_fma_f32 v5, v117, v4, v116
	v_mul_f32_e32 v1, v1, v5
	v_max_f32_e32 v1, 0xda24260, v1
	v_mul_f32_e32 v3, v3, v4
	v_rcp_f32_e32 v4, v1
	v_mul_f32_e32 v3, v117, v3
	v_mul_f32_e32 v3, v3, v4
	v_bfe_u32 v4, v3, 16, 1
	v_add3_u32 v102, v3, v4, s10
	s_waitcnt vmcnt(20)
	v_lshlrev_b32_e32 v3, 16, v99
	v_mul_f32_e32 v3, v1, v3
	v_bfe_u32 v4, v3, 16, 1
	v_add3_u32 v3, v3, v4, s10
	ds_write_b16_d16_hi v17, v3 offset:1440
	ds_write_b16_d16_hi v17, v102 offset:6048
	s_waitcnt vmcnt(19)
	v_lshlrev_b32_e32 v3, 16, v98
	v_max_f32_e32 v3, v3, v3
	v_med3_f32 v3, v3, s9, v244
	v_mul_f32_e32 v3, 0xbfb8aa3b, v3
	v_exp_f32_e32 v3, v3
	s_nop 0
	v_add_f32_e32 v4, 1.0, v3
	v_rcp_f32_e32 v4, v4
	s_nop 0
	v_fma_f32 v5, v117, v4, v116
	v_mul_f32_e32 v1, v1, v5
	v_max_f32_e32 v1, 0xda24260, v1
	v_mul_f32_e32 v3, v3, v4
	v_rcp_f32_e32 v4, v1
	v_mul_f32_e32 v3, v117, v3
	v_mul_f32_e32 v3, v3, v4
	v_bfe_u32 v4, v3, 16, 1
	v_add3_u32 v3, v3, v4, s10
	s_waitcnt vmcnt(18)
	v_lshlrev_b32_e32 v4, 16, v21
	v_mul_f32_e32 v4, v1, v4
	v_bfe_u32 v5, v4, 16, 1
	v_add3_u32 v4, v4, v5, s10
	ds_write_b16_d16_hi v17, v4 offset:1296
	ds_write_b16_d16_hi v17, v3 offset:5904
	s_waitcnt vmcnt(17)
	v_lshlrev_b32_e32 v4, 16, v20
	v_max_f32_e32 v4, v4, v4
	v_med3_f32 v4, v4, s9, v244
	v_mul_f32_e32 v4, 0xbfb8aa3b, v4
	v_exp_f32_e32 v4, v4
	s_nop 0
	v_add_f32_e32 v5, 1.0, v4
	v_rcp_f32_e32 v5, v5
	s_nop 0
	v_fma_f32 v6, v117, v5, v116
	v_mul_f32_e32 v1, v1, v6
	v_max_f32_e32 v12, 0xda24260, v1
	v_rcp_f32_e32 v1, v12
	v_mul_f32_e32 v4, v4, v5
	v_mul_f32_e32 v4, v117, v4
	v_mul_f32_e32 v1, v4, v1
	v_bfe_u32 v4, v1, 16, 1
	v_add3_u32 v20, v1, v4, s10
	s_waitcnt vmcnt(16)
	v_lshlrev_b32_e32 v1, 16, v19
	v_mul_f32_e32 v1, v12, v1
	v_bfe_u32 v4, v1, 16, 1
	v_add3_u32 v1, v1, v4, s10
	ds_write_b16_d16_hi v17, v1 offset:1152
	ds_write_b16_d16_hi v17, v20 offset:5760
	s_waitcnt vmcnt(15)
	v_lshlrev_b32_e32 v8, 16, v175
	v_max_f32_e32 v8, v8, v8
	v_med3_f32 v8, v8, s9, v244
	v_mul_f32_e32 v8, 0xbfb8aa3b, v8
	v_exp_f32_e32 v98, v8
	v_and_b32_e32 v113, 0xffff0000, v2
	v_lshl_or_b32 v2, v108, 16, v124
	v_and_b32_e32 v115, 0xffff0000, v3
	v_add_f32_e32 v13, 1.0, v98
	v_rcp_f32_e32 v104, v13
	v_lshl_or_b32 v3, v110, 16, v112
	v_lshl_or_b32 v11, v151, 16, v129
	v_and_b32_e32 v19, 0xffff0000, v114
	v_fma_f32 v106, v117, v104, v116
	v_mul_f32_e32 v12, v12, v106
	v_max_f32_e32 v106, 0xda24260, v12
	v_rcp_f32_e32 v108, v106
	v_mul_f32_e32 v98, v98, v104
	v_mul_f32_e32 v98, v117, v98
	v_lshl_or_b32 v7, v133, 16, v127
	v_mul_f32_e32 v98, v98, v108
	v_bfe_u32 v104, v98, 16, 1
	v_add3_u32 v98, v98, v104, s10
	s_waitcnt vmcnt(13)
	v_lshlrev_b32_e32 v104, 16, v174
	v_max_f32_e32 v104, v104, v104
	v_med3_f32 v104, v104, s9, v244
	v_mul_f32_e32 v104, 0xbfb8aa3b, v104
	v_exp_f32_e32 v104, v104
	v_lshlrev_b32_e32 v108, 16, v173
	v_mul_f32_e32 v108, v106, v108
	v_bfe_u32 v112, v108, 16, 1
	v_add_f32_e32 v110, 1.0, v104
	v_rcp_f32_e32 v110, v110
	v_add3_u32 v108, v108, v112, s10
	ds_write_b16_d16_hi v17, v108 offset:1008
	v_and_b32_e32 v129, 0xffff0000, v98
	v_fma_f32 v108, v117, v110, v116
	v_mul_f32_e32 v106, v106, v108
	v_max_f32_e32 v106, 0xda24260, v106
	v_rcp_f32_e32 v108, v106
	ds_write_b16_d16_hi v17, v98 offset:5616
	v_mul_f32_e32 v98, v104, v110
	v_mul_f32_e32 v98, v117, v98
	v_mul_f32_e32 v98, v98, v108
	s_waitcnt vmcnt(11)
	v_lshlrev_b32_e32 v108, 16, v172
	v_max_f32_e32 v108, v108, v108
	v_med3_f32 v108, v108, s9, v244
	v_mul_f32_e32 v108, 0xbfb8aa3b, v108
	v_exp_f32_e32 v108, v108
	v_bfe_u32 v104, v98, 16, 1
	v_add3_u32 v98, v98, v104, s10
	v_lshlrev_b32_e32 v104, 16, v171
	v_add_f32_e32 v110, 1.0, v108
	v_rcp_f32_e32 v110, v110
	v_mul_f32_e32 v104, v106, v104
	v_bfe_u32 v112, v104, 16, 1
	v_add3_u32 v104, v104, v112, s10
	ds_write_b16_d16_hi v17, v104 offset:864
	v_fma_f32 v104, v117, v110, v116
	v_mul_f32_e32 v104, v106, v104
	v_max_f32_e32 v104, 0xda24260, v104
	v_rcp_f32_e32 v106, v104
	v_mul_f32_e32 v108, v108, v110
	v_mul_f32_e32 v108, v117, v108
	s_waitcnt vmcnt(10)
	v_lshlrev_b32_e32 v110, 16, v169
	v_mul_f32_e32 v106, v108, v106
	v_bfe_u32 v108, v106, 16, 1
	v_add3_u32 v106, v106, v108, s10
	s_waitcnt vmcnt(9)
	v_lshlrev_b32_e32 v108, 16, v170
	v_max_f32_e32 v108, v108, v108
	v_med3_f32 v108, v108, s9, v244
	v_mul_f32_e32 v108, 0xbfb8aa3b, v108
	v_exp_f32_e32 v108, v108
	v_mul_f32_e32 v110, v104, v110
	v_bfe_u32 v114, v110, 16, 1
	v_add3_u32 v110, v110, v114, s10
	v_add_f32_e32 v112, 1.0, v108
	v_rcp_f32_e32 v112, v112
	ds_write_b16_d16_hi v17, v110 offset:720
	v_and_b32_e32 v127, 0xffff0000, v106
	ds_write_b16_d16_hi v17, v106 offset:5328
	v_fma_f32 v110, v117, v112, v116
	v_mul_f32_e32 v104, v104, v110
	v_max_f32_e32 v104, 0xda24260, v104
	v_rcp_f32_e32 v110, v104
	v_mul_f32_e32 v106, v108, v112
	v_mul_f32_e32 v106, v117, v106
	v_lshl_or_b32 v1, v135, 16, v123
	v_mul_f32_e32 v106, v106, v110
	s_waitcnt vmcnt(7)
	v_lshlrev_b32_e32 v110, 16, v168
	v_max_f32_e32 v110, v110, v110
	v_med3_f32 v110, v110, s9, v244
	v_mul_f32_e32 v110, 0xbfb8aa3b, v110
	v_exp_f32_e32 v110, v110
	v_bfe_u32 v108, v106, 16, 1
	v_add3_u32 v106, v106, v108, s10
	v_lshlrev_b32_e32 v108, 16, v166
	v_add_f32_e32 v112, 1.0, v110
	v_rcp_f32_e32 v112, v112
	v_mul_f32_e32 v108, v104, v108
	v_bfe_u32 v114, v108, 16, 1
	v_add3_u32 v108, v108, v114, s10
	ds_write_b16_d16_hi v17, v108 offset:576
	v_fma_f32 v108, v117, v112, v116
	v_mul_f32_e32 v104, v104, v108
	v_max_f32_e32 v104, 0xda24260, v104
	v_rcp_f32_e32 v108, v104
	v_mul_f32_e32 v110, v110, v112
	v_mul_f32_e32 v110, v117, v110
	s_waitcnt vmcnt(6)
	v_lshlrev_b32_e32 v112, 16, v165
	v_mul_f32_e32 v108, v110, v108
	v_bfe_u32 v110, v108, 16, 1
	v_add3_u32 v108, v108, v110, s10
	s_waitcnt vmcnt(5)
	v_lshlrev_b32_e32 v110, 16, v167
	v_max_f32_e32 v110, v110, v110
	v_med3_f32 v110, v110, s9, v244
	v_mul_f32_e32 v110, 0xbfb8aa3b, v110
	v_exp_f32_e32 v110, v110
	v_mul_f32_e32 v112, v104, v112
	v_bfe_u32 v123, v112, 16, 1
	v_add3_u32 v112, v112, v123, s10
	v_add_f32_e32 v114, 1.0, v110
	v_rcp_f32_e32 v114, v114
	ds_write_b16_d16_hi v17, v112 offset:432
	v_lshl_or_b32 v5, v137, 16, v131
	v_and_b32_e32 v131, 0xffff0000, v108
	v_fma_f32 v112, v117, v114, v116
	v_mul_f32_e32 v104, v104, v112
	v_max_f32_e32 v104, 0xda24260, v104
	v_rcp_f32_e32 v112, v104
	ds_write_b16_d16_hi v17, v108 offset:5040
	v_mul_f32_e32 v108, v110, v114
	v_mul_f32_e32 v108, v117, v108
	v_mul_f32_e32 v108, v108, v112
	s_waitcnt vmcnt(3)
	v_lshlrev_b32_e32 v112, 16, v164
	v_max_f32_e32 v112, v112, v112
	v_med3_f32 v112, v112, s9, v244
	v_mul_f32_e32 v112, 0xbfb8aa3b, v112
	v_exp_f32_e32 v112, v112
	v_bfe_u32 v110, v108, 16, 1
	v_add3_u32 v108, v108, v110, s10
	v_lshlrev_b32_e32 v110, 16, v163
	v_add_f32_e32 v114, 1.0, v112
	v_rcp_f32_e32 v114, v114
	v_mul_f32_e32 v110, v104, v110
	v_bfe_u32 v123, v110, 16, 1
	v_add3_u32 v110, v110, v123, s10
	ds_write_b16_d16_hi v17, v110 offset:288
	v_fma_f32 v110, v117, v114, v116
	v_mul_f32_e32 v104, v104, v110
	v_max_f32_e32 v104, 0xda24260, v104
	v_rcp_f32_e32 v110, v104
	v_mul_f32_e32 v112, v112, v114
	v_mul_f32_e32 v112, v117, v112
	s_waitcnt vmcnt(2)
	v_lshlrev_b32_e32 v114, 16, v160
	v_mul_f32_e32 v110, v112, v110
	v_bfe_u32 v112, v110, 16, 1
	v_add3_u32 v110, v110, v112, s10
	s_waitcnt vmcnt(1)
	v_lshlrev_b32_e32 v112, 16, v162
	v_max_f32_e32 v112, v112, v112
	v_med3_f32 v112, v112, s9, v244
	v_mul_f32_e32 v112, 0xbfb8aa3b, v112
	v_exp_f32_e32 v112, v112
	v_mul_f32_e32 v114, v104, v114
	v_bfe_u32 v124, v114, 16, 1
	v_add3_u32 v114, v114, v124, s10
	v_add_f32_e32 v123, 1.0, v112
	v_rcp_f32_e32 v123, v123
	ds_write_b16_d16_hi v17, v114 offset:144
	v_lshl_or_b32 v12, v145, 16, v132
	v_lshl_or_b32 v6, v139, 16, v125
	v_fma_f32 v114, v117, v123, v116
	v_mul_f32_e32 v104, v104, v114
	v_max_f32_e32 v132, 0xda24260, v104
	v_rcp_f32_e32 v104, v132
	v_and_b32_e32 v125, 0xffff0000, v110
	ds_write_b16_d16_hi v17, v110 offset:4752
	v_mul_f32_e32 v110, v112, v123
	v_mul_f32_e32 v110, v117, v110
	v_mul_f32_e32 v104, v110, v104
	v_bfe_u32 v110, v104, 16, 1
	v_add3_u32 v104, v104, v110, s10
	s_waitcnt vmcnt(0)
	v_lshlrev_b32_e32 v110, 16, v158
	v_mul_f32_e32 v110, v132, v110
	v_bfe_u32 v112, v110, 16, 1
	v_add3_u32 v110, v110, v112, s10
	v_and_b32_e32 v111, 0xffff0000, v0
	v_and_b32_e32 v109, 0xffff0000, v109
	v_and_b32_e32 v107, 0xffff0000, v105
	v_and_b32_e32 v105, 0xffff0000, v101
	v_and_b32_e32 v103, 0xffff0000, v23
	v_and_b32_e32 v101, 0xffff0000, v156
	v_and_b32_e32 v99, 0xffff0000, v155
	v_and_b32_e32 v23, 0xffff0000, v154
	v_and_b32_e32 v21, 0xffff0000, v153
	v_lshl_or_b32 v0, v134, 16, v128
	v_lshl_or_b32 v4, v150, 16, v130
	v_lshl_or_b32 v10, v149, 16, v126
	v_lshl_or_b32 v9, v144, 16, v143
	v_lshl_or_b32 v8, v148, 16, v141
	v_lshl_or_b32 v15, v146, 16, v140
	v_lshl_or_b32 v14, v147, 16, v138
	v_lshl_or_b32 v13, v142, 16, v136
	ds_write_b16_d16_hi v17, v98 offset:5472
	ds_write_b16_d16_hi v17, v106 offset:5184
	ds_write_b16_d16_hi v17, v108 offset:4896
	ds_write_b16_d16_hi v17, v110
	ds_write_b16_d16_hi v17, v104 offset:4608
	v_and_b32_e32 v124, 0xffff0000, v104
	v_and_b32_e32 v130, 0xffff0000, v108
	v_and_b32_e32 v126, 0xffff0000, v106
	v_and_b32_e32 v128, 0xffff0000, v98
	s_movk_i32 s0, 0x50
	v_pk_mul_f32 v[124:125], v[132:133], v[124:125] op_sel_hi:[0,1]
	v_pk_mul_f32 v[130:131], v[132:133], v[130:131] op_sel_hi:[0,1]
	v_pk_mul_f32 v[126:127], v[132:133], v[126:127] op_sel_hi:[0,1]
	v_pk_mul_f32 v[128:129], v[132:133], v[128:129] op_sel_hi:[0,1]
	v_and_b32_e32 v114, 0xffff0000, v20
	v_and_b32_e32 v112, 0xffff0000, v102
	v_and_b32_e32 v110, 0xffff0000, v159
	v_and_b32_e32 v108, 0xffff0000, v157
	v_and_b32_e32 v106, 0xffff0000, v100
	v_and_b32_e32 v104, 0xffff0000, v22
	v_and_b32_e32 v102, 0xffff0000, v18
	v_and_b32_e32 v100, 0xffff0000, v152
	v_and_b32_e32 v98, 0xffff0000, v122
	v_and_b32_e32 v22, 0xffff0000, v121
	v_and_b32_e32 v20, 0xffff0000, v120
	v_and_b32_e32 v18, 0xffff0000, v88
	v_mad_u64_u32 v[134:135], s[2:3], v16, s0, v[92:93]
	v_cvt_pk_bf16_f32 v124, v124, v125
	v_cvt_pk_bf16_f32 v125, v130, v131
	v_cvt_pk_bf16_f32 v126, v126, v127
	v_cvt_pk_bf16_f32 v127, v128, v129
	v_pk_mul_f32 v[114:115], v[132:133], v[114:115] op_sel_hi:[0,1]
	v_pk_mul_f32 v[112:113], v[132:133], v[112:113] op_sel_hi:[0,1]
	v_pk_mul_f32 v[110:111], v[132:133], v[110:111] op_sel_hi:[0,1]
	v_pk_mul_f32 v[108:109], v[132:133], v[108:109] op_sel_hi:[0,1]
	v_pk_mul_f32 v[106:107], v[132:133], v[106:107] op_sel_hi:[0,1]
	v_pk_mul_f32 v[104:105], v[132:133], v[104:105] op_sel_hi:[0,1]
	v_pk_mul_f32 v[102:103], v[132:133], v[102:103] op_sel_hi:[0,1]
	v_pk_mul_f32 v[100:101], v[132:133], v[100:101] op_sel_hi:[0,1]
	v_pk_mul_f32 v[98:99], v[132:133], v[98:99] op_sel_hi:[0,1]
	v_pk_mul_f32 v[22:23], v[132:133], v[22:23] op_sel_hi:[0,1]
	v_pk_mul_f32 v[20:21], v[132:133], v[20:21] op_sel_hi:[0,1]
	v_pk_mul_f32 v[18:19], v[132:133], v[18:19] op_sel_hi:[0,1]
	ds_write_b128 v134, v[124:127] offset:9216
	v_cvt_pk_bf16_f32 v124, v114, v115
	v_cvt_pk_bf16_f32 v125, v112, v113
	v_cvt_pk_bf16_f32 v126, v110, v111
	v_cvt_pk_bf16_f32 v127, v108, v109
	v_cvt_pk_bf16_f32 v106, v106, v107
	v_cvt_pk_bf16_f32 v107, v104, v105
	v_cvt_pk_bf16_f32 v108, v102, v103
	v_cvt_pk_bf16_f32 v109, v100, v101
	v_cvt_pk_bf16_f32 v98, v98, v99
	v_cvt_pk_bf16_f32 v99, v22, v23
	v_cvt_pk_bf16_f32 v100, v20, v21
	v_cvt_pk_bf16_f32 v101, v18, v19
	v_lshl_add_u32 v16, v16, 2, v92
	ds_write_b128 v134, v[124:127] offset:9232
	ds_write_b128 v134, v[106:109] offset:9248
	ds_write_b128 v134, v[98:101] offset:9264
	ds_write_b32 v16, v132 offset:19456
	ds_write_b128 v134, v[12:15] offset:14336
	ds_write_b128 v134, v[8:11] offset:14352
	ds_write_b128 v134, v[4:7] offset:14368
	ds_write_b128 v134, v[0:3] offset:14384
	s_waitcnt lgkmcnt(0)
	v_or_b32_e32 v88, v95, v118
	v_lshlrev_b64 v[0:1], 11, v[88:89]
	v_lshlrev_b32_e32 v100, 2, v119
	v_lshl_add_u64 v[0:1], s[40:41], 0, v[0:1]
	v_ashrrev_i32_e32 v101, 31, v100
	v_mad_u32_u24 v106, v118, s48, v92
	v_lshlrev_b32_e32 v95, 4, v119
	v_lshl_add_u64 v[0:1], v[0:1], 0, v[90:91]
	v_lshlrev_b64 v[102:103], 1, v[100:101]
	v_add_u32_e32 v107, v106, v95
	v_lshl_add_u64 v[104:105], v[0:1], 0, v[102:103]
	ds_read_b128 v[0:3], v107 offset:4608
	ds_read_b128 v[4:7], v107
	ds_read_b128 v[16:19], v107 offset:32
	ds_read_b128 v[20:23], v107 offset:4640
	s_waitcnt lgkmcnt(2)
	v_mfma_f32_32x32x16_bf16 v[0:15], v[0:3], v[4:7], 0
	v_cmp_ge_i32_e32 vcc, v100, v118
	v_cvt_pk_bf16_f32 v120, v32, v33
	v_cvt_pk_bf16_f32 v121, v34, v35
	v_cvt_pk_bf16_f32 v122, v36, v37
	v_cvt_pk_bf16_f32 v123, v38, v39
	v_lshl_add_u64 v[98:99], v[104:105], 0, s[4:5]
	s_waitcnt lgkmcnt(0)
	v_mfma_f32_32x32x16_bf16 v[0:15], v[20:23], v[16:19], v[0:15]
	ds_read_b128 v[16:19], v107 offset:4672
	ds_read_b128 v[20:23], v107 offset:64
	s_waitcnt lgkmcnt(0)
	v_mfma_f32_32x32x16_bf16 v[0:15], v[16:19], v[20:23], v[0:15]
	ds_read_b128 v[16:19], v107 offset:4704
	ds_read_b128 v[20:23], v107 offset:96
	s_waitcnt lgkmcnt(0)
	v_mfma_f32_32x32x16_bf16 v[0:15], v[16:19], v[20:23], v[0:15]
	v_or_b32_e32 v16, 1, v100
	s_nop 10
	v_cndmask_b32_e32 v0, 0, v0, vcc
	v_cmp_ge_i32_e32 vcc, v16, v118
	v_or_b32_e32 v16, 2, v100
	s_nop 0
	v_cndmask_b32_e32 v1, 0, v1, vcc
	v_cmp_ge_i32_e32 vcc, v16, v118
	v_or_b32_e32 v16, 3, v100
	s_nop 0
	v_cndmask_b32_e32 v2, 0, v2, vcc
	v_cmp_ge_i32_e32 vcc, v16, v118
	v_add_u32_e32 v16, 8, v100
	s_nop 0
	v_cndmask_b32_e32 v3, 0, v3, vcc
	v_cmp_ge_i32_e32 vcc, v16, v118
	v_add_u32_e32 v16, 9, v100
	v_cvt_pk_bf16_f32 v17, v2, v3
	v_cndmask_b32_e32 v4, 0, v4, vcc
	v_cmp_ge_i32_e32 vcc, v16, v118
	v_add_u32_e32 v16, 10, v100
	s_nop 0
	v_cndmask_b32_e32 v5, 0, v5, vcc
	v_cmp_ge_i32_e32 vcc, v16, v118
	v_add_u32_e32 v16, 11, v100
	v_cvt_pk_bf16_f32 v18, v4, v5
	v_cndmask_b32_e32 v6, 0, v6, vcc
	v_cmp_ge_i32_e32 vcc, v16, v118
	v_add_u32_e32 v16, 16, v100
	s_nop 0
	v_cndmask_b32_e32 v7, 0, v7, vcc
	v_cmp_ge_i32_e32 vcc, v16, v118
	v_add_u32_e32 v16, 17, v100
	v_cvt_pk_bf16_f32 v19, v6, v7
	v_cndmask_b32_e32 v8, 0, v8, vcc
	v_cmp_ge_i32_e32 vcc, v16, v118
	v_add_u32_e32 v16, 18, v100
	s_nop 0
	v_cndmask_b32_e32 v9, 0, v9, vcc
	v_cmp_ge_i32_e32 vcc, v16, v118
	v_add_u32_e32 v16, 19, v100
	v_cvt_pk_bf16_f32 v20, v8, v9
	v_cndmask_b32_e32 v10, 0, v10, vcc
	v_cmp_ge_i32_e32 vcc, v16, v118
	v_add_u32_e32 v16, 24, v100
	s_nop 0
	v_cndmask_b32_e32 v11, 0, v11, vcc
	v_cmp_ge_i32_e32 vcc, v16, v118
	v_add_u32_e32 v16, 25, v100
	v_cvt_pk_bf16_f32 v21, v10, v11
	v_cndmask_b32_e32 v12, 0, v12, vcc
	v_cmp_ge_i32_e32 vcc, v16, v118
	v_add_u32_e32 v16, 26, v100
	s_nop 0
	v_cndmask_b32_e32 v13, 0, v13, vcc
	v_cmp_ge_i32_e32 vcc, v16, v118
	v_add_u32_e32 v16, 27, v100
	v_cvt_pk_bf16_f32 v22, v12, v13
	v_cndmask_b32_e32 v14, 0, v14, vcc
	v_cmp_ge_i32_e32 vcc, v16, v118
	v_cvt_pk_bf16_f32 v16, v0, v1
	v_lshlrev_b32_e32 v0, 3, v119
	v_mul_u32_u24_e32 v1, 0x50, v118
	v_add3_u32 v107, v92, v0, v1
	v_add_u32_e32 v4, 0x3800, v107
	v_add_u32_e32 v106, v106, v0
	ds_read2_b64 v[0:3], v4 offset1:2
	ds_read2_b64 v[108:111], v4 offset0:4 offset1:6
	v_cndmask_b32_e32 v15, 0, v15, vcc
	v_cvt_pk_bf16_f32 v23, v14, v15
	s_waitcnt lgkmcnt(1)
	v_mfma_f32_32x32x16_bf16 v[0:15], v[0:3], v[16:19], 0
	v_add_co_u32_e32 v104, vcc, s6, v104
	s_nop 1
	v_addc_co_u32_e32 v105, vcc, 0, v105, vcc
	s_waitcnt lgkmcnt(0)
	v_mfma_f32_32x32x16_bf16 v[0:15], v[108:111], v[20:23], v[0:15]
	ds_read2_b64 v[108:111], v106 offset1:2
	ds_read2_b64 v[112:115], v106 offset0:4 offset1:6
	s_waitcnt lgkmcnt(1)
	v_mfma_f32_32x32x16_bf16 v[0:15], v[120:123], v[108:111], v[0:15]
	v_cvt_pk_bf16_f32 v108, v40, v41
	v_cvt_pk_bf16_f32 v109, v42, v43
	v_cvt_pk_bf16_f32 v110, v44, v45
	v_cvt_pk_bf16_f32 v111, v46, v47
	s_waitcnt lgkmcnt(0)
	s_nop 0
	v_mfma_f32_32x32x16_bf16 v[0:15], v[108:111], v[112:115], v[0:15]
	ds_read2_b64 v[108:111], v106 offset0:8 offset1:10
	v_cvt_pk_bf16_f32 v112, v54, v55
	v_cvt_pk_bf16_f32 v113, v50, v51
	v_cvt_pk_bf16_f32 v114, v52, v53
	v_cvt_pk_bf16_f32 v115, v82, v83
	s_waitcnt lgkmcnt(0)
	s_nop 0
	v_mfma_f32_32x32x16_bf16 v[0:15], v[112:115], v[108:111], v[0:15]
	ds_read2_b64 v[108:111], v106 offset0:12 offset1:14
	v_cvt_pk_bf16_f32 v112, v56, v57
	v_cvt_pk_bf16_f32 v113, v58, v59
	v_cvt_pk_bf16_f32 v114, v60, v61
	v_cvt_pk_bf16_f32 v115, v62, v63
	s_waitcnt lgkmcnt(0)
	s_nop 0
	v_mfma_f32_32x32x16_bf16 v[0:15], v[112:115], v[108:111], v[0:15]
	global_load_dwordx2 v[108:109], v[104:105], off offset:1536
	s_waitcnt vmcnt(0)
	v_lshlrev_b32_e32 v110, 16, v108
	v_and_b32_e32 v111, 0xffff0000, v108
	s_nop 7
	v_pk_add_f32 v[0:1], v[0:1], v[110:111]
	v_lshlrev_b32_e32 v108, 16, v109
	v_and_b32_e32 v109, 0xffff0000, v109
	v_pk_add_f32 v[2:3], v[2:3], v[108:109]
	v_mul_f32_e32 v108, v1, v1
	v_pk_fma_f32 v[108:109], v[0:1], v[0:1], v[108:109] op_sel_hi:[1,1,0]
	v_cvt_pk_bf16_f32 v0, v0, v1
	v_cvt_pk_bf16_f32 v1, v2, v3
	global_store_dwordx2 v[104:105], v[0:1], off offset:1536
	global_load_dwordx2 v[0:1], v[98:99], off offset:16
	v_mul_f32_e32 v110, v3, v3
	v_pk_fma_f32 v[110:111], v[2:3], v[2:3], v[110:111] op_sel_hi:[1,1,0]
	s_waitcnt vmcnt(0)
	v_lshlrev_b32_e32 v2, 16, v0
	v_and_b32_e32 v3, 0xffff0000, v0
	v_lshlrev_b32_e32 v0, 16, v1
	v_and_b32_e32 v1, 0xffff0000, v1
	v_pk_add_f32 v[2:3], v[4:5], v[2:3]
	v_pk_add_f32 v[0:1], v[6:7], v[0:1]
	v_mul_f32_e32 v4, v3, v3
	v_mul_f32_e32 v6, v1, v1
	v_pk_fma_f32 v[4:5], v[2:3], v[2:3], v[4:5] op_sel_hi:[1,1,0]
	v_pk_fma_f32 v[6:7], v[0:1], v[0:1], v[6:7] op_sel_hi:[1,1,0]
	v_cvt_pk_bf16_f32 v2, v2, v3
	v_cvt_pk_bf16_f32 v3, v0, v1
	global_load_dwordx2 v[0:1], v[98:99], off offset:32
	v_pk_add_f32 v[4:5], v[4:5], v[6:7]
	global_store_dwordx2 v[98:99], v[2:3], off offset:16
	v_pk_add_f32 v[108:109], v[108:109], v[110:111]
	s_waitcnt vmcnt(1)
	v_lshlrev_b32_e32 v2, 16, v0
	v_and_b32_e32 v3, 0xffff0000, v0
	v_pk_add_f32 v[2:3], v[8:9], v[2:3]
	v_lshlrev_b32_e32 v0, 16, v1
	v_and_b32_e32 v1, 0xffff0000, v1
	v_pk_add_f32 v[6:7], v[10:11], v[0:1]
	v_mul_f32_e32 v0, v3, v3
	v_pk_fma_f32 v[0:1], v[2:3], v[2:3], v[0:1] op_sel_hi:[1,1,0]
	v_cvt_pk_bf16_f32 v2, v2, v3
	v_cvt_pk_bf16_f32 v3, v6, v7
	global_store_dwordx2 v[98:99], v[2:3], off offset:32
	global_load_dwordx2 v[2:3], v[98:99], off offset:48
	v_mul_f32_e32 v8, v7, v7
	v_pk_fma_f32 v[8:9], v[6:7], v[6:7], v[8:9] op_sel_hi:[1,1,0]
	v_pk_add_f32 v[4:5], v[108:109], v[4:5]
	v_pk_add_f32 v[0:1], v[0:1], v[8:9]
	s_nop 0
	v_pk_add_f32 v[0:1], v[4:5], v[0:1]
	s_waitcnt vmcnt(0)
	v_lshlrev_b32_e32 v4, 16, v2
	v_and_b32_e32 v5, 0xffff0000, v2
	v_lshlrev_b32_e32 v2, 16, v3
	v_and_b32_e32 v3, 0xffff0000, v3
	v_pk_add_f32 v[4:5], v[12:13], v[4:5]
	v_pk_add_f32 v[2:3], v[14:15], v[2:3]
	v_mul_f32_e32 v6, v5, v5
	v_mul_f32_e32 v8, v3, v3
	v_pk_fma_f32 v[6:7], v[4:5], v[4:5], v[6:7] op_sel_hi:[1,1,0]
	v_pk_fma_f32 v[8:9], v[2:3], v[2:3], v[8:9] op_sel_hi:[1,1,0]
	s_nop 0
	v_pk_add_f32 v[6:7], v[6:7], v[8:9]
	s_nop 0
	v_pk_add_f32 v[112:113], v[0:1], v[6:7]
	v_cvt_pk_bf16_f32 v0, v4, v5
	v_cvt_pk_bf16_f32 v1, v2, v3
	global_store_dwordx2 v[98:99], v[0:1], off offset:48
	v_add_u32_e32 v4, 0x4000, v107
	ds_read2_b64 v[0:3], v4 offset0:64 offset1:66
	ds_read2_b64 v[108:111], v4 offset0:68 offset1:70
	s_waitcnt lgkmcnt(1)
	v_mfma_f32_32x32x16_bf16 v[0:15], v[0:3], v[16:19], 0
	s_waitcnt lgkmcnt(0)
	v_mfma_f32_32x32x16_bf16 v[0:15], v[108:111], v[20:23], v[0:15]
	v_cvt_pk_bf16_f32 v108, v26, v27
	v_cvt_pk_bf16_f32 v109, v28, v29
	v_cvt_pk_bf16_f32 v110, v30, v31
	v_cvt_pk_bf16_f32 v111, v48, v49
	ds_read2_b64 v[16:19], v106 offset1:2
	ds_read2_b64 v[20:23], v106 offset0:4 offset1:6
	s_waitcnt lgkmcnt(1)
	v_mfma_f32_32x32x16_bf16 v[0:15], v[108:111], v[16:19], v[0:15]
	v_cvt_pk_bf16_f32 v16, v24, v25
	v_cvt_pk_bf16_f32 v17, v84, v85
	v_cvt_pk_bf16_f32 v18, v86, v87
	v_cvt_pk_bf16_f32 v19, v96, v97
	s_waitcnt lgkmcnt(0)
	s_nop 0
	v_mfma_f32_32x32x16_bf16 v[0:15], v[16:19], v[20:23], v[0:15]
	ds_read2_b64 v[16:19], v106 offset0:8 offset1:10
	v_cvt_pk_bf16_f32 v20, v66, v67
	v_cvt_pk_bf16_f32 v21, v68, v69
	v_cvt_pk_bf16_f32 v22, v70, v71
	v_cvt_pk_bf16_f32 v23, v72, v73
	s_waitcnt lgkmcnt(0)
	s_nop 0
	v_mfma_f32_32x32x16_bf16 v[0:15], v[20:23], v[16:19], v[0:15]
	ds_read2_b64 v[16:19], v106 offset0:12 offset1:14
	v_cvt_pk_bf16_f32 v20, v74, v75
	v_cvt_pk_bf16_f32 v21, v76, v77
	v_cvt_pk_bf16_f32 v22, v78, v79
	v_cvt_pk_bf16_f32 v23, v80, v81
	s_waitcnt lgkmcnt(0)
	s_nop 0
	v_mfma_f32_32x32x16_bf16 v[0:15], v[20:23], v[16:19], v[0:15]
	global_load_dwordx2 v[16:17], v[98:99], off offset:64
	s_waitcnt vmcnt(0)
	v_lshlrev_b32_e32 v18, 16, v16
	v_and_b32_e32 v19, 0xffff0000, v16
	s_nop 7
	v_pk_add_f32 v[0:1], v[0:1], v[18:19]
	v_lshlrev_b32_e32 v16, 16, v17
	v_and_b32_e32 v17, 0xffff0000, v17
	v_pk_add_f32 v[2:3], v[2:3], v[16:17]
	v_mul_f32_e32 v16, v1, v1
	v_pk_fma_f32 v[16:17], v[0:1], v[0:1], v[16:17] op_sel_hi:[1,1,0]
	v_cvt_pk_bf16_f32 v0, v0, v1
	v_cvt_pk_bf16_f32 v1, v2, v3
	global_store_dwordx2 v[98:99], v[0:1], off offset:64
	global_load_dwordx2 v[0:1], v[98:99], off offset:80
	v_mul_f32_e32 v18, v3, v3
	v_pk_fma_f32 v[18:19], v[2:3], v[2:3], v[18:19] op_sel_hi:[1,1,0]
	s_waitcnt vmcnt(0)
	v_lshlrev_b32_e32 v2, 16, v0
	v_and_b32_e32 v3, 0xffff0000, v0
	v_lshlrev_b32_e32 v0, 16, v1
	v_and_b32_e32 v1, 0xffff0000, v1
	v_pk_add_f32 v[2:3], v[4:5], v[2:3]
	v_pk_add_f32 v[0:1], v[6:7], v[0:1]
	v_mul_f32_e32 v4, v3, v3
	v_mul_f32_e32 v6, v1, v1
	v_pk_fma_f32 v[4:5], v[2:3], v[2:3], v[4:5] op_sel_hi:[1,1,0]
	v_pk_fma_f32 v[6:7], v[0:1], v[0:1], v[6:7] op_sel_hi:[1,1,0]
	v_cvt_pk_bf16_f32 v2, v2, v3
	v_cvt_pk_bf16_f32 v3, v0, v1
	global_load_dwordx2 v[0:1], v[98:99], off offset:96
	v_pk_add_f32 v[4:5], v[4:5], v[6:7]
	global_store_dwordx2 v[98:99], v[2:3], off offset:80
	v_pk_add_f32 v[16:17], v[16:17], v[18:19]
	s_waitcnt vmcnt(1)
	v_lshlrev_b32_e32 v2, 16, v0
	v_and_b32_e32 v3, 0xffff0000, v0
	v_lshlrev_b32_e32 v0, 16, v1
	v_and_b32_e32 v1, 0xffff0000, v1
	v_pk_add_f32 v[2:3], v[8:9], v[2:3]
	v_pk_add_f32 v[6:7], v[10:11], v[0:1]
	v_mov_b32_e32 v0, v2
	v_mov_b32_e32 v8, v3
	v_cvt_pk_bf16_f32 v2, v2, v3
	v_cvt_pk_bf16_f32 v3, v6, v7
	global_store_dwordx2 v[98:99], v[2:3], off offset:96
	global_load_dwordx2 v[2:3], v[98:99], off offset:112
	v_mov_b32_e32 v9, v7
	v_mov_b32_e32 v1, v6
	v_pk_mul_f32 v[8:9], v[8:9], v[8:9]
	v_pk_add_f32 v[16:17], v[112:113], v[16:17]
	v_pk_fma_f32 v[0:1], v[0:1], v[0:1], v[8:9]
	v_pk_add_f32 v[4:5], v[16:17], v[4:5]
	v_pk_add_f32 v[0:1], v[0:1], v[0:1] op_sel:[0,1] op_sel_hi:[1,0]
	s_nop 0
	v_pk_add_f32 v[0:1], v[4:5], v[0:1]
	s_waitcnt vmcnt(0)
	v_lshlrev_b32_e32 v4, 16, v2
	v_and_b32_e32 v5, 0xffff0000, v2
	v_lshlrev_b32_e32 v2, 16, v3
	v_and_b32_e32 v3, 0xffff0000, v3
	v_pk_add_f32 v[4:5], v[12:13], v[4:5]
	v_pk_add_f32 v[2:3], v[14:15], v[2:3]
	v_mov_b32_e32 v8, v5
	v_mov_b32_e32 v9, v3
	v_mov_b32_e32 v6, v4
	v_mov_b32_e32 v7, v2
	v_pk_mul_f32 v[8:9], v[8:9], v[8:9]
	s_nop 0
	v_pk_fma_f32 v[6:7], v[6:7], v[6:7], v[8:9]
	s_nop 0
	v_pk_add_f32 v[6:7], v[6:7], v[6:7] op_sel:[0,1] op_sel_hi:[1,0]
	s_nop 0
	v_pk_add_f32 v[114:115], v[0:1], v[6:7]
	v_cvt_pk_bf16_f32 v0, v4, v5
	v_cvt_pk_bf16_f32 v1, v2, v3
	global_store_dwordx2 v[98:99], v[0:1], off offset:112
	v_add_u32_e32 v95, v92, v95
	v_mad_u32_u24 v115, v118, s0, v95
	ds_read_b128 v[0:3], v95 offset:19456
	ds_read_b128 v[4:7], v95 offset:19488
	ds_read_b128 v[8:11], v95 offset:19520
	ds_read_b128 v[12:15], v95 offset:19552
	ds_read_b128 v[16:19], v115 offset:9216
	ds_read_b128 v[20:23], v115 offset:14336
	ds_read_b128 v[106:109], v115 offset:9248
	ds_read_b128 v[110:113], v115 offset:14368
	ds_read_b128 v[118:121], v115 offset:16896
	s_waitcnt lgkmcnt(8)
	v_pk_mul_f32 v[34:35], v[2:3], v[34:35]
	v_pk_mul_f32 v[32:33], v[0:1], v[32:33]
	s_waitcnt lgkmcnt(7)
	v_pk_mul_f32 v[38:39], v[6:7], v[38:39]
	v_pk_mul_f32 v[36:37], v[4:5], v[36:37]
	s_waitcnt lgkmcnt(6)
	v_pk_mul_f32 v[42:43], v[10:11], v[42:43]
	v_pk_mul_f32 v[40:41], v[8:9], v[40:41]
	s_waitcnt lgkmcnt(5)
	v_pk_mul_f32 v[46:47], v[14:15], v[46:47]
	v_pk_mul_f32 v[44:45], v[12:13], v[44:45]
	v_pk_mul_f32 v[0:1], v[0:1], v[26:27]
	v_pk_mul_f32 v[2:3], v[2:3], v[28:29]
	v_pk_mul_f32 v[4:5], v[4:5], v[30:31]
	v_pk_mul_f32 v[6:7], v[6:7], v[48:49]
	v_pk_mul_f32 v[8:9], v[8:9], v[24:25]
	v_pk_mul_f32 v[10:11], v[10:11], v[84:85]
	v_pk_mul_f32 v[12:13], v[12:13], v[86:87]
	v_pk_mul_f32 v[14:15], v[14:15], v[96:97]
	s_waitcnt lgkmcnt(3)
	v_mfma_f32_32x32x16_bf16 v[32:47], v[16:19], v[20:23], v[32:47]
	ds_read_b128 v[84:87], v115 offset:16928
	s_movk_i32 s4, 0x50
	s_waitcnt lgkmcnt(1)
	v_mfma_f32_32x32x16_bf16 v[0:15], v[16:19], v[118:121], v[0:15]
	v_mfma_f32_32x32x16_bf16 v[32:47], v[106:109], v[110:113], v[32:47]
	s_waitcnt lgkmcnt(0)
	v_mfma_f32_32x32x16_bf16 v[0:15], v[106:109], v[84:87], v[0:15]
	ds_read_b128 v[16:19], v95 offset:19584
	ds_read_b128 v[24:27], v95 offset:19616
	ds_read_b128 v[28:31], v95 offset:19648
	ds_read_b128 v[106:109], v95 offset:19680
	ds_read_b128 v[122:125], v115 offset:11776
	s_waitcnt lgkmcnt(4)
	v_pk_mul_f32 v[50:51], v[18:19], v[50:51]
	v_pk_mul_f32 v[48:49], v[16:17], v[54:55]
	s_waitcnt lgkmcnt(3)
	v_pk_mul_f32 v[54:55], v[26:27], v[82:83]
	v_pk_mul_f32 v[52:53], v[24:25], v[52:53]
	s_waitcnt lgkmcnt(2)
	v_pk_mul_f32 v[58:59], v[30:31], v[58:59]
	v_pk_mul_f32 v[56:57], v[28:29], v[56:57]
	s_waitcnt lgkmcnt(1)
	v_pk_mul_f32 v[62:63], v[108:109], v[62:63]
	v_pk_mul_f32 v[60:61], v[106:107], v[60:61]
	ds_read_b128 v[126:129], v115 offset:11808
	v_pk_mul_f32 v[16:17], v[16:17], v[66:67]
	s_waitcnt lgkmcnt(1)
	v_mfma_f32_32x32x16_bf16 v[48:63], v[122:125], v[20:23], v[48:63]
	v_mul_f32_e64 v18, v18, v68
	v_mul_f32_e64 v19, v19, v69
	v_mul_f32_e64 v20, v24, v70
	v_mul_f32_e64 v21, v25, v71
	v_mul_f32_e64 v22, v26, v72
	v_mul_f32_e64 v23, v27, v73
	v_pk_mul_f32 v[24:25], v[28:29], v[74:75]
	v_pk_mul_f32 v[26:27], v[30:31], v[76:77]
	v_pk_mul_f32 v[28:29], v[106:107], v[78:79]
	v_pk_mul_f32 v[30:31], v[108:109], v[80:81]
	s_waitcnt lgkmcnt(0)
	s_waitcnt lgkmcnt(0)
	v_mfma_f32_32x32x16_bf16 v[48:63], v[126:129], v[110:113], v[48:63]
	v_mfma_f32_32x32x16_bf16 v[16:31], v[122:125], v[118:121], v[16:31]
	v_mfma_f32_32x32x16_bf16 v[16:31], v[126:129], v[84:87], v[16:31]
	v_mad_i64_i32 v[64:65], s[2:3], v88, s1, v[64:65]
	v_lshl_add_u64 v[64:65], v[64:65], 0, v[90:91]
	v_lshl_add_u64 v[64:65], v[64:65], 0, v[102:103]
	s_mov_b64 s[48:49], 0x1000
	s_movk_i32 s5, 0x1000
	v_lshl_add_u64 v[72:73], v[64:65], 0, s[48:49]
	v_add_co_u32_e32 v64, vcc, s5, v64
	global_load_dwordx2 v[74:75], v[104:105], off offset:1536
	s_nop 0
	v_addc_co_u32_e32 v65, vcc, 0, v65, vcc
	global_load_dwordx2 v[76:77], v[64:65], off
	v_readlane_b32 s0, v255, 18
	v_readlane_b32 s1, v255, 19
	s_add_u32 s2, s40, s0
	v_mov_b32_e32 v66, v114
	s_addc_u32 s3, s41, s1
	s_nop 0
	v_permlane32_swap_b32_e32 v114, v66
	v_lshl_add_u64 v[64:65], v[100:101], 2, s[2:3]
	s_mov_b64 s[2:3], 0x4800
	v_add_f32_e32 v66, v114, v66
	v_lshl_add_u64 v[70:71], v[64:65], 0, s[2:3]
	v_add_co_u32_e32 v64, vcc, s7, v64
	v_fmamk_f32 v66, v66, 0x3c800000, v237
	s_nop 0
	v_addc_co_u32_e32 v65, vcc, 0, v65, vcc
	v_rsq_f32_e32 v68, v66
	global_load_dwordx4 v[64:67], v[64:65], off offset:2048
	global_load_dwordx4 v[206:209], v[70:71], off offset:32
	global_load_dwordx2 v[210:211], v[72:73], off offset:16
	global_load_dwordx2 v[212:213], v[98:99], off offset:16
	global_load_dwordx4 v[214:217], v[70:71], off offset:64
	global_load_dwordx2 v[218:219], v[72:73], off offset:32
	global_load_dwordx2 v[220:221], v[98:99], off offset:32
	global_load_dwordx4 v[222:225], v[70:71], off offset:96
	global_load_dwordx2 v[226:227], v[72:73], off offset:48
	global_load_dwordx2 v[228:229], v[98:99], off offset:48
	s_movk_i32 s6, 0x1200
	s_waitcnt vmcnt(11)
	v_lshlrev_b32_e32 v82, 16, v74
	v_and_b32_e32 v83, 0xffff0000, v74
	v_lshlrev_b32_e32 v74, 16, v75
	s_waitcnt vmcnt(10)
	v_lshlrev_b32_e32 v78, 16, v76
	v_mul_f32_e32 v69, 0xbfb8aa3b, v78
	v_exp_f32_e32 v69, v69
	v_and_b32_e32 v79, 0xffff0000, v76
	v_lshlrev_b32_e32 v76, 16, v77
	v_and_b32_e32 v77, 0xffff0000, v77
	v_add_f32_e32 v69, 1.0, v69
	v_rcp_f32_e32 v80, v69
	v_mul_f32_e32 v69, 0xbfb8aa3b, v79
	v_exp_f32_e32 v69, v69
	v_and_b32_e32 v75, 0xffff0000, v75
	v_add_f32_e32 v69, 1.0, v69
	v_rcp_f32_e32 v81, v69
	v_pk_mul_f32 v[82:83], v[68:69], v[82:83] op_sel_hi:[0,1]
	v_pk_mul_f32 v[74:75], v[68:69], v[74:75] op_sel_hi:[0,1]
	s_waitcnt vmcnt(9)
	v_pk_mul_f32 v[64:65], v[64:65], v[82:83]
	v_pk_mul_f32 v[78:79], v[80:81], v[78:79]
	v_pk_mul_f32 v[66:67], v[66:67], v[74:75]
	v_pk_mul_f32 v[64:65], v[64:65], v[78:79]
	s_nop 0
	v_cvt_pk_bf16_f32 v64, v64, v65
	v_mul_f32_e32 v65, 0xbfb8aa3b, v76
	v_exp_f32_e32 v65, v65
	s_nop 0
	v_add_f32_e32 v65, 1.0, v65
	v_rcp_f32_e32 v78, v65
	v_mul_f32_e32 v65, 0xbfb8aa3b, v77
	v_exp_f32_e32 v65, v65
	s_nop 0
	v_add_f32_e32 v65, 1.0, v65
	v_rcp_f32_e32 v79, v65
	s_nop 0
	v_pk_mul_f32 v[74:75], v[78:79], v[76:77]
	s_nop 0
	v_pk_mul_f32 v[66:67], v[66:67], v[74:75]
	s_nop 0
	v_cvt_pk_bf16_f32 v65, v66, v67
	global_store_dwordx2 v[104:105], v[64:65], off offset:1536
	s_nop 0
	s_waitcnt vmcnt(8)
	v_lshlrev_b32_e32 v78, 16, v210
	v_mul_f32_e32 v69, 0xbfb8aa3b, v78
	v_exp_f32_e32 v69, v69
	v_and_b32_e32 v79, 0xffff0000, v210
	s_waitcnt vmcnt(7)
	v_lshlrev_b32_e32 v82, 16, v212
	v_and_b32_e32 v83, 0xffff0000, v212
	v_add_f32_e32 v69, 1.0, v69
	v_rcp_f32_e32 v80, v69
	v_mul_f32_e32 v69, 0xbfb8aa3b, v79
	v_exp_f32_e32 v69, v69
	v_lshlrev_b32_e32 v74, 16, v211
	v_and_b32_e32 v75, 0xffff0000, v211
	v_lshlrev_b32_e32 v76, 16, v213
	v_add_f32_e32 v69, 1.0, v69
	v_rcp_f32_e32 v81, v69
	v_pk_mul_f32 v[82:83], v[68:69], v[82:83] op_sel_hi:[0,1]
	v_pk_mul_f32 v[64:65], v[206:207], v[82:83]
	v_and_b32_e32 v77, 0xffff0000, v213
	v_pk_mul_f32 v[78:79], v[80:81], v[78:79]
	v_pk_mul_f32 v[76:77], v[68:69], v[76:77] op_sel_hi:[0,1]
	v_pk_mul_f32 v[64:65], v[64:65], v[78:79]
	v_pk_mul_f32 v[66:67], v[208:209], v[76:77]
	v_cvt_pk_bf16_f32 v64, v64, v65
	v_mul_f32_e32 v65, 0xbfb8aa3b, v74
	v_exp_f32_e32 v65, v65
	s_nop 0
	v_add_f32_e32 v65, 1.0, v65
	v_rcp_f32_e32 v78, v65
	v_mul_f32_e32 v65, 0xbfb8aa3b, v75
	v_exp_f32_e32 v65, v65
	s_nop 0
	v_add_f32_e32 v65, 1.0, v65
	v_rcp_f32_e32 v79, v65
	s_nop 0
	v_pk_mul_f32 v[74:75], v[78:79], v[74:75]
	s_nop 0
	v_pk_mul_f32 v[66:67], v[66:67], v[74:75]
	s_nop 0
	v_cvt_pk_bf16_f32 v65, v66, v67
	global_store_dwordx2 v[98:99], v[64:65], off offset:16
	s_nop 0
	s_waitcnt vmcnt(6)
	v_lshlrev_b32_e32 v78, 16, v218
	v_mul_f32_e32 v69, 0xbfb8aa3b, v78
	v_exp_f32_e32 v69, v69
	v_and_b32_e32 v79, 0xffff0000, v218
	s_waitcnt vmcnt(5)
	v_lshlrev_b32_e32 v82, 16, v220
	v_and_b32_e32 v83, 0xffff0000, v220
	v_add_f32_e32 v69, 1.0, v69
	v_rcp_f32_e32 v80, v69
	v_mul_f32_e32 v69, 0xbfb8aa3b, v79
	v_exp_f32_e32 v69, v69
	v_lshlrev_b32_e32 v74, 16, v219
	v_and_b32_e32 v75, 0xffff0000, v219
	v_lshlrev_b32_e32 v76, 16, v221
	v_add_f32_e32 v69, 1.0, v69
	v_rcp_f32_e32 v81, v69
	v_pk_mul_f32 v[82:83], v[68:69], v[82:83] op_sel_hi:[0,1]
	v_pk_mul_f32 v[64:65], v[214:215], v[82:83]
	v_and_b32_e32 v77, 0xffff0000, v221
	v_pk_mul_f32 v[78:79], v[80:81], v[78:79]
	v_pk_mul_f32 v[76:77], v[68:69], v[76:77] op_sel_hi:[0,1]
	v_pk_mul_f32 v[64:65], v[64:65], v[78:79]
	v_pk_mul_f32 v[66:67], v[216:217], v[76:77]
	v_cvt_pk_bf16_f32 v64, v64, v65
	v_mul_f32_e32 v65, 0xbfb8aa3b, v74
	v_exp_f32_e32 v65, v65
	s_nop 0
	v_add_f32_e32 v65, 1.0, v65
	v_rcp_f32_e32 v78, v65
	v_mul_f32_e32 v65, 0xbfb8aa3b, v75
	v_exp_f32_e32 v65, v65
	s_nop 0
	v_add_f32_e32 v65, 1.0, v65
	v_rcp_f32_e32 v79, v65
	s_nop 0
	v_pk_mul_f32 v[74:75], v[78:79], v[74:75]
	s_nop 0
	v_pk_mul_f32 v[66:67], v[66:67], v[74:75]
	s_nop 0
	v_cvt_pk_bf16_f32 v65, v66, v67
	global_store_dwordx2 v[98:99], v[64:65], off offset:32
	s_nop 0
	s_waitcnt vmcnt(4)
	v_lshlrev_b32_e32 v78, 16, v226
	v_mul_f32_e32 v69, 0xbfb8aa3b, v78
	v_exp_f32_e32 v69, v69
	v_and_b32_e32 v79, 0xffff0000, v226
	s_waitcnt vmcnt(3)
	v_lshlrev_b32_e32 v82, 16, v228
	v_and_b32_e32 v83, 0xffff0000, v228
	v_add_f32_e32 v69, 1.0, v69
	v_rcp_f32_e32 v80, v69
	v_mul_f32_e32 v69, 0xbfb8aa3b, v79
	v_exp_f32_e32 v69, v69
	v_lshlrev_b32_e32 v74, 16, v227
	v_and_b32_e32 v75, 0xffff0000, v227
	v_lshlrev_b32_e32 v76, 16, v229
	v_add_f32_e32 v69, 1.0, v69
	v_rcp_f32_e32 v81, v69
	v_pk_mul_f32 v[82:83], v[68:69], v[82:83] op_sel_hi:[0,1]
	v_pk_mul_f32 v[64:65], v[222:223], v[82:83]
	v_and_b32_e32 v77, 0xffff0000, v229
	v_pk_mul_f32 v[78:79], v[80:81], v[78:79]
	v_pk_mul_f32 v[76:77], v[68:69], v[76:77] op_sel_hi:[0,1]
	v_pk_mul_f32 v[64:65], v[64:65], v[78:79]
	v_pk_mul_f32 v[66:67], v[224:225], v[76:77]
	v_cvt_pk_bf16_f32 v64, v64, v65
	v_mul_f32_e32 v65, 0xbfb8aa3b, v74
	v_exp_f32_e32 v65, v65
	s_nop 0
	v_add_f32_e32 v65, 1.0, v65
	v_rcp_f32_e32 v78, v65
	v_mul_f32_e32 v65, 0xbfb8aa3b, v75
	v_exp_f32_e32 v65, v65
	s_nop 0
	v_add_f32_e32 v65, 1.0, v65
	v_rcp_f32_e32 v79, v65
	s_nop 0
	v_pk_mul_f32 v[74:75], v[78:79], v[74:75]
	s_nop 0
	v_pk_mul_f32 v[66:67], v[66:67], v[74:75]
	s_nop 0
	v_cvt_pk_bf16_f32 v65, v66, v67
	global_store_dwordx2 v[98:99], v[64:65], off offset:48
	global_load_dwordx2 v[74:75], v[98:99], off offset:64
	global_load_dwordx2 v[76:77], v[72:73], off offset:64
	global_load_dwordx4 v[64:67], v[70:71], off offset:128
	global_load_dwordx2 v[212:213], v[98:99], off offset:80
	global_load_dwordx2 v[210:211], v[72:73], off offset:80
	global_load_dwordx4 v[206:209], v[70:71], off offset:160
	global_load_dwordx2 v[220:221], v[98:99], off offset:96
	global_load_dwordx2 v[218:219], v[72:73], off offset:96
	global_load_dwordx4 v[214:217], v[70:71], off offset:192
	global_load_dwordx2 v[228:229], v[98:99], off offset:112
	global_load_dwordx2 v[226:227], v[72:73], off offset:112
	global_load_dwordx4 v[222:225], v[70:71], off offset:224
	s_waitcnt vmcnt(11)
	v_lshlrev_b32_e32 v82, 16, v74
	s_waitcnt vmcnt(10)
	v_lshlrev_b32_e32 v78, 16, v76
	v_mul_f32_e32 v69, 0xbfb8aa3b, v78
	v_exp_f32_e32 v69, v69
	v_and_b32_e32 v79, 0xffff0000, v76
	v_and_b32_e32 v83, 0xffff0000, v74
	v_lshlrev_b32_e32 v76, 16, v77
	v_add_f32_e32 v69, 1.0, v69
	v_rcp_f32_e32 v80, v69
	v_mul_f32_e32 v69, 0xbfb8aa3b, v79
	v_exp_f32_e32 v69, v69
	v_and_b32_e32 v77, 0xffff0000, v77
	v_lshlrev_b32_e32 v74, 16, v75
	v_and_b32_e32 v75, 0xffff0000, v75
	v_add_f32_e32 v69, 1.0, v69
	v_rcp_f32_e32 v81, v69
	v_pk_mul_f32 v[82:83], v[68:69], v[82:83] op_sel_hi:[0,1]
	s_waitcnt vmcnt(9)
	v_pk_mul_f32 v[64:65], v[64:65], v[82:83]
	v_pk_mul_f32 v[74:75], v[68:69], v[74:75] op_sel_hi:[0,1]
	v_pk_mul_f32 v[78:79], v[80:81], v[78:79]
	v_pk_mul_f32 v[66:67], v[66:67], v[74:75]
	v_pk_mul_f32 v[64:65], v[64:65], v[78:79]
	s_nop 0
	v_cvt_pk_bf16_f32 v64, v64, v65
	v_mul_f32_e32 v65, 0xbfb8aa3b, v76
	v_exp_f32_e32 v65, v65
	s_nop 0
	v_add_f32_e32 v65, 1.0, v65
	v_rcp_f32_e32 v78, v65
	v_mul_f32_e32 v65, 0xbfb8aa3b, v77
	v_exp_f32_e32 v65, v65
	s_nop 0
	v_add_f32_e32 v65, 1.0, v65
	v_rcp_f32_e32 v79, v65
	s_nop 0
	v_pk_mul_f32 v[74:75], v[78:79], v[76:77]
	s_nop 0
	v_pk_mul_f32 v[66:67], v[66:67], v[74:75]
	s_nop 0
	v_cvt_pk_bf16_f32 v65, v66, v67
	global_store_dwordx2 v[98:99], v[64:65], off offset:64
	s_nop 0
	s_waitcnt vmcnt(9)
	v_lshlrev_b32_e32 v82, 16, v212
	s_waitcnt vmcnt(8)
	v_lshlrev_b32_e32 v78, 16, v210
	v_mul_f32_e32 v69, 0xbfb8aa3b, v78
	v_exp_f32_e32 v69, v69
	v_and_b32_e32 v79, 0xffff0000, v210
	v_and_b32_e32 v83, 0xffff0000, v212
	v_lshlrev_b32_e32 v76, 16, v211
	v_add_f32_e32 v69, 1.0, v69
	v_rcp_f32_e32 v80, v69
	v_mul_f32_e32 v69, 0xbfb8aa3b, v79
	v_exp_f32_e32 v69, v69
	v_and_b32_e32 v77, 0xffff0000, v211
	v_lshlrev_b32_e32 v74, 16, v213
	v_and_b32_e32 v75, 0xffff0000, v213
	v_add_f32_e32 v69, 1.0, v69
	v_rcp_f32_e32 v81, v69
	v_pk_mul_f32 v[82:83], v[68:69], v[82:83] op_sel_hi:[0,1]
	s_waitcnt vmcnt(7)
	v_pk_mul_f32 v[64:65], v[206:207], v[82:83]
	v_pk_mul_f32 v[74:75], v[68:69], v[74:75] op_sel_hi:[0,1]
	v_pk_mul_f32 v[78:79], v[80:81], v[78:79]
	v_pk_mul_f32 v[66:67], v[208:209], v[74:75]
	v_pk_mul_f32 v[64:65], v[64:65], v[78:79]
	s_nop 0
	v_cvt_pk_bf16_f32 v64, v64, v65
	v_mul_f32_e32 v65, 0xbfb8aa3b, v76
	v_exp_f32_e32 v65, v65
	s_nop 0
	v_add_f32_e32 v65, 1.0, v65
	v_rcp_f32_e32 v78, v65
	v_mul_f32_e32 v65, 0xbfb8aa3b, v77
	v_exp_f32_e32 v65, v65
	s_nop 0
	v_add_f32_e32 v65, 1.0, v65
	v_rcp_f32_e32 v79, v65
	s_nop 0
	v_pk_mul_f32 v[74:75], v[78:79], v[76:77]
	s_nop 0
	v_pk_mul_f32 v[66:67], v[66:67], v[74:75]
	s_nop 0
	v_cvt_pk_bf16_f32 v65, v66, v67
	global_store_dwordx2 v[98:99], v[64:65], off offset:80
	s_nop 0
	s_waitcnt vmcnt(7)
	v_lshlrev_b32_e32 v82, 16, v220
	s_waitcnt vmcnt(6)
	v_lshlrev_b32_e32 v78, 16, v218
	v_mul_f32_e32 v69, 0xbfb8aa3b, v78
	v_exp_f32_e32 v69, v69
	v_and_b32_e32 v79, 0xffff0000, v218
	v_and_b32_e32 v83, 0xffff0000, v220
	v_lshlrev_b32_e32 v76, 16, v219
	v_add_f32_e32 v69, 1.0, v69
	v_rcp_f32_e32 v80, v69
	v_mul_f32_e32 v69, 0xbfb8aa3b, v79
	v_exp_f32_e32 v69, v69
	v_and_b32_e32 v77, 0xffff0000, v219
	v_lshlrev_b32_e32 v74, 16, v221
	v_and_b32_e32 v75, 0xffff0000, v221
	v_add_f32_e32 v69, 1.0, v69
	v_rcp_f32_e32 v81, v69
	v_pk_mul_f32 v[82:83], v[68:69], v[82:83] op_sel_hi:[0,1]
	s_waitcnt vmcnt(5)
	v_pk_mul_f32 v[64:65], v[214:215], v[82:83]
	v_pk_mul_f32 v[74:75], v[68:69], v[74:75] op_sel_hi:[0,1]
	v_pk_mul_f32 v[78:79], v[80:81], v[78:79]
	v_pk_mul_f32 v[66:67], v[216:217], v[74:75]
	v_pk_mul_f32 v[64:65], v[64:65], v[78:79]
	s_nop 0
	v_cvt_pk_bf16_f32 v64, v64, v65
	v_mul_f32_e32 v65, 0xbfb8aa3b, v76
	v_exp_f32_e32 v65, v65
	s_nop 0
	v_add_f32_e32 v65, 1.0, v65
	v_rcp_f32_e32 v78, v65
	v_mul_f32_e32 v65, 0xbfb8aa3b, v77
	v_exp_f32_e32 v65, v65
	s_nop 0
	v_add_f32_e32 v65, 1.0, v65
	v_rcp_f32_e32 v79, v65
	s_nop 0
	v_pk_mul_f32 v[74:75], v[78:79], v[76:77]
	s_nop 0
	v_pk_mul_f32 v[66:67], v[66:67], v[74:75]
	s_nop 0
	v_cvt_pk_bf16_f32 v65, v66, v67
	global_store_dwordx2 v[98:99], v[64:65], off offset:96
	s_nop 0
	s_nop 0
	s_waitcnt vmcnt(5)
	v_lshlrev_b32_e32 v78, 16, v228
	s_waitcnt vmcnt(4)
	v_lshlrev_b32_e32 v74, 16, v226
	v_mul_f32_e32 v69, 0xbfb8aa3b, v74
	v_exp_f32_e32 v69, v69
	v_and_b32_e32 v75, 0xffff0000, v226
	v_lshlrev_b32_e32 v66, 16, v227
	v_and_b32_e32 v79, 0xffff0000, v228
	v_add_f32_e32 v69, 1.0, v69
	v_rcp_f32_e32 v76, v69
	v_mul_f32_e32 v69, 0xbfb8aa3b, v75
	v_exp_f32_e32 v69, v69
	v_and_b32_e32 v67, 0xffff0000, v227
	v_add_f32_e32 v69, 1.0, v69
	v_rcp_f32_e32 v77, v69
	v_pk_mul_f32 v[78:79], v[68:69], v[78:79] op_sel_hi:[0,1]
	v_mul_f32_e32 v69, 0xbfb8aa3b, v66
	v_exp_f32_e32 v69, v69
	s_waitcnt vmcnt(3)
	v_pk_mul_f32 v[70:71], v[222:223], v[78:79]
	v_pk_mul_f32 v[74:75], v[76:77], v[74:75]
	v_add_f32_e32 v69, 1.0, v69
	v_pk_mul_f32 v[70:71], v[70:71], v[74:75]
	v_lshlrev_b32_e32 v74, 16, v229
	v_cvt_pk_bf16_f32 v64, v70, v71
	v_rcp_f32_e32 v70, v69
	v_mul_f32_e32 v69, 0xbfb8aa3b, v67
	v_exp_f32_e32 v69, v69
	v_and_b32_e32 v75, 0xffff0000, v229
	v_add_f32_e32 v69, 1.0, v69
	v_rcp_f32_e32 v71, v69
	v_pk_mul_f32 v[68:69], v[68:69], v[74:75] op_sel_hi:[0,1]
	v_pk_mul_f32 v[68:69], v[224:225], v[68:69]
	v_pk_mul_f32 v[66:67], v[70:71], v[66:67]
	s_nop 0
	v_pk_mul_f32 v[66:67], v[68:69], v[66:67]
	s_nop 0
	v_cvt_pk_bf16_f32 v65, v66, v67
	global_store_dwordx2 v[98:99], v[64:65], off offset:112
	s_add_u32 s2, s12, 0xb200000
	v_and_b32_e32 v114, 31, v94
	v_ashrrev_i32_e32 v115, 5, v94
	s_addc_u32 s3, s13, 0
	v_mov_b64_e32 v[96:97], s[2:3]
	v_mad_i64_i32 v[64:65], s[2:3], v93, s6, v[96:97]
	v_ashrrev_i32_e32 v95, 31, v94
	v_lshl_add_u64 v[64:65], v[64:65], 0, v[90:91]
	v_lshl_add_u64 v[64:65], v[94:95], 1, v[64:65]
	v_add_co_u32_e32 v76, vcc, s37, v64
	s_movk_i32 s2, 0x5000
	s_nop 0
	v_addc_co_u32_e32 v77, vcc, 0, v65, vcc
	global_load_ushort v95, v[76:77], off offset:3072
	global_load_ushort v107, v[76:77], off offset:1536
	v_add_co_u32_e32 v66, vcc, s20, v64
	v_lshl_add_u32 v88, v94, 1, v92
	s_nop 0
	v_addc_co_u32_e32 v67, vcc, 0, v65, vcc
	v_add_co_u32_e32 v68, vcc, s2, v64
	s_movk_i32 s2, 0x7000
	s_nop 0
	v_addc_co_u32_e32 v69, vcc, 0, v65, vcc
	v_add_co_u32_e32 v70, vcc, s2, v64
	s_mov_b32 s2, 0x10000
	s_nop 0
	v_addc_co_u32_e32 v71, vcc, 0, v65, vcc
	v_add_co_u32_e32 v80, vcc, s28, v64
	s_waitcnt vmcnt(0)
	v_lshlrev_b32_e32 v107, 16, v107
	v_addc_co_u32_e32 v81, vcc, 0, v65, vcc
	v_add_co_u32_e32 v82, vcc, s29, v64
	v_readlane_b32 s28, v255, 28
	s_nop 0
	v_addc_co_u32_e32 v83, vcc, 0, v65, vcc
	v_add_co_u32_e32 v84, vcc, s18, v64
	v_readlane_b32 s29, v255, 29
	s_nop 0
	v_addc_co_u32_e32 v85, vcc, 0, v65, vcc
	v_add_co_u32_e32 v86, vcc, s2, v64
	s_mov_b32 s2, 0x14000
	s_nop 0
	v_addc_co_u32_e32 v87, vcc, 0, v65, vcc
	v_add_co_u32_e32 v72, vcc, s51, v64
	s_nop 1
	v_addc_co_u32_e32 v73, vcc, 0, v65, vcc
	v_add_co_u32_e32 v74, vcc, s2, v64
	s_mov_b32 s2, 0x1a000
	s_nop 0
	v_addc_co_u32_e32 v75, vcc, 0, v65, vcc
	v_add_co_u32_e32 v78, vcc, s30, v64
	s_nop 1
	v_addc_co_u32_e32 v79, vcc, 0, v65, vcc
	v_add_co_u32_e32 v98, vcc, s31, v64
	s_mov_b64 s[30:31], 0x4800
	s_nop 0
	v_addc_co_u32_e32 v99, vcc, 0, v65, vcc
	v_add_co_u32_e32 v100, vcc, s34, v64
	s_nop 1
	v_addc_co_u32_e32 v101, vcc, 0, v65, vcc
	v_add_co_u32_e32 v102, vcc, s35, v64
	s_mov_b64 s[34:35], 0x1200
	s_nop 0
	v_addc_co_u32_e32 v103, vcc, 0, v65, vcc
	v_add_co_u32_e32 v104, vcc, s19, v64
	v_readlane_b32 s18, v255, 26
	s_nop 0
	v_addc_co_u32_e32 v105, vcc, 0, v65, vcc
	v_add_co_u32_e32 v118, vcc, s36, v64
	v_readlane_b32 s36, v255, 30
	s_nop 0
	v_addc_co_u32_e32 v119, vcc, 0, v65, vcc
	v_add_co_u32_e32 v108, vcc, s21, v64
	v_readlane_b32 s19, v255, 27
	s_nop 0
	v_addc_co_u32_e32 v109, vcc, 0, v65, vcc
	global_load_ushort v111, v[108:109], off offset:512
	global_load_ushort v106, v[108:109], off offset:1024
	global_load_ushort v113, v[108:109], off offset:2048
	s_nop 0
	global_load_ushort v108, v[76:77], off offset:2048
	global_load_ushort v110, v[118:119], off offset:1536
	global_load_ushort v120, v[118:119], off offset:2560
	global_load_ushort v121, v[102:103], off offset:3584
	global_load_ushort v122, v[104:105], off offset:512
	global_load_ushort v152, v[118:119], off offset:1024
	global_load_ushort v153, v[104:105], off offset:1536
	global_load_ushort v154, v[104:105], off
	global_load_ushort v158, v[102:103], off offset:3072
	global_load_ushort v160, v[102:103], off
	global_load_ushort v165, v[100:101], off offset:3584
	v_lshlrev_b32_e32 v76, 16, v95
	v_max_f32_e32 v76, v76, v76
	v_med3_f32 v76, v76, s9, v244
	v_mul_f32_e32 v76, 0xbfb8aa3b, v76
	v_exp_f32_e32 v95, v76
	v_add_co_u32_e32 v76, vcc, s42, v64
	global_load_ushort v123, v[78:79], off offset:512
	global_load_ushort v124, v[98:99], off offset:1536
	global_load_ushort v126, v[100:101], off offset:2560
	global_load_ushort v166, v[100:101], off offset:2048
	global_load_ushort v168, v[98:99], off offset:2560
	global_load_ushort v171, v[98:99], off offset:1024
	global_load_ushort v167, v[78:79], off offset:1536
	global_load_ushort v163, v[78:79], off
	v_add_f32_e32 v109, 1.0, v95
	v_addc_co_u32_e32 v77, vcc, 0, v65, vcc
	v_rcp_f32_e32 v109, v109
	v_add_co_u32_e32 v134, vcc, s17, v64
	v_readlane_b32 s37, v255, 31
	s_nop 0
	v_addc_co_u32_e32 v135, vcc, 0, v65, vcc
	v_add_co_u32_e32 v132, vcc, s16, v64
	v_fma_f32 v112, v117, v109, v116
	s_nop 0
	v_addc_co_u32_e32 v133, vcc, 0, v65, vcc
	v_max_f32_e32 v150, 0xda24260, v112
	v_add_co_u32_e32 v118, vcc, s2, v64
	v_mul_f32_e32 v95, v95, v109
	v_rcp_f32_e32 v109, v150
	v_addc_co_u32_e32 v119, vcc, 0, v65, vcc
	s_mov_b32 s2, 0x18000
	v_add_co_u32_e32 v136, vcc, s2, v64
	s_mov_b32 s2, 0x16000
	s_nop 0
	v_addc_co_u32_e32 v137, vcc, 0, v65, vcc
	v_mul_f32_e32 v95, v117, v95
	v_mul_f32_e32 v107, v150, v107
	v_add_co_u32_e32 v78, vcc, s2, v64
	v_bfe_u32 v112, v107, 16, 1
	v_mul_f32_e32 v95, v95, v109
	v_addc_co_u32_e32 v79, vcc, 0, v65, vcc
	v_add3_u32 v151, v107, v112, s10
	v_bfe_u32 v107, v95, 16, 1
	v_add_co_u32_e32 v138, vcc, s43, v64
	v_add3_u32 v112, v95, v107, s10
	s_nop 0
	v_addc_co_u32_e32 v139, vcc, 0, v65, vcc
	global_load_ushort v125, v[84:85], off offset:512
	global_load_ushort v127, v[86:87], off offset:1536
	global_load_ushort v128, v[72:73], off offset:2560
	global_load_ushort v129, v[74:75], off offset:3584
	global_load_ushort v157, v[74:75], off offset:3072
	global_load_ushort v155, v[74:75], off
	global_load_ushort v109, v[72:73], off offset:3584
	global_load_ushort v107, v[72:73], off offset:2048
	global_load_ushort v172, v[76:77], off offset:1024
	global_load_ushort v173, v[134:135], off offset:3584
	global_load_ushort v174, v[132:133], off offset:2560
	global_load_ushort v175, v[118:119], off offset:1536
	global_load_ushort v131, v[118:119], off offset:2048
	s_nop 0
	global_load_ushort v132, v[132:133], off offset:3072
	s_nop 0
	global_load_ushort v176, v[134:135], off offset:512
	global_load_ushort v133, v[76:77], off
	global_load_ushort v177, v[118:119], off offset:3072
	global_load_ushort v170, v[136:137], off offset:2048
	global_load_ushort v169, v[136:137], off offset:512
	global_load_ushort v164, v[78:79], off offset:1024
	global_load_ushort v162, v[138:139], off offset:3584
	global_load_ushort v159, v[138:139], off offset:512
	global_load_ushort v135, v[78:79], off
	s_nop 0
	global_load_ushort v137, v[136:137], off offset:1024
	v_add_co_u32_e32 v144, vcc, s44, v64
	global_load_ushort v130, v[64:65], off offset:2560
	global_load_ushort v134, v[66:67], off offset:3584
	global_load_ushort v136, v[68:69], off offset:512
	global_load_ushort v138, v[70:71], off offset:1536
	global_load_ushort v139, v[80:81], off offset:2560
	global_load_ushort v141, v[82:83], off offset:3584
	global_load_ushort v142, v[84:85], off offset:-4096
	global_load_ushort v140, v[68:69], off offset:-4096
	v_addc_co_u32_e32 v145, vcc, 0, v65, vcc
	v_add_co_u32_e32 v100, vcc, s45, v64
	v_readlane_b32 s42, v255, 32
	s_nop 0
	v_addc_co_u32_e32 v101, vcc, 0, v65, vcc
	v_add_co_u32_e32 v102, vcc, s46, v64
	v_readlane_b32 s43, v255, 33
	s_nop 0
	v_addc_co_u32_e32 v103, vcc, 0, v65, vcc
	v_add_co_u32_e32 v104, vcc, s47, v64
	v_readlane_b32 s46, v255, 38
	s_nop 0
	v_addc_co_u32_e32 v105, vcc, 0, v65, vcc
	v_add_co_u32_e32 v98, vcc, s15, v64
	s_waitcnt vmcnt(53)
	v_lshlrev_b32_e32 v111, 16, v111
	v_addc_co_u32_e32 v99, vcc, 0, v65, vcc
	s_waitcnt vmcnt(51)
	v_lshlrev_b32_e32 v113, 16, v113
	s_waitcnt vmcnt(48)
	v_lshlrev_b32_e32 v72, 16, v120
	v_max_f32_e32 v72, v72, v72
	v_med3_f32 v72, v72, s9, v244
	v_mul_f32_e32 v72, 0xbfb8aa3b, v72
	v_exp_f32_e32 v95, v72
	v_add_co_u32_e32 v74, vcc, s14, v64
	v_max_f32_e32 v113, v113, v113
	v_add_f32_e32 v118, 1.0, v95
	v_rcp_f32_e32 v118, v118
	v_addc_co_u32_e32 v75, vcc, 0, v65, vcc
	v_med3_f32 v113, v113, s9, v244
	v_fma_f32 v119, v117, v118, v116
	v_mul_f32_e32 v119, v150, v119
	v_max_f32_e32 v119, 0xda24260, v119
	v_add_co_u32_e32 v76, vcc, s27, v64
	v_rcp_f32_e32 v120, v119
	v_mul_f32_e32 v113, 0xbfb8aa3b, v113
	v_addc_co_u32_e32 v77, vcc, 0, v65, vcc
	v_exp_f32_e32 v113, v113
	v_add_co_u32_e32 v78, vcc, s7, v64
	v_mul_f32_e32 v95, v95, v118
	s_nop 0
	v_addc_co_u32_e32 v79, vcc, 0, v65, vcc
	v_mul_f32_e32 v95, v117, v95
	v_add_co_u32_e32 v72, vcc, s5, v64
	v_mul_f32_e32 v95, v95, v120
	s_nop 0
	v_addc_co_u32_e32 v73, vcc, 0, v65, vcc
	global_load_ushort v156, v[144:145], off offset:2560
	global_load_ushort v148, v[144:145], off offset:3072
	global_load_ushort v149, v[100:101], off offset:2048
	global_load_ushort v147, v[102:103], off offset:1024
	global_load_ushort v146, v[98:99], off offset:3072
	s_nop 0
	global_load_ushort v144, v[74:75], off offset:2048
	global_load_ushort v145, v[76:77], off offset:1024
	global_load_ushort v143, v[72:73], off offset:3072
	v_bfe_u32 v118, v95, 16, 1
	v_add_f32_e32 v120, 1.0, v113
	v_add3_u32 v95, v95, v118, s10
	s_waitcnt vmcnt(53)
	v_lshlrev_b32_e32 v118, 16, v152
	v_rcp_f32_e32 v120, v120
	v_mul_f32_e32 v118, v119, v118
	v_bfe_u32 v150, v118, 16, 1
	v_add3_u32 v118, v118, v150, s10
	ds_write_b16_d16_hi v88, v118 offset:4320
	v_fma_f32 v118, v117, v120, v116
	v_mul_f32_e32 v118, v119, v118
	v_mul_f32_e32 v113, v113, v120
	s_waitcnt vmcnt(52)
	v_lshlrev_b32_e32 v120, 16, v153
	v_max_f32_e32 v118, 0xda24260, v118
	v_max_f32_e32 v120, v120, v120
	v_rcp_f32_e32 v119, v118
	v_med3_f32 v120, v120, s9, v244
	v_mul_f32_e32 v120, 0xbfb8aa3b, v120
	v_exp_f32_e32 v120, v120
	v_mul_f32_e32 v113, v117, v113
	v_mul_f32_e32 v113, v113, v119
	v_bfe_u32 v119, v113, 16, 1
	ds_write_b16_d16_hi v88, v151 offset:4464
	v_add3_u32 v151, v113, v119, s10
	v_add_f32_e32 v113, 1.0, v120
	v_rcp_f32_e32 v113, v113
	v_mul_f32_e32 v111, v118, v111
	v_bfe_u32 v119, v111, 16, 1
	v_add3_u32 v111, v111, v119, s10
	ds_write_b16_d16_hi v88, v111 offset:4176
	v_fma_f32 v111, v117, v113, v116
	s_waitcnt vmcnt(31)
	v_lshlrev_b32_e32 v119, 16, v172
	v_mul_f32_e32 v111, v118, v111
	v_max_f32_e32 v119, v119, v119
	v_max_f32_e32 v111, 0xda24260, v111
	v_med3_f32 v119, v119, s9, v244
	v_rcp_f32_e32 v118, v111
	v_mul_f32_e32 v119, 0xbfb8aa3b, v119
	v_exp_f32_e32 v119, v119
	v_mul_f32_e32 v113, v120, v113
	v_mul_f32_e32 v113, v117, v113
	v_mul_f32_e32 v113, v113, v118
	v_bfe_u32 v118, v113, 16, 1
	v_add_f32_e32 v120, 1.0, v119
	v_add3_u32 v118, v113, v118, s10
	v_lshlrev_b32_e32 v113, 16, v154
	v_rcp_f32_e32 v120, v120
	v_mul_f32_e32 v113, v111, v113
	v_bfe_u32 v150, v113, 16, 1
	v_add3_u32 v113, v113, v150, s10
	ds_write_b16_d16_hi v88, v113 offset:4032
	v_fma_f32 v113, v117, v120, v116
	v_mul_f32_e32 v111, v111, v113
	v_mul_f32_e32 v119, v119, v120
	s_waitcnt vmcnt(25)
	v_lshlrev_b32_e32 v120, 16, v176
	v_max_f32_e32 v111, 0xda24260, v111
	v_max_f32_e32 v120, v120, v120
	v_rcp_f32_e32 v113, v111
	v_med3_f32 v120, v120, s9, v244
	v_mul_f32_e32 v120, 0xbfb8aa3b, v120
	v_exp_f32_e32 v120, v120
	v_mul_f32_e32 v119, v117, v119
	v_mul_f32_e32 v113, v119, v113
	v_bfe_u32 v119, v113, 16, 1
	v_add3_u32 v152, v113, v119, s10
	v_add_f32_e32 v119, 1.0, v120
	v_lshlrev_b32_e32 v113, 16, v173
	v_rcp_f32_e32 v119, v119
	v_mul_f32_e32 v113, v111, v113
	v_bfe_u32 v150, v113, 16, 1
	v_add3_u32 v113, v113, v150, s10
	ds_write_b16_d16_hi v88, v113 offset:3888
	v_fma_f32 v113, v117, v119, v116
	v_mul_f32_e32 v119, v120, v119
	v_lshlrev_b32_e32 v120, 16, v160
	v_mul_f32_e32 v111, v111, v113
	v_max_f32_e32 v120, v120, v120
	v_max_f32_e32 v111, 0xda24260, v111
	v_med3_f32 v120, v120, s9, v244
	v_rcp_f32_e32 v113, v111
	v_mul_f32_e32 v120, 0xbfb8aa3b, v120
	v_exp_f32_e32 v120, v120
	v_mul_f32_e32 v119, v117, v119
	v_mul_f32_e32 v113, v119, v113
	v_bfe_u32 v119, v113, 16, 1
	v_add_f32_e32 v150, 1.0, v120
	v_add3_u32 v119, v113, v119, s10
	v_lshlrev_b32_e32 v113, 16, v158
	v_rcp_f32_e32 v150, v150
	v_mul_f32_e32 v113, v111, v113
	v_bfe_u32 v153, v113, 16, 1
	v_add3_u32 v113, v113, v153, s10
	ds_write_b16_d16_hi v88, v113 offset:3744
	v_fma_f32 v113, v117, v150, v116
	v_mul_f32_e32 v111, v111, v113
	v_mul_f32_e32 v120, v120, v150
	v_lshlrev_b32_e32 v150, 16, v165
	v_max_f32_e32 v111, 0xda24260, v111
	v_max_f32_e32 v150, v150, v150
	v_rcp_f32_e32 v113, v111
	v_med3_f32 v150, v150, s9, v244
	v_mul_f32_e32 v150, 0xbfb8aa3b, v150
	v_exp_f32_e32 v150, v150
	v_mul_f32_e32 v120, v117, v120
	v_mul_f32_e32 v113, v120, v113
	v_bfe_u32 v120, v113, 16, 1
	v_add3_u32 v153, v113, v120, s10
	v_add_f32_e32 v120, 1.0, v150
	v_lshlrev_b32_e32 v113, 16, v174
	v_rcp_f32_e32 v120, v120
	v_mul_f32_e32 v113, v111, v113
	v_bfe_u32 v154, v113, 16, 1
	v_add3_u32 v113, v113, v154, s10
	ds_write_b16_d16_hi v88, v113 offset:3600
	v_fma_f32 v113, v117, v120, v116
	v_mul_f32_e32 v111, v111, v113
	v_max_f32_e32 v111, 0xda24260, v111
	v_rcp_f32_e32 v113, v111
	v_mul_f32_e32 v120, v150, v120
	v_mul_f32_e32 v120, v117, v120
	v_readlane_b32 s47, v255, 39
	v_mul_f32_e32 v113, v120, v113
	v_bfe_u32 v120, v113, 16, 1
	v_add3_u32 v120, v113, v120, s10
	v_lshlrev_b32_e32 v113, 16, v166
	v_mul_f32_e32 v113, v111, v113
	v_bfe_u32 v150, v113, 16, 1
	v_add3_u32 v113, v113, v150, s10
	ds_write_b16_d16_hi v88, v112 offset:9072
	ds_write_b16_d16_hi v88, v95 offset:8928
	ds_write_b16_d16_hi v88, v151 offset:8784
	ds_write_b16_d16_hi v88, v118 offset:8640
	ds_write_b16_d16_hi v88, v152 offset:8496
	ds_write_b16_d16_hi v88, v119 offset:8352
	ds_write_b16_d16_hi v88, v153 offset:8208
	ds_write_b16_d16_hi v88, v113 offset:3456
	ds_write_b16_d16_hi v88, v120 offset:8064
	s_waitcnt vmcnt(23)
	v_lshlrev_b32_e32 v113, 16, v177
	v_max_f32_e32 v113, v113, v113
	v_med3_f32 v113, v113, s9, v244
	v_mul_f32_e32 v113, 0xbfb8aa3b, v113
	v_exp_f32_e32 v113, v113
	v_lshlrev_b32_e32 v107, 16, v107
	v_add_f32_e32 v150, 1.0, v113
	v_rcp_f32_e32 v150, v150
	s_nop 0
	v_fma_f32 v154, v117, v150, v116
	v_mul_f32_e32 v111, v111, v154
	v_max_f32_e32 v111, 0xda24260, v111
	v_mul_f32_e32 v113, v113, v150
	v_rcp_f32_e32 v150, v111
	v_mul_f32_e32 v113, v117, v113
	v_mul_f32_e32 v113, v113, v150
	v_bfe_u32 v150, v113, 16, 1
	v_add3_u32 v154, v113, v150, s10
	v_lshlrev_b32_e32 v113, 16, v175
	v_mul_f32_e32 v113, v111, v113
	v_bfe_u32 v150, v113, 16, 1
	v_add3_u32 v113, v113, v150, s10
	ds_write_b16_d16_hi v88, v113 offset:3312
	ds_write_b16_d16_hi v88, v154 offset:7920
	v_lshlrev_b32_e32 v113, 16, v168
	v_max_f32_e32 v113, v113, v113
	v_med3_f32 v113, v113, s9, v244
	v_mul_f32_e32 v113, 0xbfb8aa3b, v113
	v_exp_f32_e32 v113, v113
	s_nop 0
	v_add_f32_e32 v150, 1.0, v113
	v_rcp_f32_e32 v150, v150
	s_nop 0
	v_fma_f32 v158, v117, v150, v116
	v_mul_f32_e32 v111, v111, v158
	v_max_f32_e32 v172, 0xda24260, v111
	v_rcp_f32_e32 v111, v172
	v_mul_f32_e32 v113, v113, v150
	v_mul_f32_e32 v113, v117, v113
	v_mul_f32_e32 v111, v113, v111
	v_bfe_u32 v113, v111, 16, 1
	v_add3_u32 v150, v111, v113, s10
	v_lshlrev_b32_e32 v111, 16, v171
	v_mul_f32_e32 v111, v172, v111
	v_bfe_u32 v113, v111, 16, 1
	v_add3_u32 v171, v111, v113, s10
	global_load_ushort v168, v[100:101], off offset:3072
	global_load_ushort v166, v[100:101], off offset:1536
	global_load_ushort v165, v[86:87], off offset:2560
	global_load_ushort v160, v[86:87], off offset:1024
	global_load_ushort v158, v[102:103], off offset:2048
	global_load_ushort v113, v[102:103], off offset:512
	global_load_ushort v111, v[84:85], off offset:1536
	s_nop 0
	global_load_ushort v103, v[84:85], off
	global_load_ushort v102, v[104:105], off offset:1024
	v_add_co_u32_e32 v84, vcc, s50, v64
	s_nop 1
	v_addc_co_u32_e32 v85, vcc, 0, v65, vcc
	global_load_ushort v101, v[84:85], off offset:3584
	global_load_ushort v100, v[84:85], off offset:512
	global_load_ushort v87, v[82:83], off offset:3072
	global_load_ushort v86, v[82:83], off
	s_nop 0
	global_load_ushort v83, v[98:99], off offset:2560
	global_load_ushort v82, v[80:81], off offset:3584
	s_nop 0
	global_load_ushort v81, v[80:81], off offset:2048
	s_waitcnt vmcnt(38)
	v_lshlrev_b32_e32 v80, 16, v170
	v_max_f32_e32 v80, v80, v80
	v_med3_f32 v80, v80, s9, v244
	v_mul_f32_e32 v80, 0xbfb8aa3b, v80
	v_exp_f32_e32 v80, v80
	ds_write_b16_d16_hi v88, v171 offset:3168
	ds_write_b16_d16_hi v88, v150 offset:7776
	v_add_f32_e32 v84, 1.0, v80
	v_rcp_f32_e32 v84, v84
	s_nop 0
	v_fma_f32 v85, v117, v84, v116
	v_mul_f32_e32 v80, v80, v84
	v_mul_f32_e32 v84, v172, v85
	v_max_f32_e32 v84, 0xda24260, v84
	v_rcp_f32_e32 v85, v84
	v_mul_f32_e32 v80, v117, v80
	v_mul_f32_e32 v80, v80, v85
	v_bfe_u32 v85, v80, 16, 1
	v_add3_u32 v85, v80, v85, s10
	s_waitcnt vmcnt(37)
	v_lshlrev_b32_e32 v80, 16, v169
	v_mul_f32_e32 v80, v84, v80
	v_bfe_u32 v98, v80, 16, 1
	v_add3_u32 v80, v80, v98, s10
	ds_write_b16_d16_hi v88, v80 offset:3024
	ds_write_b16_d16_hi v88, v85 offset:7632
	v_lshlrev_b32_e32 v80, 16, v167
	v_max_f32_e32 v80, v80, v80
	v_med3_f32 v80, v80, s9, v244
	v_mul_f32_e32 v80, 0xbfb8aa3b, v80
	v_exp_f32_e32 v80, v80
	s_nop 0
	v_add_f32_e32 v98, 1.0, v80
	v_rcp_f32_e32 v98, v98
	s_nop 0
	v_fma_f32 v99, v117, v98, v116
	v_mul_f32_e32 v84, v84, v99
	v_max_f32_e32 v84, 0xda24260, v84
	v_mul_f32_e32 v80, v80, v98
	v_rcp_f32_e32 v98, v84
	v_mul_f32_e32 v80, v117, v80
	v_mul_f32_e32 v80, v80, v98
	v_bfe_u32 v98, v80, 16, 1
	v_add3_u32 v80, v80, v98, s10
	v_lshlrev_b32_e32 v98, 16, v163
	v_mul_f32_e32 v98, v84, v98
	v_bfe_u32 v99, v98, 16, 1
	v_add3_u32 v98, v98, v99, s10
	ds_write_b16_d16_hi v88, v98 offset:2880
	ds_write_b16_d16_hi v88, v80 offset:7488
	s_waitcnt vmcnt(36)
	v_lshlrev_b32_e32 v98, 16, v164
	v_max_f32_e32 v98, v98, v98
	v_med3_f32 v98, v98, s9, v244
	v_mul_f32_e32 v98, 0xbfb8aa3b, v98
	v_exp_f32_e32 v98, v98
	s_nop 0
	v_add_f32_e32 v99, 1.0, v98
	v_rcp_f32_e32 v99, v99
	s_nop 0
	v_fma_f32 v104, v117, v99, v116
	v_mul_f32_e32 v84, v84, v104
	v_max_f32_e32 v84, 0xda24260, v84
	v_mul_f32_e32 v98, v98, v99
	v_rcp_f32_e32 v99, v84
	v_mul_f32_e32 v98, v117, v98
	v_mul_f32_e32 v98, v98, v99
	v_bfe_u32 v99, v98, 16, 1
	v_add3_u32 v99, v98, v99, s10
	s_waitcnt vmcnt(35)
	v_lshlrev_b32_e32 v98, 16, v162
	v_mul_f32_e32 v98, v84, v98
	v_bfe_u32 v104, v98, 16, 1
	v_add3_u32 v98, v98, v104, s10
	ds_write_b16_d16_hi v88, v98 offset:2736
	ds_write_b16_d16_hi v88, v99 offset:7344
	s_waitcnt vmcnt(34)
	v_lshlrev_b32_e32 v98, 16, v159
	v_max_f32_e32 v98, v98, v98
	v_med3_f32 v98, v98, s9, v244
	v_mul_f32_e32 v98, 0xbfb8aa3b, v98
	v_exp_f32_e32 v98, v98
	s_nop 0
	v_add_f32_e32 v104, 1.0, v98
	v_rcp_f32_e32 v104, v104
	s_nop 0
	v_fma_f32 v105, v117, v104, v116
	v_mul_f32_e32 v84, v84, v105
	v_mul_f32_e32 v98, v98, v104
	v_max_f32_e32 v104, 0xda24260, v84
	v_rcp_f32_e32 v84, v104
	v_mul_f32_e32 v98, v117, v98
	v_mul_f32_e32 v84, v98, v84
	v_bfe_u32 v98, v84, 16, 1
	v_add3_u32 v84, v84, v98, s10
	v_lshlrev_b32_e32 v98, 16, v157
	v_mul_f32_e32 v98, v104, v98
	v_bfe_u32 v105, v98, 16, 1
	v_add3_u32 v98, v98, v105, s10
	ds_write_b16_d16_hi v88, v98 offset:2592
	ds_write_b16_d16_hi v88, v84 offset:7200
	v_lshlrev_b32_e32 v98, 16, v155
	v_max_f32_e32 v98, v98, v98
	v_med3_f32 v98, v98, s9, v244
	v_mul_f32_e32 v98, 0xbfb8aa3b, v98
	v_exp_f32_e32 v98, v98
	s_nop 0
	v_add_f32_e32 v105, 1.0, v98
	v_rcp_f32_e32 v105, v105
	s_nop 0
	v_fma_f32 v155, v117, v105, v116
	v_mul_f32_e32 v104, v104, v155
	v_max_f32_e32 v104, 0xda24260, v104
	v_mul_f32_e32 v98, v98, v105
	v_rcp_f32_e32 v105, v104
	v_mul_f32_e32 v98, v117, v98
	v_mul_f32_e32 v98, v98, v105
	v_bfe_u32 v105, v98, 16, 1
	v_add3_u32 v105, v98, v105, s10
	s_waitcnt vmcnt(23)
	v_lshlrev_b32_e32 v98, 16, v156
	v_mul_f32_e32 v98, v104, v98
	v_bfe_u32 v155, v98, 16, 1
	v_add3_u32 v98, v98, v155, s10
	ds_write_b16_d16_hi v88, v98 offset:2448
	ds_write_b16_d16_hi v88, v105 offset:7056
	v_lshlrev_b32_e32 v98, 16, v109
	v_max_f32_e32 v98, v98, v98
	v_med3_f32 v98, v98, s9, v244
	v_mul_f32_e32 v98, 0xbfb8aa3b, v98
	v_exp_f32_e32 v98, v98
	s_nop 0
	v_add_f32_e32 v109, 1.0, v98
	v_rcp_f32_e32 v109, v109
	s_nop 0
	v_fma_f32 v155, v117, v109, v116
	v_mul_f32_e32 v104, v104, v155
	v_max_f32_e32 v104, 0xda24260, v104
	v_mul_f32_e32 v98, v98, v109
	v_rcp_f32_e32 v109, v104
	v_mul_f32_e32 v98, v117, v98
	v_mul_f32_e32 v107, v104, v107
	v_mul_f32_e32 v98, v98, v109
	v_bfe_u32 v109, v98, 16, 1
	v_add3_u32 v98, v98, v109, s10
	v_bfe_u32 v109, v107, 16, 1
	v_add3_u32 v107, v107, v109, s10
	ds_write_b16_d16_hi v88, v107 offset:2304
	ds_write_b16_d16_hi v88, v98 offset:6912
	s_waitcnt vmcnt(15)
	v_lshlrev_b32_e32 v107, 16, v168
	v_max_f32_e32 v107, v107, v107
	v_med3_f32 v107, v107, s9, v244
	v_mul_f32_e32 v107, 0xbfb8aa3b, v107
	v_exp_f32_e32 v107, v107
	s_nop 0
	v_add_f32_e32 v109, 1.0, v107
	v_rcp_f32_e32 v109, v109
	s_nop 0
	v_fma_f32 v155, v117, v109, v116
	v_mul_f32_e32 v104, v104, v155
	v_max_f32_e32 v104, 0xda24260, v104
	v_mul_f32_e32 v107, v107, v109
	v_rcp_f32_e32 v109, v104
	v_mul_f32_e32 v107, v117, v107
	v_mul_f32_e32 v107, v107, v109
	v_bfe_u32 v109, v107, 16, 1
	v_add3_u32 v107, v107, v109, s10
	s_waitcnt vmcnt(14)
	v_lshlrev_b32_e32 v109, 16, v166
	v_mul_f32_e32 v109, v104, v109
	v_bfe_u32 v155, v109, 16, 1
	v_add3_u32 v109, v109, v155, s10
	ds_write_b16_d16_hi v88, v109 offset:2160
	ds_write_b16_d16_hi v88, v107 offset:6768
	s_waitcnt vmcnt(13)
	v_lshlrev_b32_e32 v109, 16, v165
	v_max_f32_e32 v109, v109, v109
	v_med3_f32 v109, v109, s9, v244
	v_mul_f32_e32 v109, 0xbfb8aa3b, v109
	v_exp_f32_e32 v109, v109
	global_load_ushort v172, v[74:75], off offset:3072
	global_load_ushort v170, v[74:75], off offset:1536
	global_load_ushort v171, v[70:71], off offset:2560
	global_load_ushort v168, v[70:71], off offset:1024
	global_load_ushort v169, v[76:77], off offset:2048
	global_load_ushort v166, v[76:77], off offset:512
	global_load_ushort v167, v[68:69], off offset:1536
	global_load_ushort v162, v[68:69], off
	global_load_ushort v164, v[78:79], off offset:1024
	v_add_co_u32_e32 v68, vcc, s11, v64
	v_add_f32_e32 v155, 1.0, v109
	v_rcp_f32_e32 v155, v155
	v_addc_co_u32_e32 v69, vcc, 0, v65, vcc
	v_fma_f32 v156, v117, v155, v116
	v_mul_f32_e32 v104, v104, v156
	v_max_f32_e32 v173, 0xda24260, v104
	v_rcp_f32_e32 v104, v173
	v_mul_f32_e32 v109, v109, v155
	v_mul_f32_e32 v109, v117, v109
	v_mul_f32_e32 v104, v109, v104
	v_bfe_u32 v109, v104, 16, 1
	v_add3_u32 v104, v104, v109, s10
	s_waitcnt vmcnt(21)
	v_lshlrev_b32_e32 v109, 16, v160
	v_mul_f32_e32 v109, v173, v109
	v_bfe_u32 v155, v109, 16, 1
	v_add3_u32 v109, v109, v155, s10
	global_load_ushort v163, v[68:69], off offset:3584
	global_load_ushort v165, v[68:69], off offset:512
	global_load_ushort v159, v[66:67], off offset:3072
	global_load_ushort v160, v[66:67], off
	global_load_ushort v156, v[72:73], off offset:2560
	global_load_ushort v157, v[64:65], off offset:3584
	global_load_ushort v155, v[64:65], off offset:2048
	s_waitcnt vmcnt(27)
	v_lshlrev_b32_e32 v64, 16, v158
	v_max_f32_e32 v64, v64, v64
	v_med3_f32 v64, v64, s9, v244
	v_mul_f32_e32 v64, 0xbfb8aa3b, v64
	v_exp_f32_e32 v64, v64
	ds_write_b16_d16_hi v88, v109 offset:2016
	ds_write_b16_d16_hi v88, v104 offset:6624
	v_add_f32_e32 v65, 1.0, v64
	v_rcp_f32_e32 v65, v65
	s_nop 0
	v_fma_f32 v66, v117, v65, v116
	v_mul_f32_e32 v64, v64, v65
	v_mul_f32_e32 v65, v173, v66
	v_max_f32_e32 v65, 0xda24260, v65
	v_rcp_f32_e32 v66, v65
	v_mul_f32_e32 v64, v117, v64
	v_mul_f32_e32 v64, v64, v66
	v_bfe_u32 v66, v64, 16, 1
	v_add3_u32 v64, v64, v66, s10
	s_waitcnt vmcnt(26)
	v_lshlrev_b32_e32 v66, 16, v113
	v_mul_f32_e32 v66, v65, v66
	v_bfe_u32 v67, v66, 16, 1
	v_add3_u32 v66, v66, v67, s10
	ds_write_b16_d16_hi v88, v66 offset:1872
	ds_write_b16_d16_hi v88, v64 offset:6480
	s_waitcnt vmcnt(25)
	v_lshlrev_b32_e32 v66, 16, v111
	v_max_f32_e32 v66, v66, v66
	v_med3_f32 v66, v66, s9, v244
	v_mul_f32_e32 v66, 0xbfb8aa3b, v66
	v_exp_f32_e32 v66, v66
	s_nop 0
	v_add_f32_e32 v67, 1.0, v66
	v_rcp_f32_e32 v67, v67
	s_nop 0
	v_fma_f32 v68, v117, v67, v116
	v_mul_f32_e32 v65, v65, v68
	v_max_f32_e32 v65, 0xda24260, v65
	v_mul_f32_e32 v66, v66, v67
	v_rcp_f32_e32 v67, v65
	v_mul_f32_e32 v66, v117, v66
	v_mul_f32_e32 v66, v66, v67
	v_bfe_u32 v67, v66, 16, 1
	v_add3_u32 v158, v66, v67, s10
	s_waitcnt vmcnt(24)
	v_lshlrev_b32_e32 v66, 16, v103
	v_mul_f32_e32 v66, v65, v66
	v_bfe_u32 v67, v66, 16, 1
	v_add3_u32 v66, v66, v67, s10
	ds_write_b16_d16_hi v88, v66 offset:1728
	ds_write_b16_d16_hi v88, v158 offset:6336
	s_waitcnt vmcnt(23)
	v_lshlrev_b32_e32 v66, 16, v102
	v_max_f32_e32 v66, v66, v66
	v_med3_f32 v66, v66, s9, v244
	v_mul_f32_e32 v66, 0xbfb8aa3b, v66
	v_exp_f32_e32 v66, v66
	s_nop 0
	v_add_f32_e32 v67, 1.0, v66
	v_rcp_f32_e32 v67, v67
	s_nop 0
	v_fma_f32 v68, v117, v67, v116
	v_mul_f32_e32 v65, v65, v68
	v_max_f32_e32 v65, 0xda24260, v65
	v_mul_f32_e32 v66, v66, v67
	v_rcp_f32_e32 v67, v65
	v_mul_f32_e32 v66, v117, v66
	v_mul_f32_e32 v66, v66, v67
	v_bfe_u32 v67, v66, 16, 1
	v_add3_u32 v66, v66, v67, s10
	s_waitcnt vmcnt(22)
	v_lshlrev_b32_e32 v67, 16, v101
	v_mul_f32_e32 v67, v65, v67
	v_bfe_u32 v68, v67, 16, 1
	v_add3_u32 v67, v67, v68, s10
	ds_write_b16_d16_hi v88, v67 offset:1584
	ds_write_b16_d16_hi v88, v66 offset:6192
	s_waitcnt vmcnt(21)
	v_lshlrev_b32_e32 v67, 16, v100
	v_max_f32_e32 v67, v67, v67
	v_med3_f32 v67, v67, s9, v244
	v_mul_f32_e32 v67, 0xbfb8aa3b, v67
	v_exp_f32_e32 v67, v67
	s_nop 0
	v_add_f32_e32 v68, 1.0, v67
	v_rcp_f32_e32 v68, v68
	s_nop 0
	v_fma_f32 v69, v117, v68, v116
	v_mul_f32_e32 v65, v65, v69
	v_max_f32_e32 v65, 0xda24260, v65
	v_mul_f32_e32 v67, v67, v68
	v_rcp_f32_e32 v68, v65
	v_mul_f32_e32 v67, v117, v67
	v_mul_f32_e32 v67, v67, v68
	v_bfe_u32 v68, v67, 16, 1
	v_add3_u32 v100, v67, v68, s10
	s_waitcnt vmcnt(20)
	v_lshlrev_b32_e32 v67, 16, v87
	v_mul_f32_e32 v67, v65, v67
	v_bfe_u32 v68, v67, 16, 1
	v_add3_u32 v67, v67, v68, s10
	ds_write_b16_d16_hi v88, v67 offset:1440
	ds_write_b16_d16_hi v88, v100 offset:6048
	s_waitcnt vmcnt(19)
	v_lshlrev_b32_e32 v67, 16, v86
	v_max_f32_e32 v67, v67, v67
	v_med3_f32 v67, v67, s9, v244
	v_mul_f32_e32 v67, 0xbfb8aa3b, v67
	v_exp_f32_e32 v67, v67
	s_nop 0
	v_add_f32_e32 v68, 1.0, v67
	v_rcp_f32_e32 v68, v68
	s_nop 0
	v_fma_f32 v69, v117, v68, v116
	v_mul_f32_e32 v65, v65, v69
	v_max_f32_e32 v65, 0xda24260, v65
	v_mul_f32_e32 v67, v67, v68
	v_rcp_f32_e32 v68, v65
	v_mul_f32_e32 v67, v117, v67
	v_mul_f32_e32 v67, v67, v68
	v_bfe_u32 v68, v67, 16, 1
	v_add3_u32 v67, v67, v68, s10
	s_waitcnt vmcnt(18)
	v_lshlrev_b32_e32 v68, 16, v83
	v_mul_f32_e32 v68, v65, v68
	v_bfe_u32 v69, v68, 16, 1
	v_add3_u32 v68, v68, v69, s10
	ds_write_b16_d16_hi v88, v68 offset:1296
	ds_write_b16_d16_hi v88, v67 offset:5904
	s_waitcnt vmcnt(17)
	v_lshlrev_b32_e32 v68, 16, v82
	v_max_f32_e32 v68, v68, v68
	v_med3_f32 v68, v68, s9, v244
	v_mul_f32_e32 v68, 0xbfb8aa3b, v68
	v_exp_f32_e32 v68, v68
	s_nop 0
	v_add_f32_e32 v69, 1.0, v68
	v_rcp_f32_e32 v69, v69
	s_nop 0
	v_fma_f32 v70, v117, v69, v116
	v_mul_f32_e32 v65, v65, v70
	v_max_f32_e32 v76, 0xda24260, v65
	v_rcp_f32_e32 v65, v76
	v_mul_f32_e32 v68, v68, v69
	v_mul_f32_e32 v68, v117, v68
	v_mul_f32_e32 v65, v68, v65
	v_bfe_u32 v68, v65, 16, 1
	v_add3_u32 v82, v65, v68, s10
	s_waitcnt vmcnt(16)
	v_lshlrev_b32_e32 v65, 16, v81
	v_mul_f32_e32 v65, v76, v65
	v_bfe_u32 v68, v65, 16, 1
	v_add3_u32 v65, v65, v68, s10
	ds_write_b16_d16_hi v88, v65 offset:1152
	ds_write_b16_d16_hi v88, v82 offset:5760
	s_waitcnt vmcnt(15)
	v_lshlrev_b32_e32 v72, 16, v172
	v_max_f32_e32 v72, v72, v72
	v_med3_f32 v72, v72, s9, v244
	v_mul_f32_e32 v72, 0xbfb8aa3b, v72
	v_exp_f32_e32 v86, v72
	v_and_b32_e32 v111, 0xffff0000, v66
	v_lshl_or_b32 v66, v106, 16, v122
	v_and_b32_e32 v113, 0xffff0000, v67
	v_add_f32_e32 v77, 1.0, v86
	v_rcp_f32_e32 v102, v77
	v_lshl_or_b32 v67, v108, 16, v110
	v_and_b32_e32 v81, 0xffff0000, v112
	v_lshl_or_b32 v75, v149, 16, v127
	v_fma_f32 v106, v117, v102, v116
	v_mul_f32_e32 v76, v76, v106
	v_max_f32_e32 v106, 0xda24260, v76
	v_rcp_f32_e32 v108, v106
	v_mul_f32_e32 v86, v86, v102
	v_mul_f32_e32 v86, v117, v86
	v_lshl_or_b32 v65, v133, 16, v121
	v_mul_f32_e32 v86, v86, v108
	v_bfe_u32 v102, v86, 16, 1
	v_add3_u32 v86, v86, v102, s10
	s_waitcnt vmcnt(13)
	v_lshlrev_b32_e32 v102, 16, v171
	v_max_f32_e32 v102, v102, v102
	v_med3_f32 v102, v102, s9, v244
	v_mul_f32_e32 v102, 0xbfb8aa3b, v102
	v_exp_f32_e32 v102, v102
	v_lshlrev_b32_e32 v108, 16, v170
	v_mul_f32_e32 v108, v106, v108
	v_bfe_u32 v112, v108, 16, 1
	v_add_f32_e32 v110, 1.0, v102
	v_rcp_f32_e32 v110, v110
	v_add3_u32 v108, v108, v112, s10
	ds_write_b16_d16_hi v88, v108 offset:1008
	v_and_b32_e32 v127, 0xffff0000, v86
	v_fma_f32 v108, v117, v110, v116
	v_mul_f32_e32 v106, v106, v108
	v_max_f32_e32 v106, 0xda24260, v106
	v_rcp_f32_e32 v108, v106
	ds_write_b16_d16_hi v88, v86 offset:5616
	v_mul_f32_e32 v86, v102, v110
	v_mul_f32_e32 v86, v117, v86
	v_mul_f32_e32 v86, v86, v108
	s_waitcnt vmcnt(11)
	v_lshlrev_b32_e32 v108, 16, v169
	v_max_f32_e32 v108, v108, v108
	v_med3_f32 v108, v108, s9, v244
	v_mul_f32_e32 v108, 0xbfb8aa3b, v108
	v_exp_f32_e32 v108, v108
	v_bfe_u32 v102, v86, 16, 1
	v_add3_u32 v86, v86, v102, s10
	v_lshlrev_b32_e32 v102, 16, v168
	v_add_f32_e32 v110, 1.0, v108
	v_rcp_f32_e32 v110, v110
	v_mul_f32_e32 v102, v106, v102
	v_bfe_u32 v112, v102, 16, 1
	v_add3_u32 v102, v102, v112, s10
	ds_write_b16_d16_hi v88, v102 offset:864
	v_fma_f32 v102, v117, v110, v116
	v_mul_f32_e32 v102, v106, v102
	v_max_f32_e32 v102, 0xda24260, v102
	v_rcp_f32_e32 v106, v102
	v_mul_f32_e32 v108, v108, v110
	v_mul_f32_e32 v108, v117, v108
	s_waitcnt vmcnt(10)
	v_lshlrev_b32_e32 v110, 16, v166
	v_mul_f32_e32 v106, v108, v106
	v_bfe_u32 v108, v106, 16, 1
	v_add3_u32 v106, v106, v108, s10
	s_waitcnt vmcnt(9)
	v_lshlrev_b32_e32 v108, 16, v167
	v_max_f32_e32 v108, v108, v108
	v_med3_f32 v108, v108, s9, v244
	v_mul_f32_e32 v108, 0xbfb8aa3b, v108
	v_exp_f32_e32 v108, v108
	v_mul_f32_e32 v110, v102, v110
	v_bfe_u32 v121, v110, 16, 1
	v_add3_u32 v110, v110, v121, s10
	v_add_f32_e32 v112, 1.0, v108
	v_rcp_f32_e32 v112, v112
	ds_write_b16_d16_hi v88, v110 offset:720
	v_lshl_or_b32 v74, v147, 16, v125
	v_and_b32_e32 v125, 0xffff0000, v106
	v_fma_f32 v110, v117, v112, v116
	v_mul_f32_e32 v102, v102, v110
	v_max_f32_e32 v102, 0xda24260, v102
	v_rcp_f32_e32 v110, v102
	ds_write_b16_d16_hi v88, v106 offset:5328
	v_mul_f32_e32 v106, v108, v112
	v_mul_f32_e32 v106, v117, v106
	v_mul_f32_e32 v106, v106, v110
	s_waitcnt vmcnt(7)
	v_lshlrev_b32_e32 v110, 16, v164
	v_max_f32_e32 v110, v110, v110
	v_med3_f32 v110, v110, s9, v244
	v_mul_f32_e32 v110, 0xbfb8aa3b, v110
	v_exp_f32_e32 v110, v110
	v_bfe_u32 v108, v106, 16, 1
	v_add3_u32 v106, v106, v108, s10
	v_lshlrev_b32_e32 v108, 16, v162
	v_add_f32_e32 v112, 1.0, v110
	v_rcp_f32_e32 v112, v112
	v_mul_f32_e32 v108, v102, v108
	v_bfe_u32 v121, v108, 16, 1
	v_add3_u32 v108, v108, v121, s10
	ds_write_b16_d16_hi v88, v108 offset:576
	v_fma_f32 v108, v117, v112, v116
	v_mul_f32_e32 v102, v102, v108
	v_max_f32_e32 v102, 0xda24260, v102
	v_rcp_f32_e32 v108, v102
	v_mul_f32_e32 v110, v110, v112
	v_mul_f32_e32 v110, v117, v110
	s_waitcnt vmcnt(6)
	v_lshlrev_b32_e32 v112, 16, v163
	v_mul_f32_e32 v108, v110, v108
	v_bfe_u32 v110, v108, 16, 1
	v_add3_u32 v108, v108, v110, s10
	s_waitcnt vmcnt(5)
	v_lshlrev_b32_e32 v110, 16, v165
	v_max_f32_e32 v110, v110, v110
	v_med3_f32 v110, v110, s9, v244
	v_mul_f32_e32 v110, 0xbfb8aa3b, v110
	v_exp_f32_e32 v110, v110
	v_mul_f32_e32 v112, v102, v112
	v_bfe_u32 v122, v112, 16, 1
	v_add3_u32 v112, v112, v122, s10
	v_add_f32_e32 v121, 1.0, v110
	v_rcp_f32_e32 v121, v121
	ds_write_b16_d16_hi v88, v112 offset:432
	v_lshl_or_b32 v69, v135, 16, v129
	v_and_b32_e32 v129, 0xffff0000, v108
	v_fma_f32 v112, v117, v121, v116
	v_mul_f32_e32 v102, v102, v112
	v_max_f32_e32 v102, 0xda24260, v102
	v_rcp_f32_e32 v112, v102
	ds_write_b16_d16_hi v88, v108 offset:5040
	v_mul_f32_e32 v108, v110, v121
	v_mul_f32_e32 v108, v117, v108
	v_mul_f32_e32 v108, v108, v112
	s_waitcnt vmcnt(3)
	v_lshlrev_b32_e32 v112, 16, v160
	v_max_f32_e32 v112, v112, v112
	v_med3_f32 v112, v112, s9, v244
	v_mul_f32_e32 v112, 0xbfb8aa3b, v112
	v_exp_f32_e32 v112, v112
	v_bfe_u32 v110, v108, 16, 1
	v_add3_u32 v108, v108, v110, s10
	v_lshlrev_b32_e32 v110, 16, v159
	v_add_f32_e32 v121, 1.0, v112
	v_rcp_f32_e32 v121, v121
	v_mul_f32_e32 v110, v102, v110
	v_bfe_u32 v122, v110, 16, 1
	v_add3_u32 v110, v110, v122, s10
	ds_write_b16_d16_hi v88, v110 offset:288
	v_fma_f32 v110, v117, v121, v116
	v_mul_f32_e32 v102, v102, v110
	v_max_f32_e32 v102, 0xda24260, v102
	v_rcp_f32_e32 v110, v102
	v_mul_f32_e32 v112, v112, v121
	v_mul_f32_e32 v112, v117, v112
	s_waitcnt vmcnt(2)
	v_lshlrev_b32_e32 v121, 16, v156
	v_mul_f32_e32 v110, v112, v110
	v_bfe_u32 v112, v110, 16, 1
	v_add3_u32 v110, v110, v112, s10
	s_waitcnt vmcnt(1)
	v_lshlrev_b32_e32 v112, 16, v157
	v_max_f32_e32 v112, v112, v112
	v_med3_f32 v112, v112, s9, v244
	v_mul_f32_e32 v112, 0xbfb8aa3b, v112
	v_exp_f32_e32 v112, v112
	v_mul_f32_e32 v121, v102, v121
	v_lshl_or_b32 v70, v137, 16, v123
	v_and_b32_e32 v123, 0xffff0000, v110
	v_add_f32_e32 v122, 1.0, v112
	v_rcp_f32_e32 v122, v122
	ds_write_b16_d16_hi v88, v110 offset:4752
	v_lshl_or_b32 v71, v131, 16, v124
	v_bfe_u32 v124, v121, 16, 1
	v_fmac_f32_e32 v116, v117, v122
	v_mul_f32_e32 v102, v102, v116
	v_max_f32_e32 v116, 0xda24260, v102
	v_rcp_f32_e32 v102, v116
	v_mul_f32_e32 v110, v112, v122
	v_mul_f32_e32 v110, v117, v110
	v_readlane_b32 s9, v255, 34
	v_mul_f32_e32 v102, v110, v102
	v_bfe_u32 v110, v102, 16, 1
	v_add3_u32 v102, v102, v110, s10
	s_waitcnt vmcnt(0)
	v_lshlrev_b32_e32 v110, 16, v155
	v_mul_f32_e32 v110, v116, v110
	v_bfe_u32 v112, v110, 16, 1
	v_add3_u32 v121, v121, v124, s10
	v_add3_u32 v110, v110, v112, s10
	v_readlane_b32 s10, v255, 36
	v_and_b32_e32 v109, 0xffff0000, v64
	v_and_b32_e32 v107, 0xffff0000, v107
	v_and_b32_e32 v105, 0xffff0000, v105
	v_and_b32_e32 v103, 0xffff0000, v99
	v_and_b32_e32 v101, 0xffff0000, v85
	v_and_b32_e32 v99, 0xffff0000, v154
	v_and_b32_e32 v87, 0xffff0000, v153
	v_and_b32_e32 v85, 0xffff0000, v152
	v_and_b32_e32 v83, 0xffff0000, v151
	v_lshl_or_b32 v64, v132, 16, v126
	v_lshl_or_b32 v68, v148, 16, v128
	v_lshl_or_b32 v73, v142, 16, v141
	v_lshl_or_b32 v72, v146, 16, v139
	v_lshl_or_b32 v79, v144, 16, v138
	v_lshl_or_b32 v78, v145, 16, v136
	v_lshl_or_b32 v77, v140, 16, v134
	v_lshl_or_b32 v76, v143, 16, v130
	ds_write_b16_d16_hi v88, v86 offset:5472
	ds_write_b16_d16_hi v88, v106 offset:5184
	ds_write_b16_d16_hi v88, v108 offset:4896
	ds_write_b16_d16_hi v88, v121 offset:144
	ds_write_b16_d16_hi v88, v110
	ds_write_b16_d16_hi v88, v102 offset:4608
	v_and_b32_e32 v122, 0xffff0000, v102
	v_and_b32_e32 v128, 0xffff0000, v108
	v_and_b32_e32 v124, 0xffff0000, v106
	v_and_b32_e32 v126, 0xffff0000, v86
	v_pk_mul_f32 v[122:123], v[116:117], v[122:123] op_sel_hi:[0,1]
	v_pk_mul_f32 v[128:129], v[116:117], v[128:129] op_sel_hi:[0,1]
	v_pk_mul_f32 v[124:125], v[116:117], v[124:125] op_sel_hi:[0,1]
	v_pk_mul_f32 v[126:127], v[116:117], v[126:127] op_sel_hi:[0,1]
	v_and_b32_e32 v112, 0xffff0000, v82
	v_and_b32_e32 v110, 0xffff0000, v100
	v_and_b32_e32 v108, 0xffff0000, v158
	v_and_b32_e32 v106, 0xffff0000, v104
	v_and_b32_e32 v104, 0xffff0000, v98
	v_and_b32_e32 v102, 0xffff0000, v84
	v_and_b32_e32 v100, 0xffff0000, v80
	v_and_b32_e32 v98, 0xffff0000, v150
	v_and_b32_e32 v86, 0xffff0000, v120
	v_and_b32_e32 v84, 0xffff0000, v119
	v_and_b32_e32 v82, 0xffff0000, v118
	v_and_b32_e32 v80, 0xffff0000, v95
	v_mad_u64_u32 v[130:131], s[2:3], v94, s4, v[92:93]
	v_cvt_pk_bf16_f32 v122, v122, v123
	v_cvt_pk_bf16_f32 v123, v128, v129
	v_cvt_pk_bf16_f32 v124, v124, v125
	v_cvt_pk_bf16_f32 v125, v126, v127
	v_pk_mul_f32 v[112:113], v[116:117], v[112:113] op_sel_hi:[0,1]
	v_pk_mul_f32 v[110:111], v[116:117], v[110:111] op_sel_hi:[0,1]
	v_pk_mul_f32 v[108:109], v[116:117], v[108:109] op_sel_hi:[0,1]
	v_pk_mul_f32 v[106:107], v[116:117], v[106:107] op_sel_hi:[0,1]
	v_pk_mul_f32 v[104:105], v[116:117], v[104:105] op_sel_hi:[0,1]
	v_pk_mul_f32 v[102:103], v[116:117], v[102:103] op_sel_hi:[0,1]
	v_pk_mul_f32 v[100:101], v[116:117], v[100:101] op_sel_hi:[0,1]
	v_pk_mul_f32 v[98:99], v[116:117], v[98:99] op_sel_hi:[0,1]
	v_pk_mul_f32 v[86:87], v[116:117], v[86:87] op_sel_hi:[0,1]
	v_pk_mul_f32 v[84:85], v[116:117], v[84:85] op_sel_hi:[0,1]
	v_pk_mul_f32 v[82:83], v[116:117], v[82:83] op_sel_hi:[0,1]
	v_pk_mul_f32 v[80:81], v[116:117], v[80:81] op_sel_hi:[0,1]
	ds_write_b128 v130, v[122:125] offset:9216
	v_cvt_pk_bf16_f32 v122, v112, v113
	v_cvt_pk_bf16_f32 v123, v110, v111
	v_cvt_pk_bf16_f32 v124, v108, v109
	v_cvt_pk_bf16_f32 v125, v106, v107
	v_cvt_pk_bf16_f32 v104, v104, v105
	v_cvt_pk_bf16_f32 v105, v102, v103
	v_cvt_pk_bf16_f32 v106, v100, v101
	v_cvt_pk_bf16_f32 v107, v98, v99
	v_cvt_pk_bf16_f32 v98, v86, v87
	v_cvt_pk_bf16_f32 v99, v84, v85
	v_cvt_pk_bf16_f32 v100, v82, v83
	v_cvt_pk_bf16_f32 v101, v80, v81
	v_lshl_add_u32 v80, v94, 2, v92
	ds_write_b128 v130, v[122:125] offset:9232
	ds_write_b128 v130, v[104:107] offset:9248
	ds_write_b128 v130, v[98:101] offset:9264
	ds_write_b32 v80, v116 offset:19456
	ds_write_b128 v130, v[76:79] offset:14336
	ds_write_b128 v130, v[72:75] offset:14352
	ds_write_b128 v130, v[68:71] offset:14368
	ds_write_b128 v130, v[64:67] offset:14384
	s_waitcnt lgkmcnt(0)
	v_or_b32_e32 v88, v93, v114
	v_lshlrev_b64 v[64:65], 11, v[88:89]
	v_lshlrev_b32_e32 v98, 2, v115
	v_lshl_add_u64 v[64:65], s[12:13], 0, v[64:65]
	v_ashrrev_i32_e32 v99, 31, v98
	v_lshl_add_u64 v[64:65], v[64:65], 0, v[90:91]
	v_lshlrev_b64 v[100:101], 1, v[98:99]
	v_lshl_add_u64 v[102:103], v[64:65], 0, v[100:101]
	s_mov_b64 s[2:3], 0x16f00600
	v_lshl_add_u64 v[94:95], v[102:103], 0, s[2:3]
	s_movk_i32 s2, 0x90
	v_mad_u32_u24 v89, v114, s2, v92
	v_lshl_add_u32 v93, v115, 4, v89
	ds_read_b128 v[64:67], v93 offset:4608
	ds_read_b128 v[68:71], v93
	ds_read_b128 v[80:83], v93 offset:32
	ds_read_b128 v[84:87], v93 offset:4640
	s_waitcnt lgkmcnt(2)
	v_mfma_f32_32x32x16_bf16 v[64:79], v[64:67], v[68:71], 0
	v_cmp_ge_i32_e32 vcc, v98, v114
	v_cvt_pk_bf16_f32 v32, v32, v33
	v_cvt_pk_bf16_f32 v33, v34, v35
	v_cvt_pk_bf16_f32 v34, v36, v37
	v_cvt_pk_bf16_f32 v35, v38, v39
	v_cvt_pk_bf16_f32 v36, v48, v49
	v_cvt_pk_bf16_f32 v37, v50, v51
	s_waitcnt lgkmcnt(0)
	v_mfma_f32_32x32x16_bf16 v[64:79], v[84:87], v[80:83], v[64:79]
	ds_read_b128 v[80:83], v93 offset:4672
	ds_read_b128 v[84:87], v93 offset:64
	v_cvt_pk_bf16_f32 v38, v52, v53
	v_cvt_pk_bf16_f32 v39, v54, v55
	s_mov_b32 s2, 0x16f00000
	s_waitcnt lgkmcnt(0)
	v_mfma_f32_32x32x16_bf16 v[64:79], v[80:83], v[84:87], v[64:79]
	ds_read_b128 v[80:83], v93 offset:4704
	ds_read_b128 v[84:87], v93 offset:96
	s_waitcnt lgkmcnt(0)
	v_mfma_f32_32x32x16_bf16 v[64:79], v[80:83], v[84:87], v[64:79]
	v_or_b32_e32 v80, 1, v98
	s_nop 10
	v_cndmask_b32_e32 v64, 0, v64, vcc
	v_cmp_ge_i32_e32 vcc, v80, v114
	v_or_b32_e32 v80, 2, v98
	s_nop 0
	v_cndmask_b32_e32 v65, 0, v65, vcc
	v_cmp_ge_i32_e32 vcc, v80, v114
	v_or_b32_e32 v80, 3, v98
	s_nop 0
	v_cndmask_b32_e32 v66, 0, v66, vcc
	v_cmp_ge_i32_e32 vcc, v80, v114
	v_add_u32_e32 v80, 8, v98
	s_nop 0
	v_cndmask_b32_e32 v67, 0, v67, vcc
	v_cmp_ge_i32_e32 vcc, v80, v114
	v_add_u32_e32 v80, 9, v98
	v_cvt_pk_bf16_f32 v81, v66, v67
	v_cndmask_b32_e32 v68, 0, v68, vcc
	v_cmp_ge_i32_e32 vcc, v80, v114
	v_add_u32_e32 v80, 10, v98
	s_nop 0
	v_cndmask_b32_e32 v69, 0, v69, vcc
	v_cmp_ge_i32_e32 vcc, v80, v114
	v_add_u32_e32 v80, 11, v98
	v_cvt_pk_bf16_f32 v82, v68, v69
	v_cndmask_b32_e32 v70, 0, v70, vcc
	v_cmp_ge_i32_e32 vcc, v80, v114
	v_add_u32_e32 v80, 16, v98
	s_nop 0
	v_cndmask_b32_e32 v71, 0, v71, vcc
	v_cmp_ge_i32_e32 vcc, v80, v114
	v_add_u32_e32 v80, 17, v98
	v_cvt_pk_bf16_f32 v83, v70, v71
	v_cndmask_b32_e32 v72, 0, v72, vcc
	v_cmp_ge_i32_e32 vcc, v80, v114
	v_add_u32_e32 v80, 18, v98
	s_nop 0
	v_cndmask_b32_e32 v73, 0, v73, vcc
	v_cmp_ge_i32_e32 vcc, v80, v114
	v_add_u32_e32 v80, 19, v98
	v_cvt_pk_bf16_f32 v84, v72, v73
	v_cndmask_b32_e32 v74, 0, v74, vcc
	v_cmp_ge_i32_e32 vcc, v80, v114
	v_add_u32_e32 v80, 24, v98
	s_nop 0
	v_cndmask_b32_e32 v75, 0, v75, vcc
	v_cmp_ge_i32_e32 vcc, v80, v114
	v_add_u32_e32 v80, 25, v98
	v_cvt_pk_bf16_f32 v85, v74, v75
	v_cndmask_b32_e32 v76, 0, v76, vcc
	v_cmp_ge_i32_e32 vcc, v80, v114
	v_add_u32_e32 v80, 26, v98
	s_nop 0
	v_cndmask_b32_e32 v77, 0, v77, vcc
	v_cmp_ge_i32_e32 vcc, v80, v114
	v_add_u32_e32 v80, 27, v98
	v_cvt_pk_bf16_f32 v86, v76, v77
	v_cndmask_b32_e32 v78, 0, v78, vcc
	v_cmp_ge_i32_e32 vcc, v80, v114
	v_cvt_pk_bf16_f32 v80, v64, v65
	v_lshlrev_b32_e32 v64, 3, v115
	v_mul_u32_u24_e32 v65, 0x50, v114
	v_add3_u32 v92, v92, v64, v65
	v_add_u32_e32 v68, 0x3800, v92
	v_add_u32_e32 v89, v89, v64
	ds_read2_b64 v[64:67], v68 offset1:2
	ds_read2_b64 v[104:107], v68 offset0:4 offset1:6
	v_cndmask_b32_e32 v79, 0, v79, vcc
	v_cvt_pk_bf16_f32 v87, v78, v79
	s_waitcnt lgkmcnt(1)
	v_mfma_f32_32x32x16_bf16 v[64:79], v[64:67], v[80:83], 0
	v_add_co_u32_e32 v48, vcc, s2, v102
	s_nop 1
	v_addc_co_u32_e32 v49, vcc, 0, v103, vcc
	s_waitcnt lgkmcnt(0)
	v_mfma_f32_32x32x16_bf16 v[64:79], v[104:107], v[84:87], v[64:79]
	ds_read2_b64 v[104:107], v89 offset1:2
	ds_read2_b64 v[108:111], v89 offset0:4 offset1:6
	s_waitcnt lgkmcnt(1)
	v_mfma_f32_32x32x16_bf16 v[64:79], v[32:35], v[104:107], v[64:79]
	v_cvt_pk_bf16_f32 v32, v40, v41
	v_cvt_pk_bf16_f32 v33, v42, v43
	v_cvt_pk_bf16_f32 v34, v44, v45
	v_cvt_pk_bf16_f32 v35, v46, v47
	s_waitcnt lgkmcnt(0)
	s_nop 0
	v_mfma_f32_32x32x16_bf16 v[64:79], v[32:35], v[108:111], v[64:79]
	ds_read2_b64 v[32:35], v89 offset0:8 offset1:10
	s_waitcnt lgkmcnt(0)
	v_mfma_f32_32x32x16_bf16 v[64:79], v[36:39], v[32:35], v[64:79]
	ds_read2_b64 v[32:35], v89 offset0:12 offset1:14
	v_cvt_pk_bf16_f32 v36, v56, v57
	v_cvt_pk_bf16_f32 v37, v58, v59
	v_cvt_pk_bf16_f32 v38, v60, v61
	v_cvt_pk_bf16_f32 v39, v62, v63
	s_waitcnt lgkmcnt(0)
	s_nop 0
	v_mfma_f32_32x32x16_bf16 v[64:79], v[36:39], v[32:35], v[64:79]
	global_load_dwordx2 v[32:33], v[48:49], off offset:1536
	s_waitcnt vmcnt(0)
	v_lshlrev_b32_e32 v34, 16, v32
	v_and_b32_e32 v35, 0xffff0000, v32
	v_lshlrev_b32_e32 v32, 16, v33
	v_and_b32_e32 v33, 0xffff0000, v33
	s_nop 5
	v_pk_add_f32 v[34:35], v[64:65], v[34:35]
	v_pk_add_f32 v[32:33], v[66:67], v[32:33]
	v_mul_f32_e32 v36, v35, v35
	v_mul_f32_e32 v38, v33, v33
	v_pk_fma_f32 v[36:37], v[34:35], v[34:35], v[36:37] op_sel_hi:[1,1,0]
	v_pk_fma_f32 v[38:39], v[32:33], v[32:33], v[38:39] op_sel_hi:[1,1,0]
	v_cvt_pk_bf16_f32 v34, v34, v35
	v_cvt_pk_bf16_f32 v35, v32, v33
	global_load_dwordx2 v[32:33], v[94:95], off offset:16
	v_pk_add_f32 v[36:37], v[36:37], v[38:39]
	global_store_dwordx2 v[48:49], v[34:35], off offset:1536
	s_waitcnt vmcnt(1)
	v_lshlrev_b32_e32 v34, 16, v32
	v_and_b32_e32 v35, 0xffff0000, v32
	v_lshlrev_b32_e32 v32, 16, v33
	v_and_b32_e32 v33, 0xffff0000, v33
	v_pk_add_f32 v[34:35], v[68:69], v[34:35]
	v_pk_add_f32 v[32:33], v[70:71], v[32:33]
	v_mul_f32_e32 v38, v35, v35
	v_mul_f32_e32 v40, v33, v33
	v_pk_fma_f32 v[38:39], v[34:35], v[34:35], v[38:39] op_sel_hi:[1,1,0]
	v_pk_fma_f32 v[40:41], v[32:33], v[32:33], v[40:41] op_sel_hi:[1,1,0]
	v_cvt_pk_bf16_f32 v34, v34, v35
	v_cvt_pk_bf16_f32 v35, v32, v33
	global_load_dwordx2 v[32:33], v[94:95], off offset:32
	v_pk_add_f32 v[38:39], v[38:39], v[40:41]
	global_store_dwordx2 v[94:95], v[34:35], off offset:16
	v_pk_add_f32 v[36:37], v[36:37], v[38:39]
	s_waitcnt vmcnt(1)
	v_lshlrev_b32_e32 v34, 16, v32
	v_and_b32_e32 v35, 0xffff0000, v32
	v_pk_add_f32 v[34:35], v[72:73], v[34:35]
	v_lshlrev_b32_e32 v32, 16, v33
	v_and_b32_e32 v33, 0xffff0000, v33
	v_pk_add_f32 v[38:39], v[74:75], v[32:33]
	v_mul_f32_e32 v32, v35, v35
	v_pk_fma_f32 v[32:33], v[34:35], v[34:35], v[32:33] op_sel_hi:[1,1,0]
	v_cvt_pk_bf16_f32 v34, v34, v35
	v_cvt_pk_bf16_f32 v35, v38, v39
	global_store_dwordx2 v[94:95], v[34:35], off offset:32
	global_load_dwordx2 v[34:35], v[94:95], off offset:48
	v_mul_f32_e32 v40, v39, v39
	v_pk_fma_f32 v[40:41], v[38:39], v[38:39], v[40:41] op_sel_hi:[1,1,0]
	s_nop 0
	v_pk_add_f32 v[32:33], v[32:33], v[40:41]
	s_nop 0
	v_pk_add_f32 v[32:33], v[36:37], v[32:33]
	s_waitcnt vmcnt(0)
	v_lshlrev_b32_e32 v36, 16, v34
	v_and_b32_e32 v37, 0xffff0000, v34
	v_lshlrev_b32_e32 v34, 16, v35
	v_and_b32_e32 v35, 0xffff0000, v35
	v_pk_add_f32 v[36:37], v[76:77], v[36:37]
	v_pk_add_f32 v[34:35], v[78:79], v[34:35]
	v_mul_f32_e32 v38, v37, v37
	v_mul_f32_e32 v40, v35, v35
	v_pk_fma_f32 v[38:39], v[36:37], v[36:37], v[38:39] op_sel_hi:[1,1,0]
	v_pk_fma_f32 v[40:41], v[34:35], v[34:35], v[40:41] op_sel_hi:[1,1,0]
	s_nop 0
	v_pk_add_f32 v[38:39], v[38:39], v[40:41]
	s_nop 0
	v_pk_add_f32 v[58:59], v[32:33], v[38:39]
	v_cvt_pk_bf16_f32 v32, v36, v37
	v_cvt_pk_bf16_f32 v33, v34, v35
	global_store_dwordx2 v[94:95], v[32:33], off offset:48
	v_add_u32_e32 v36, 0x4000, v92
	ds_read2_b64 v[32:35], v36 offset0:64 offset1:66
	ds_read2_b64 v[50:53], v36 offset0:68 offset1:70
	v_cvt_pk_bf16_f32 v0, v0, v1
	v_cvt_pk_bf16_f32 v1, v2, v3
	v_cvt_pk_bf16_f32 v2, v4, v5
	s_waitcnt lgkmcnt(1)
	v_mfma_f32_32x32x16_bf16 v[32:47], v[32:35], v[80:83], 0
	v_cvt_pk_bf16_f32 v3, v6, v7
	v_cvt_pk_bf16_f32 v4, v16, v17
	v_cvt_pk_bf16_f32 v5, v18, v19
	v_cvt_pk_bf16_f32 v6, v20, v21
	v_cvt_pk_bf16_f32 v7, v22, v23
	s_waitcnt lgkmcnt(0)
	v_mfma_f32_32x32x16_bf16 v[32:47], v[50:53], v[84:87], v[32:47]
	ds_read2_b64 v[50:53], v89 offset1:2
	ds_read2_b64 v[54:57], v89 offset0:4 offset1:6
	s_waitcnt lgkmcnt(1)
	v_mfma_f32_32x32x16_bf16 v[32:47], v[0:3], v[50:53], v[32:47]
	v_cvt_pk_bf16_f32 v0, v8, v9
	v_cvt_pk_bf16_f32 v1, v10, v11
	v_cvt_pk_bf16_f32 v2, v12, v13
	v_cvt_pk_bf16_f32 v3, v14, v15
	s_waitcnt lgkmcnt(0)
	s_nop 0
	v_mfma_f32_32x32x16_bf16 v[32:47], v[0:3], v[54:57], v[32:47]
	ds_read2_b64 v[0:3], v89 offset0:8 offset1:10
	s_waitcnt lgkmcnt(0)
	v_mfma_f32_32x32x16_bf16 v[32:47], v[4:7], v[0:3], v[32:47]
	ds_read2_b64 v[0:3], v89 offset0:12 offset1:14
	v_cvt_pk_bf16_f32 v4, v24, v25
	v_cvt_pk_bf16_f32 v5, v26, v27
	v_cvt_pk_bf16_f32 v6, v28, v29
	v_cvt_pk_bf16_f32 v7, v30, v31
	s_waitcnt lgkmcnt(0)
	s_nop 0
	v_mfma_f32_32x32x16_bf16 v[32:47], v[4:7], v[0:3], v[32:47]
	global_load_dwordx2 v[0:1], v[94:95], off offset:64
	s_waitcnt vmcnt(0)
	v_lshlrev_b32_e32 v2, 16, v0
	v_and_b32_e32 v3, 0xffff0000, v0
	v_lshlrev_b32_e32 v0, 16, v1
	v_and_b32_e32 v1, 0xffff0000, v1
	s_nop 5
	v_pk_add_f32 v[2:3], v[32:33], v[2:3]
	v_pk_add_f32 v[0:1], v[34:35], v[0:1]
	v_mul_f32_e32 v4, v3, v3
	v_mul_f32_e32 v6, v1, v1
	v_pk_fma_f32 v[4:5], v[2:3], v[2:3], v[4:5] op_sel_hi:[1,1,0]
	v_pk_fma_f32 v[6:7], v[0:1], v[0:1], v[6:7] op_sel_hi:[1,1,0]
	v_cvt_pk_bf16_f32 v2, v2, v3
	v_cvt_pk_bf16_f32 v3, v0, v1
	global_load_dwordx2 v[0:1], v[94:95], off offset:80
	v_pk_add_f32 v[4:5], v[4:5], v[6:7]
	global_store_dwordx2 v[94:95], v[2:3], off offset:64
	v_pk_add_f32 v[4:5], v[58:59], v[4:5]
	s_waitcnt vmcnt(1)
	v_lshlrev_b32_e32 v2, 16, v0
	v_and_b32_e32 v3, 0xffff0000, v0
	v_lshlrev_b32_e32 v0, 16, v1
	v_and_b32_e32 v1, 0xffff0000, v1
	v_pk_add_f32 v[2:3], v[36:37], v[2:3]
	v_pk_add_f32 v[0:1], v[38:39], v[0:1]
	v_mul_f32_e32 v6, v3, v3
	v_mul_f32_e32 v8, v1, v1
	v_pk_fma_f32 v[6:7], v[2:3], v[2:3], v[6:7] op_sel_hi:[1,1,0]
	v_pk_fma_f32 v[8:9], v[0:1], v[0:1], v[8:9] op_sel_hi:[1,1,0]
	v_cvt_pk_bf16_f32 v2, v2, v3
	v_cvt_pk_bf16_f32 v3, v0, v1
	global_load_dwordx2 v[0:1], v[94:95], off offset:96
	v_pk_add_f32 v[6:7], v[6:7], v[8:9]
	global_store_dwordx2 v[94:95], v[2:3], off offset:80
	v_pk_add_f32 v[4:5], v[4:5], v[6:7]
	s_waitcnt vmcnt(1)
	v_lshlrev_b32_e32 v2, 16, v0
	v_and_b32_e32 v3, 0xffff0000, v0
	v_lshlrev_b32_e32 v0, 16, v1
	v_and_b32_e32 v1, 0xffff0000, v1
	v_pk_add_f32 v[2:3], v[40:41], v[2:3]
	v_pk_add_f32 v[6:7], v[42:43], v[0:1]
	v_mov_b32_e32 v0, v2
	v_mov_b32_e32 v8, v3
	v_cvt_pk_bf16_f32 v2, v2, v3
	v_cvt_pk_bf16_f32 v3, v6, v7
	global_store_dwordx2 v[94:95], v[2:3], off offset:96
	global_load_dwordx2 v[2:3], v[94:95], off offset:112
	v_mov_b32_e32 v9, v7
	v_mov_b32_e32 v1, v6
	v_pk_mul_f32 v[8:9], v[8:9], v[8:9]
	s_nop 0
	v_pk_fma_f32 v[0:1], v[0:1], v[0:1], v[8:9]
	s_nop 0
	v_pk_add_f32 v[0:1], v[0:1], v[0:1] op_sel:[0,1] op_sel_hi:[1,0]
	s_nop 0
	v_pk_add_f32 v[0:1], v[4:5], v[0:1]
	s_waitcnt vmcnt(0)
	v_lshlrev_b32_e32 v4, 16, v2
	v_and_b32_e32 v5, 0xffff0000, v2
	v_lshlrev_b32_e32 v2, 16, v3
	v_and_b32_e32 v3, 0xffff0000, v3
	v_pk_add_f32 v[4:5], v[44:45], v[4:5]
	v_pk_add_f32 v[2:3], v[46:47], v[2:3]
	v_mov_b32_e32 v8, v5
	v_mov_b32_e32 v9, v3
	v_mov_b32_e32 v6, v4
	v_mov_b32_e32 v7, v2
	v_pk_mul_f32 v[8:9], v[8:9], v[8:9]
	v_cvt_pk_bf16_f32 v4, v4, v5
	v_pk_fma_f32 v[6:7], v[6:7], v[6:7], v[8:9]
	v_cvt_pk_bf16_f32 v5, v2, v3
	v_pk_add_f32 v[6:7], v[6:7], v[6:7] op_sel:[0,1] op_sel_hi:[1,0]
	global_store_dwordx2 v[94:95], v[4:5], off offset:112
	v_pk_add_f32 v[0:1], v[0:1], v[6:7]
	s_waitcnt lgkmcnt(0)
	s_nop 0
	v_mov_b32_e32 v1, v0
	s_nop 1
	v_permlane32_swap_b32_e32 v0, v1
	v_add_f32_e32 v0, v0, v1
	v_fmamk_f32 v0, v0, 0x3c800000, v237
	v_rsq_f32_e32 v4, v0
	v_mad_i64_i32 v[0:1], s[2:3], v88, s6, v[96:97]
	v_lshl_add_u64 v[0:1], v[0:1], 0, v[90:91]
	v_lshl_add_u64 v[0:1], v[0:1], 0, v[100:101]
	v_lshl_add_u64 v[8:9], v[0:1], 0, s[48:49]
	v_add_co_u32_e32 v0, vcc, s5, v0
	global_load_dwordx2 v[10:11], v[48:49], off offset:1536
	s_nop 0
	v_addc_co_u32_e32 v1, vcc, 0, v1, vcc
	global_load_dwordx2 v[12:13], v[0:1], off
	s_add_u32 s2, s12, s0
	s_addc_u32 s3, s13, s1
	v_lshl_add_u64 v[0:1], v[98:99], 2, s[2:3]
	v_lshl_add_u64 v[6:7], v[0:1], 0, s[30:31]
	v_add_co_u32_e32 v0, vcc, s7, v0
	v_readlane_b32 s48, v254, 11
	s_nop 0
	v_addc_co_u32_e32 v1, vcc, 0, v1, vcc
	global_load_dwordx4 v[0:3], v[0:1], off offset:2048
	global_load_dwordx4 v[206:209], v[6:7], off offset:32
	global_load_dwordx2 v[210:211], v[8:9], off offset:16
	global_load_dwordx2 v[212:213], v[94:95], off offset:16
	global_load_dwordx4 v[214:217], v[6:7], off offset:64
	global_load_dwordx2 v[218:219], v[8:9], off offset:32
	global_load_dwordx2 v[220:221], v[94:95], off offset:32
	global_load_dwordx4 v[222:225], v[6:7], off offset:96
	global_load_dwordx2 v[226:227], v[8:9], off offset:48
	global_load_dwordx2 v[228:229], v[94:95], off offset:48
	v_readlane_b32 s49, v254, 12
	s_waitcnt vmcnt(11)
	v_lshlrev_b32_e32 v18, 16, v10
	v_and_b32_e32 v19, 0xffff0000, v10
	v_lshlrev_b32_e32 v10, 16, v11
	s_waitcnt vmcnt(10)
	v_lshlrev_b32_e32 v14, 16, v12
	v_mul_f32_e32 v5, 0xbfb8aa3b, v14
	v_exp_f32_e32 v5, v5
	v_and_b32_e32 v15, 0xffff0000, v12
	v_lshlrev_b32_e32 v12, 16, v13
	v_and_b32_e32 v13, 0xffff0000, v13
	v_add_f32_e32 v5, 1.0, v5
	v_rcp_f32_e32 v16, v5
	v_mul_f32_e32 v5, 0xbfb8aa3b, v15
	v_exp_f32_e32 v5, v5
	v_and_b32_e32 v11, 0xffff0000, v11
	v_add_f32_e32 v5, 1.0, v5
	v_rcp_f32_e32 v17, v5
	v_pk_mul_f32 v[18:19], v[4:5], v[18:19] op_sel_hi:[0,1]
	s_waitcnt vmcnt(9)
	v_pk_mul_f32 v[0:1], v[0:1], v[18:19]
	v_pk_mul_f32 v[10:11], v[4:5], v[10:11] op_sel_hi:[0,1]
	v_pk_mul_f32 v[14:15], v[16:17], v[14:15]
	v_pk_mul_f32 v[2:3], v[2:3], v[10:11]
	v_pk_mul_f32 v[0:1], v[0:1], v[14:15]
	s_nop 0
	v_cvt_pk_bf16_f32 v0, v0, v1
	v_mul_f32_e32 v1, 0xbfb8aa3b, v12
	v_exp_f32_e32 v1, v1
	s_nop 0
	v_add_f32_e32 v1, 1.0, v1
	v_rcp_f32_e32 v14, v1
	v_mul_f32_e32 v1, 0xbfb8aa3b, v13
	v_exp_f32_e32 v1, v1
	s_nop 0
	v_add_f32_e32 v1, 1.0, v1
	v_rcp_f32_e32 v15, v1
	s_nop 0
	v_pk_mul_f32 v[10:11], v[14:15], v[12:13]
	s_nop 0
	v_pk_mul_f32 v[2:3], v[2:3], v[10:11]
	s_nop 0
	v_cvt_pk_bf16_f32 v1, v2, v3
	global_store_dwordx2 v[48:49], v[0:1], off offset:1536
	s_nop 0
	s_waitcnt vmcnt(8)
	v_lshlrev_b32_e32 v14, 16, v210
	v_mul_f32_e32 v5, 0xbfb8aa3b, v14
	v_exp_f32_e32 v5, v5
	v_and_b32_e32 v15, 0xffff0000, v210
	s_waitcnt vmcnt(7)
	v_lshlrev_b32_e32 v18, 16, v212
	v_and_b32_e32 v19, 0xffff0000, v212
	v_add_f32_e32 v5, 1.0, v5
	v_rcp_f32_e32 v16, v5
	v_mul_f32_e32 v5, 0xbfb8aa3b, v15
	v_exp_f32_e32 v5, v5
	v_lshlrev_b32_e32 v10, 16, v211
	v_and_b32_e32 v11, 0xffff0000, v211
	v_lshlrev_b32_e32 v12, 16, v213
	v_add_f32_e32 v5, 1.0, v5
	v_rcp_f32_e32 v17, v5
	v_pk_mul_f32 v[18:19], v[4:5], v[18:19] op_sel_hi:[0,1]
	v_pk_mul_f32 v[0:1], v[206:207], v[18:19]
	v_and_b32_e32 v13, 0xffff0000, v213
	v_pk_mul_f32 v[14:15], v[16:17], v[14:15]
	v_pk_mul_f32 v[12:13], v[4:5], v[12:13] op_sel_hi:[0,1]
	v_pk_mul_f32 v[0:1], v[0:1], v[14:15]
	v_pk_mul_f32 v[2:3], v[208:209], v[12:13]
	v_cvt_pk_bf16_f32 v0, v0, v1
	v_mul_f32_e32 v1, 0xbfb8aa3b, v10
	v_exp_f32_e32 v1, v1
	s_nop 0
	v_add_f32_e32 v1, 1.0, v1
	v_rcp_f32_e32 v14, v1
	v_mul_f32_e32 v1, 0xbfb8aa3b, v11
	v_exp_f32_e32 v1, v1
	s_nop 0
	v_add_f32_e32 v1, 1.0, v1
	v_rcp_f32_e32 v15, v1
	s_nop 0
	v_pk_mul_f32 v[10:11], v[14:15], v[10:11]
	s_nop 0
	v_pk_mul_f32 v[2:3], v[2:3], v[10:11]
	s_nop 0
	v_cvt_pk_bf16_f32 v1, v2, v3
	global_store_dwordx2 v[94:95], v[0:1], off offset:16
	s_nop 0
	s_waitcnt vmcnt(6)
	v_lshlrev_b32_e32 v14, 16, v218
	v_mul_f32_e32 v5, 0xbfb8aa3b, v14
	v_exp_f32_e32 v5, v5
	v_and_b32_e32 v15, 0xffff0000, v218
	s_waitcnt vmcnt(5)
	v_lshlrev_b32_e32 v18, 16, v220
	v_and_b32_e32 v19, 0xffff0000, v220
	v_add_f32_e32 v5, 1.0, v5
	v_rcp_f32_e32 v16, v5
	v_mul_f32_e32 v5, 0xbfb8aa3b, v15
	v_exp_f32_e32 v5, v5
	v_lshlrev_b32_e32 v10, 16, v219
	v_and_b32_e32 v11, 0xffff0000, v219
	v_lshlrev_b32_e32 v12, 16, v221
	v_add_f32_e32 v5, 1.0, v5
	v_rcp_f32_e32 v17, v5
	v_pk_mul_f32 v[18:19], v[4:5], v[18:19] op_sel_hi:[0,1]
	v_pk_mul_f32 v[0:1], v[214:215], v[18:19]
	v_and_b32_e32 v13, 0xffff0000, v221
	v_pk_mul_f32 v[14:15], v[16:17], v[14:15]
	v_pk_mul_f32 v[12:13], v[4:5], v[12:13] op_sel_hi:[0,1]
	v_pk_mul_f32 v[0:1], v[0:1], v[14:15]
	v_pk_mul_f32 v[2:3], v[216:217], v[12:13]
	v_cvt_pk_bf16_f32 v0, v0, v1
	v_mul_f32_e32 v1, 0xbfb8aa3b, v10
	v_exp_f32_e32 v1, v1
	s_nop 0
	v_add_f32_e32 v1, 1.0, v1
	v_rcp_f32_e32 v14, v1
	v_mul_f32_e32 v1, 0xbfb8aa3b, v11
	v_exp_f32_e32 v1, v1
	s_nop 0
	v_add_f32_e32 v1, 1.0, v1
	v_rcp_f32_e32 v15, v1
	s_nop 0
	v_pk_mul_f32 v[10:11], v[14:15], v[10:11]
	s_nop 0
	v_pk_mul_f32 v[2:3], v[2:3], v[10:11]
	s_nop 0
	v_cvt_pk_bf16_f32 v1, v2, v3
	global_store_dwordx2 v[94:95], v[0:1], off offset:32
	s_nop 0
	s_waitcnt vmcnt(4)
	v_lshlrev_b32_e32 v14, 16, v226
	v_mul_f32_e32 v5, 0xbfb8aa3b, v14
	v_exp_f32_e32 v5, v5
	v_and_b32_e32 v15, 0xffff0000, v226
	s_waitcnt vmcnt(3)
	v_lshlrev_b32_e32 v18, 16, v228
	v_and_b32_e32 v19, 0xffff0000, v228
	v_add_f32_e32 v5, 1.0, v5
	v_rcp_f32_e32 v16, v5
	v_mul_f32_e32 v5, 0xbfb8aa3b, v15
	v_exp_f32_e32 v5, v5
	v_lshlrev_b32_e32 v10, 16, v227
	v_and_b32_e32 v11, 0xffff0000, v227
	v_lshlrev_b32_e32 v12, 16, v229
	v_add_f32_e32 v5, 1.0, v5
	v_rcp_f32_e32 v17, v5
	v_pk_mul_f32 v[18:19], v[4:5], v[18:19] op_sel_hi:[0,1]
	v_pk_mul_f32 v[0:1], v[222:223], v[18:19]
	v_and_b32_e32 v13, 0xffff0000, v229
	v_pk_mul_f32 v[14:15], v[16:17], v[14:15]
	v_pk_mul_f32 v[12:13], v[4:5], v[12:13] op_sel_hi:[0,1]
	v_pk_mul_f32 v[0:1], v[0:1], v[14:15]
	v_pk_mul_f32 v[2:3], v[224:225], v[12:13]
	v_cvt_pk_bf16_f32 v0, v0, v1
	v_mul_f32_e32 v1, 0xbfb8aa3b, v10
	v_exp_f32_e32 v1, v1
	s_nop 0
	v_add_f32_e32 v1, 1.0, v1
	v_rcp_f32_e32 v14, v1
	v_mul_f32_e32 v1, 0xbfb8aa3b, v11
	v_exp_f32_e32 v1, v1
	s_nop 0
	v_add_f32_e32 v1, 1.0, v1
	v_rcp_f32_e32 v15, v1
	s_nop 0
	v_pk_mul_f32 v[10:11], v[14:15], v[10:11]
	s_nop 0
	v_pk_mul_f32 v[2:3], v[2:3], v[10:11]
	s_nop 0
	v_cvt_pk_bf16_f32 v1, v2, v3
	global_store_dwordx2 v[94:95], v[0:1], off offset:48
	global_load_dwordx2 v[10:11], v[94:95], off offset:64
	global_load_dwordx2 v[12:13], v[8:9], off offset:64
	global_load_dwordx4 v[0:3], v[6:7], off offset:128
	global_load_dwordx2 v[212:213], v[94:95], off offset:80
	global_load_dwordx2 v[210:211], v[8:9], off offset:80
	global_load_dwordx4 v[206:209], v[6:7], off offset:160
	global_load_dwordx2 v[220:221], v[94:95], off offset:96
	global_load_dwordx2 v[218:219], v[8:9], off offset:96
	global_load_dwordx4 v[214:217], v[6:7], off offset:192
	global_load_dwordx2 v[228:229], v[94:95], off offset:112
	global_load_dwordx2 v[226:227], v[8:9], off offset:112
	global_load_dwordx4 v[222:225], v[6:7], off offset:224
	s_waitcnt vmcnt(11)
	v_lshlrev_b32_e32 v18, 16, v10
	s_waitcnt vmcnt(10)
	v_lshlrev_b32_e32 v14, 16, v12
	v_mul_f32_e32 v5, 0xbfb8aa3b, v14
	v_exp_f32_e32 v5, v5
	v_and_b32_e32 v15, 0xffff0000, v12
	v_and_b32_e32 v19, 0xffff0000, v10
	v_lshlrev_b32_e32 v12, 16, v13
	v_add_f32_e32 v5, 1.0, v5
	v_rcp_f32_e32 v16, v5
	v_mul_f32_e32 v5, 0xbfb8aa3b, v15
	v_exp_f32_e32 v5, v5
	v_and_b32_e32 v13, 0xffff0000, v13
	v_lshlrev_b32_e32 v10, 16, v11
	v_and_b32_e32 v11, 0xffff0000, v11
	v_add_f32_e32 v5, 1.0, v5
	v_rcp_f32_e32 v17, v5
	v_pk_mul_f32 v[18:19], v[4:5], v[18:19] op_sel_hi:[0,1]
	s_waitcnt vmcnt(9)
	v_pk_mul_f32 v[0:1], v[0:1], v[18:19]
	v_pk_mul_f32 v[10:11], v[4:5], v[10:11] op_sel_hi:[0,1]
	v_pk_mul_f32 v[14:15], v[16:17], v[14:15]
	v_pk_mul_f32 v[2:3], v[2:3], v[10:11]
	v_pk_mul_f32 v[0:1], v[0:1], v[14:15]
	s_nop 0
	v_cvt_pk_bf16_f32 v0, v0, v1
	v_mul_f32_e32 v1, 0xbfb8aa3b, v12
	v_exp_f32_e32 v1, v1
	s_nop 0
	v_add_f32_e32 v1, 1.0, v1
	v_rcp_f32_e32 v14, v1
	v_mul_f32_e32 v1, 0xbfb8aa3b, v13
	v_exp_f32_e32 v1, v1
	s_nop 0
	v_add_f32_e32 v1, 1.0, v1
	v_rcp_f32_e32 v15, v1
	s_nop 0
	v_pk_mul_f32 v[10:11], v[14:15], v[12:13]
	s_nop 0
	v_pk_mul_f32 v[2:3], v[2:3], v[10:11]
	s_nop 0
	v_cvt_pk_bf16_f32 v1, v2, v3
	global_store_dwordx2 v[94:95], v[0:1], off offset:64
	s_nop 0
	s_waitcnt vmcnt(9)
	v_lshlrev_b32_e32 v18, 16, v212
	s_waitcnt vmcnt(8)
	v_lshlrev_b32_e32 v14, 16, v210
	v_mul_f32_e32 v5, 0xbfb8aa3b, v14
	v_exp_f32_e32 v5, v5
	v_and_b32_e32 v15, 0xffff0000, v210
	v_and_b32_e32 v19, 0xffff0000, v212
	v_lshlrev_b32_e32 v12, 16, v211
	v_add_f32_e32 v5, 1.0, v5
	v_rcp_f32_e32 v16, v5
	v_mul_f32_e32 v5, 0xbfb8aa3b, v15
	v_exp_f32_e32 v5, v5
	v_and_b32_e32 v13, 0xffff0000, v211
	v_lshlrev_b32_e32 v10, 16, v213
	v_and_b32_e32 v11, 0xffff0000, v213
	v_add_f32_e32 v5, 1.0, v5
	v_rcp_f32_e32 v17, v5
	v_pk_mul_f32 v[18:19], v[4:5], v[18:19] op_sel_hi:[0,1]
	s_waitcnt vmcnt(7)
	v_pk_mul_f32 v[0:1], v[206:207], v[18:19]
	v_pk_mul_f32 v[10:11], v[4:5], v[10:11] op_sel_hi:[0,1]
	v_pk_mul_f32 v[14:15], v[16:17], v[14:15]
	v_pk_mul_f32 v[2:3], v[208:209], v[10:11]
	v_pk_mul_f32 v[0:1], v[0:1], v[14:15]
	s_nop 0
	v_cvt_pk_bf16_f32 v0, v0, v1
	v_mul_f32_e32 v1, 0xbfb8aa3b, v12
	v_exp_f32_e32 v1, v1
	s_nop 0
	v_add_f32_e32 v1, 1.0, v1
	v_rcp_f32_e32 v14, v1
	v_mul_f32_e32 v1, 0xbfb8aa3b, v13
	v_exp_f32_e32 v1, v1
	s_nop 0
	v_add_f32_e32 v1, 1.0, v1
	v_rcp_f32_e32 v15, v1
	s_nop 0
	v_pk_mul_f32 v[10:11], v[14:15], v[12:13]
	s_nop 0
	v_pk_mul_f32 v[2:3], v[2:3], v[10:11]
	s_nop 0
	v_cvt_pk_bf16_f32 v1, v2, v3
	global_store_dwordx2 v[94:95], v[0:1], off offset:80
	s_nop 0
	s_waitcnt vmcnt(7)
	v_lshlrev_b32_e32 v18, 16, v220
	s_waitcnt vmcnt(6)
	v_lshlrev_b32_e32 v14, 16, v218
	v_mul_f32_e32 v5, 0xbfb8aa3b, v14
	v_exp_f32_e32 v5, v5
	v_and_b32_e32 v15, 0xffff0000, v218
	v_and_b32_e32 v19, 0xffff0000, v220
	v_lshlrev_b32_e32 v12, 16, v219
	v_add_f32_e32 v5, 1.0, v5
	v_rcp_f32_e32 v16, v5
	v_mul_f32_e32 v5, 0xbfb8aa3b, v15
	v_exp_f32_e32 v5, v5
	v_and_b32_e32 v13, 0xffff0000, v219
	v_lshlrev_b32_e32 v10, 16, v221
	v_and_b32_e32 v11, 0xffff0000, v221
	v_add_f32_e32 v5, 1.0, v5
	v_rcp_f32_e32 v17, v5
	v_pk_mul_f32 v[18:19], v[4:5], v[18:19] op_sel_hi:[0,1]
	s_waitcnt vmcnt(5)
	v_pk_mul_f32 v[0:1], v[214:215], v[18:19]
	v_pk_mul_f32 v[10:11], v[4:5], v[10:11] op_sel_hi:[0,1]
	v_pk_mul_f32 v[14:15], v[16:17], v[14:15]
	v_pk_mul_f32 v[2:3], v[216:217], v[10:11]
	v_pk_mul_f32 v[0:1], v[0:1], v[14:15]
	s_nop 0
	v_cvt_pk_bf16_f32 v0, v0, v1
	v_mul_f32_e32 v1, 0xbfb8aa3b, v12
	v_exp_f32_e32 v1, v1
	s_nop 0
	v_add_f32_e32 v1, 1.0, v1
	v_rcp_f32_e32 v14, v1
	v_mul_f32_e32 v1, 0xbfb8aa3b, v13
	v_exp_f32_e32 v1, v1
	s_nop 0
	v_add_f32_e32 v1, 1.0, v1
	v_rcp_f32_e32 v15, v1
	s_nop 0
	v_pk_mul_f32 v[10:11], v[14:15], v[12:13]
	s_nop 0
	v_pk_mul_f32 v[2:3], v[2:3], v[10:11]
	s_nop 0
	v_cvt_pk_bf16_f32 v1, v2, v3
	global_store_dwordx2 v[94:95], v[0:1], off offset:96
	s_nop 0
	s_nop 0
	s_waitcnt vmcnt(5)
	v_lshlrev_b32_e32 v14, 16, v228
	s_waitcnt vmcnt(4)
	v_lshlrev_b32_e32 v10, 16, v226
	v_mul_f32_e32 v5, 0xbfb8aa3b, v10
	v_exp_f32_e32 v5, v5
	v_and_b32_e32 v11, 0xffff0000, v226
	v_lshlrev_b32_e32 v2, 16, v227
	v_and_b32_e32 v15, 0xffff0000, v228
	v_add_f32_e32 v5, 1.0, v5
	v_rcp_f32_e32 v12, v5
	v_mul_f32_e32 v5, 0xbfb8aa3b, v11
	v_exp_f32_e32 v5, v5
	v_and_b32_e32 v3, 0xffff0000, v227
	v_add_f32_e32 v5, 1.0, v5
	v_rcp_f32_e32 v13, v5
	v_pk_mul_f32 v[14:15], v[4:5], v[14:15] op_sel_hi:[0,1]
	v_mul_f32_e32 v5, 0xbfb8aa3b, v2
	v_exp_f32_e32 v5, v5
	s_waitcnt vmcnt(3)
	v_pk_mul_f32 v[6:7], v[222:223], v[14:15]
	v_pk_mul_f32 v[10:11], v[12:13], v[10:11]
	v_add_f32_e32 v5, 1.0, v5
	v_pk_mul_f32 v[6:7], v[6:7], v[10:11]
	v_lshlrev_b32_e32 v10, 16, v229
	v_cvt_pk_bf16_f32 v0, v6, v7
	v_rcp_f32_e32 v6, v5
	v_mul_f32_e32 v5, 0xbfb8aa3b, v3
	v_exp_f32_e32 v5, v5
	v_and_b32_e32 v11, 0xffff0000, v229
	v_add_f32_e32 v5, 1.0, v5
	v_rcp_f32_e32 v7, v5
	v_pk_mul_f32 v[4:5], v[4:5], v[10:11] op_sel_hi:[0,1]
	v_pk_mul_f32 v[4:5], v[224:225], v[4:5]
	v_pk_mul_f32 v[2:3], v[6:7], v[2:3]
	s_nop 0
	v_pk_mul_f32 v[2:3], v[4:5], v[2:3]
	s_nop 0
	v_cvt_pk_bf16_f32 v1, v2, v3
	global_store_dwordx2 v[94:95], v[0:1], off offset:112
	s_branch .LBB0_338
